# sc1 (write-through) output stores in all GEMM epilogues except PP
# speedup vs baseline: 1.0192x; 1.0192x over previous
; __device__ __forceinline__ u32x4 pack8(const f32x4 v0, const f32x4 v1) { u32x4 w; w.x = cvt_pk_bf16(v0[0], v0[1]); w.y = cvt_pk_bf16(v0[2], v0[3]); w.z = cvt_pk_bf16(v1[0], v1[1]); w.w = cvt_pk_bf16(v1[2], v1[3]); return w; }
;     __device__ __forceinline__ bf16_t* dst(const Unit& u, int row, int bj, int wc, int fq, int col0) const {
;         if (u.pn < 2 || u.pn >= 6) return O + (size_t)row * ldc + col0 + bj * HALF;
;         const int b = row >> 11, t = row & 2047;
;         if (u.pn < 4) { const int hc = (u.pn - 2) * 4 + bj * 2 + (wc >> 1), chunk = (wc & 1) * 4 + fq;
;             return KC + (size_t)((b * 8 + hc) * 32 + (t >> 6)) * 4096 + chunk * 512 + (t & 63) * 8; }
;         const int h = (u.pn - 4) * 2 + bj, piece = wc * 4 + ((t & 63) >> 4);
;         return VC + (size_t)((b * 4 + h) * 32 + (t >> 6)) * 8192 + piece * 512 + (t & 15) * 32 + fq * 8;
;     __device__ __forceinline__ void operator()(const f32x4 (&acc)[2][2][4][2], const Unit& u, int wr, int wc, int fr, int fq) const {
;     ...
;                 for (int m = 0; m < 4; ++m) { const int row = row0 + ai * HALF + m * 16; const float r = rs[ai * 4 + m] * sc;
; #pragma unroll
;                     for (int bj = 0; bj < 2; ++bj) *(u32x4*)dst(u, row, bj, wc, fq, col0) = pack8(acc[ai][bj][m][0] * r, acc[ai][bj][m][1] * r); }
.LBB0_160:
	v_mov_b32_e32 v165, v164
	v_lshl_add_u64 v[168:169], v[194:195], 1, v[168:169]
	global_store_dwordx4 v[168:169], v[128:131], off sc1
	v_pk_mul_f32 v[168:169], v[116:117], v[164:165]
	v_pk_mul_f32 v[178:179], v[112:113], v[164:165]
	v_mov_b32_e32 v128, v164
	v_mov_b32_e32 v129, v164
	v_cndmask_b32_e64 v165, 0, 1, s[28:29]
	v_pk_mul_f32 v[130:131], v[118:119], v[128:129]
	v_cmp_ne_u32_e64 s[0:1], 1, v165
	s_andn2_b64 vcc, exec, s[28:29]
	s_mov_b64 s[28:29], -1
	v_pk_mul_f32 v[170:171], v[114:115], v[128:129]
	v_cvt_pk_bf16_f32 v128, v168, v169
	v_cvt_pk_bf16_f32 v129, v130, v131
	v_cvt_pk_bf16_f32 v130, v178, v179
	s_nop 0
	v_cvt_pk_bf16_f32 v131, v170, v171
	s_cbranch_vccnz .LBB0_166
	s_cmp_lt_u32 s8, 4
	s_cbranch_scc1 .LBB0_163
	s_lshl_b32 s28, s8, 6
	s_add_i32 s28, s28, s40
	s_addk_i32 s28, 0xff20
	s_ashr_i32 s29, s28, 31
	s_lshl_b64 s[28:29], s[28:29], 14
	s_add_u32 s28, s16, s28
	s_addc_u32 s29, s17, s29
	s_lshl_b32 s41, s31, 1
	s_add_u32 s28, s28, s41
	s_addc_u32 s29, s29, 0
	v_lshlrev_b32_e32 v194, 1, v176
	v_lshl_add_u64 v[168:169], s[28:29], 0, v[194:195]
	s_mov_b64 s[28:29], 0

; __device__ __forceinline__ u32x4 pack8(const f32x4 v0, const f32x4 v1) { u32x4 w; w.x = cvt_pk_bf16(v0[0], v0[1]); w.y = cvt_pk_bf16(v0[2], v0[3]); w.z = cvt_pk_bf16(v1[0], v1[1]); w.w = cvt_pk_bf16(v1[2], v1[3]); return w; }
;     __device__ __forceinline__ bf16_t* dst(const Unit& u, int row, int bj, int wc, int fq, int col0) const {
;         if (u.pn < 2 || u.pn >= 6) return O + (size_t)row * ldc + col0 + bj * HALF;
;         const int b = row >> 11, t = row & 2047;
;         if (u.pn < 4) { const int hc = (u.pn - 2) * 4 + bj * 2 + (wc >> 1), chunk = (wc & 1) * 4 + fq;
;             return KC + (size_t)((b * 8 + hc) * 32 + (t >> 6)) * 4096 + chunk * 512 + (t & 63) * 8; }
;         const int h = (u.pn - 4) * 2 + bj, piece = wc * 4 + ((t & 63) >> 4);
;         return VC + (size_t)((b * 4 + h) * 32 + (t >> 6)) * 8192 + piece * 512 + (t & 15) * 32 + fq * 8;
;     __device__ __forceinline__ void operator()(const f32x4 (&acc)[2][2][4][2], const Unit& u, int wr, int wc, int fr, int fq) const {
;     ...
;                 for (int m = 0; m < 4; ++m) { const int row = row0 + ai * HALF + m * 16; const float r = rs[ai * 4 + m] * sc;
; #pragma unroll
;                     for (int bj = 0; bj < 2; ++bj) *(u32x4*)dst(u, row, bj, wc, fq, col0) = pack8(acc[ai][bj][m][0] * r, acc[ai][bj][m][1] * r); }
.LBB0_168:
	v_lshl_add_u64 v[168:169], v[194:195], 1, v[168:169]
	global_store_dwordx4 v[168:169], v[128:131], off sc1
	v_mul_f32_e32 v168, v149, v174
	v_pk_mul_f32 v[170:171], v[106:107], v[168:169] op_sel_hi:[1,0]
	v_lshlrev_b32_e32 v128, 3, v160
	v_and_b32_e32 v165, 0xf8, v128
	v_pk_mul_f32 v[130:131], v[110:111], v[168:169] op_sel_hi:[1,0]
	v_pk_mul_f32 v[128:129], v[108:109], v[168:169] op_sel_hi:[1,0]
	s_and_b64 vcc, exec, s[0:1]
	s_mov_b64 s[28:29], -1
	v_pk_mul_f32 v[178:179], v[104:105], v[168:169] op_sel_hi:[1,0]
	v_cvt_pk_bf16_f32 v128, v128, v129
	v_cvt_pk_bf16_f32 v129, v130, v131
	s_nop 0
	v_cvt_pk_bf16_f32 v130, v178, v179
	v_cvt_pk_bf16_f32 v131, v170, v171
	s_cbranch_vccnz .LBB0_174
	s_cmp_lt_u32 s8, 4
	s_cbranch_scc1 .LBB0_171
	s_lshl_b32 s28, s8, 6
	s_add_i32 s28, s28, s40
	s_addk_i32 s28, 0xff00
	s_ashr_i32 s29, s28, 31
	s_lshl_b64 s[28:29], s[28:29], 14
	s_add_u32 s28, s16, s28
	s_addc_u32 s29, s17, s29
	s_lshl_b32 s41, s31, 1
	s_add_u32 s28, s28, s41
	s_addc_u32 s29, s29, 0
	v_lshlrev_b32_e32 v194, 1, v176
	v_lshl_add_u64 v[170:171], s[28:29], 0, v[194:195]
	s_mov_b64 s[28:29], 0x400
	v_lshl_add_u64 v[170:171], v[170:171], 0, s[28:29]
	s_mov_b64 s[28:29], 0

; __device__ __forceinline__ u32x4 pack8(const f32x4 v0, const f32x4 v1) { u32x4 w; w.x = cvt_pk_bf16(v0[0], v0[1]); w.y = cvt_pk_bf16(v0[2], v0[3]); w.z = cvt_pk_bf16(v1[0], v1[1]); w.w = cvt_pk_bf16(v1[2], v1[3]); return w; }
;     __device__ __forceinline__ bf16_t* dst(const Unit& u, int row, int bj, int wc, int fq, int col0) const {
;         if (u.pn < 2 || u.pn >= 6) return O + (size_t)row * ldc + col0 + bj * HALF;
;         const int b = row >> 11, t = row & 2047;
;         if (u.pn < 4) { const int hc = (u.pn - 2) * 4 + bj * 2 + (wc >> 1), chunk = (wc & 1) * 4 + fq;
;             return KC + (size_t)((b * 8 + hc) * 32 + (t >> 6)) * 4096 + chunk * 512 + (t & 63) * 8; }
;         const int h = (u.pn - 4) * 2 + bj, piece = wc * 4 + ((t & 63) >> 4);
;         return VC + (size_t)((b * 4 + h) * 32 + (t >> 6)) * 8192 + piece * 512 + (t & 15) * 32 + fq * 8;
;     __device__ __forceinline__ void operator()(const f32x4 (&acc)[2][2][4][2], const Unit& u, int wr, int wc, int fr, int fq) const {
;     ...
;                 for (int m = 0; m < 4; ++m) { const int row = row0 + ai * HALF + m * 16; const float r = rs[ai * 4 + m] * sc;
; #pragma unroll
;                     for (int bj = 0; bj < 2; ++bj) *(u32x4*)dst(u, row, bj, wc, fq, col0) = pack8(acc[ai][bj][m][0] * r, acc[ai][bj][m][1] * r); }
.LBB0_176:
	v_lshl_add_u64 v[170:171], v[194:195], 1, v[170:171]
	v_mov_b32_e32 v169, v168
	global_store_dwordx4 v[170:171], v[128:131], off sc1
	v_pk_mul_f32 v[170:171], v[100:101], v[168:169]
	s_and_b64 vcc, exec, s[0:1]
	v_mov_b32_e32 v128, v168
	v_mov_b32_e32 v129, v168
	v_pk_mul_f32 v[130:131], v[102:103], v[128:129]
	v_pk_mul_f32 v[168:169], v[96:97], v[168:169]
	s_mov_b64 s[28:29], -1
	v_pk_mul_f32 v[178:179], v[98:99], v[128:129]
	v_cvt_pk_bf16_f32 v128, v170, v171
	v_cvt_pk_bf16_f32 v129, v130, v131
	v_cvt_pk_bf16_f32 v130, v168, v169
	s_nop 0
	v_cvt_pk_bf16_f32 v131, v178, v179
	s_cbranch_vccnz .LBB0_182
	s_cmp_lt_u32 s8, 4
	s_cbranch_scc1 .LBB0_179
	s_lshl_b32 s28, s8, 6
	s_add_i32 s28, s28, s40
	s_addk_i32 s28, 0xff20
	s_ashr_i32 s29, s28, 31
	s_lshl_b64 s[28:29], s[28:29], 14
	s_add_u32 s28, s16, s28
	s_addc_u32 s29, s17, s29
	s_lshl_b32 s41, s31, 1
	s_add_u32 s28, s28, s41
	s_addc_u32 s29, s29, 0
	v_lshlrev_b32_e32 v194, 1, v176
	v_lshl_add_u64 v[168:169], s[28:29], 0, v[194:195]
	s_mov_b64 s[28:29], 0x400
	v_lshl_add_u64 v[168:169], v[168:169], 0, s[28:29]
	s_mov_b64 s[28:29], 0

; __device__ __forceinline__ u32x4 pack8(const f32x4 v0, const f32x4 v1) { u32x4 w; w.x = cvt_pk_bf16(v0[0], v0[1]); w.y = cvt_pk_bf16(v0[2], v0[3]); w.z = cvt_pk_bf16(v1[0], v1[1]); w.w = cvt_pk_bf16(v1[2], v1[3]); return w; }
;     __device__ __forceinline__ bf16_t* dst(const Unit& u, int row, int bj, int wc, int fq, int col0) const {
;         if (u.pn < 2 || u.pn >= 6) return O + (size_t)row * ldc + col0 + bj * HALF;
;         const int b = row >> 11, t = row & 2047;
;         if (u.pn < 4) { const int hc = (u.pn - 2) * 4 + bj * 2 + (wc >> 1), chunk = (wc & 1) * 4 + fq;
;             return KC + (size_t)((b * 8 + hc) * 32 + (t >> 6)) * 4096 + chunk * 512 + (t & 63) * 8; }
;         const int h = (u.pn - 4) * 2 + bj, piece = wc * 4 + ((t & 63) >> 4);
;         return VC + (size_t)((b * 4 + h) * 32 + (t >> 6)) * 8192 + piece * 512 + (t & 15) * 32 + fq * 8;
;     __device__ __forceinline__ void operator()(const f32x4 (&acc)[2][2][4][2], const Unit& u, int wr, int wc, int fr, int fq) const {
;     ...
;                 for (int m = 0; m < 4; ++m) { const int row = row0 + ai * HALF + m * 16; const float r = rs[ai * 4 + m] * sc;
; #pragma unroll
;                     for (int bj = 0; bj < 2; ++bj) *(u32x4*)dst(u, row, bj, wc, fq, col0) = pack8(acc[ai][bj][m][0] * r, acc[ai][bj][m][1] * r); }
.LBB0_184:
	v_lshl_add_u64 v[168:169], v[194:195], 1, v[168:169]
	global_store_dwordx4 v[168:169], v[128:131], off sc1
	v_mul_f32_e32 v168, v149, v167
	v_pk_mul_f32 v[170:171], v[90:91], v[168:169] op_sel_hi:[1,0]
	v_lshlrev_b32_e32 v128, 3, v158
	v_and_b32_e32 v165, 0x178, v128
	v_pk_mul_f32 v[130:131], v[94:95], v[168:169] op_sel_hi:[1,0]
	v_pk_mul_f32 v[128:129], v[92:93], v[168:169] op_sel_hi:[1,0]
	s_and_b64 vcc, exec, s[0:1]
	s_mov_b64 s[28:29], -1
	v_pk_mul_f32 v[178:179], v[88:89], v[168:169] op_sel_hi:[1,0]
	v_cvt_pk_bf16_f32 v128, v128, v129
	v_cvt_pk_bf16_f32 v129, v130, v131
	s_nop 0
	v_cvt_pk_bf16_f32 v130, v178, v179
	v_cvt_pk_bf16_f32 v131, v170, v171
	s_cbranch_vccnz .LBB0_190
	s_cmp_lt_u32 s8, 4
	s_cbranch_scc1 .LBB0_187
	s_lshl_b32 s28, s8, 6
	s_add_i32 s28, s28, s40
	s_addk_i32 s28, 0xff00
	s_ashr_i32 s29, s28, 31
	s_lshl_b64 s[28:29], s[28:29], 14
	s_add_u32 s28, s16, s28
	s_addc_u32 s29, s17, s29
	s_lshl_b32 s41, s31, 1
	s_add_u32 s28, s28, s41
	s_addc_u32 s29, s29, 0
	v_lshlrev_b32_e32 v194, 1, v176
	v_lshl_add_u64 v[170:171], s[28:29], 0, v[194:195]
	v_lshl_add_u64 v[170:171], v[170:171], 0, s[78:79]
	s_mov_b64 s[28:29], 0

; __device__ __forceinline__ u32x4 pack8(const f32x4 v0, const f32x4 v1) { u32x4 w; w.x = cvt_pk_bf16(v0[0], v0[1]); w.y = cvt_pk_bf16(v0[2], v0[3]); w.z = cvt_pk_bf16(v1[0], v1[1]); w.w = cvt_pk_bf16(v1[2], v1[3]); return w; }
;     __device__ __forceinline__ bf16_t* dst(const Unit& u, int row, int bj, int wc, int fq, int col0) const {
;         if (u.pn < 2 || u.pn >= 6) return O + (size_t)row * ldc + col0 + bj * HALF;
;         const int b = row >> 11, t = row & 2047;
;         if (u.pn < 4) { const int hc = (u.pn - 2) * 4 + bj * 2 + (wc >> 1), chunk = (wc & 1) * 4 + fq;
;             return KC + (size_t)((b * 8 + hc) * 32 + (t >> 6)) * 4096 + chunk * 512 + (t & 63) * 8; }
;         const int h = (u.pn - 4) * 2 + bj, piece = wc * 4 + ((t & 63) >> 4);
;         return VC + (size_t)((b * 4 + h) * 32 + (t >> 6)) * 8192 + piece * 512 + (t & 15) * 32 + fq * 8;
;     __device__ __forceinline__ void operator()(const f32x4 (&acc)[2][2][4][2], const Unit& u, int wr, int wc, int fr, int fq) const {
;     ...
;                 for (int m = 0; m < 4; ++m) { const int row = row0 + ai * HALF + m * 16; const float r = rs[ai * 4 + m] * sc;
; #pragma unroll
;                     for (int bj = 0; bj < 2; ++bj) *(u32x4*)dst(u, row, bj, wc, fq, col0) = pack8(acc[ai][bj][m][0] * r, acc[ai][bj][m][1] * r); }
.LBB0_192:
	v_lshl_add_u64 v[170:171], v[194:195], 1, v[170:171]
	v_mov_b32_e32 v169, v168
	global_store_dwordx4 v[170:171], v[128:131], off sc1
	v_pk_mul_f32 v[170:171], v[84:85], v[168:169]
	s_and_b64 vcc, exec, s[0:1]
	v_mov_b32_e32 v128, v168
	v_mov_b32_e32 v129, v168
	v_pk_mul_f32 v[130:131], v[86:87], v[128:129]
	v_pk_mul_f32 v[168:169], v[80:81], v[168:169]
	s_mov_b64 s[28:29], -1
	v_pk_mul_f32 v[178:179], v[82:83], v[128:129]
	v_cvt_pk_bf16_f32 v128, v170, v171
	v_cvt_pk_bf16_f32 v129, v130, v131
	v_cvt_pk_bf16_f32 v130, v168, v169
	s_nop 0
	v_cvt_pk_bf16_f32 v131, v178, v179
	s_cbranch_vccnz .LBB0_198
	s_cmp_lt_u32 s8, 4
	s_cbranch_scc1 .LBB0_195
	s_lshl_b32 s28, s8, 6
	s_add_i32 s28, s28, s40
	s_addk_i32 s28, 0xff20
	s_ashr_i32 s29, s28, 31
	s_lshl_b64 s[28:29], s[28:29], 14
	s_add_u32 s28, s16, s28
	s_addc_u32 s29, s17, s29
	s_lshl_b32 s41, s31, 1
	s_add_u32 s28, s28, s41
	s_addc_u32 s29, s29, 0
	v_lshlrev_b32_e32 v194, 1, v176
	v_lshl_add_u64 v[168:169], s[28:29], 0, v[194:195]
	v_lshl_add_u64 v[168:169], v[168:169], 0, s[78:79]
	s_mov_b64 s[28:29], 0

; __device__ __forceinline__ u32x4 pack8(const f32x4 v0, const f32x4 v1) { u32x4 w; w.x = cvt_pk_bf16(v0[0], v0[1]); w.y = cvt_pk_bf16(v0[2], v0[3]); w.z = cvt_pk_bf16(v1[0], v1[1]); w.w = cvt_pk_bf16(v1[2], v1[3]); return w; }
;     __device__ __forceinline__ bf16_t* dst(const Unit& u, int row, int bj, int wc, int fq, int col0) const {
;         if (u.pn < 2 || u.pn >= 6) return O + (size_t)row * ldc + col0 + bj * HALF;
;         const int b = row >> 11, t = row & 2047;
;         if (u.pn < 4) { const int hc = (u.pn - 2) * 4 + bj * 2 + (wc >> 1), chunk = (wc & 1) * 4 + fq;
;             return KC + (size_t)((b * 8 + hc) * 32 + (t >> 6)) * 4096 + chunk * 512 + (t & 63) * 8; }
;         const int h = (u.pn - 4) * 2 + bj, piece = wc * 4 + ((t & 63) >> 4);
;         return VC + (size_t)((b * 4 + h) * 32 + (t >> 6)) * 8192 + piece * 512 + (t & 15) * 32 + fq * 8;
;     __device__ __forceinline__ void operator()(const f32x4 (&acc)[2][2][4][2], const Unit& u, int wr, int wc, int fr, int fq) const {
;     ...
;                 for (int m = 0; m < 4; ++m) { const int row = row0 + ai * HALF + m * 16; const float r = rs[ai * 4 + m] * sc;
; #pragma unroll
;                     for (int bj = 0; bj < 2; ++bj) *(u32x4*)dst(u, row, bj, wc, fq, col0) = pack8(acc[ai][bj][m][0] * r, acc[ai][bj][m][1] * r); }
.LBB0_200:
	v_lshl_add_u64 v[168:169], v[194:195], 1, v[168:169]
	global_store_dwordx4 v[168:169], v[128:131], off sc1
	v_mul_f32_e32 v168, v149, v161
	v_pk_mul_f32 v[170:171], v[74:75], v[168:169] op_sel_hi:[1,0]
	v_lshlrev_b32_e32 v128, 3, v156
	v_and_b32_e32 v165, 0x1f8, v128
	v_pk_mul_f32 v[130:131], v[78:79], v[168:169] op_sel_hi:[1,0]
	v_pk_mul_f32 v[128:129], v[76:77], v[168:169] op_sel_hi:[1,0]
	s_and_b64 vcc, exec, s[0:1]
	s_mov_b64 s[28:29], -1
	v_pk_mul_f32 v[178:179], v[72:73], v[168:169] op_sel_hi:[1,0]
	v_cvt_pk_bf16_f32 v128, v128, v129
	v_cvt_pk_bf16_f32 v129, v130, v131
	s_nop 0
	v_cvt_pk_bf16_f32 v130, v178, v179
	v_cvt_pk_bf16_f32 v131, v170, v171
	s_cbranch_vccnz .LBB0_206
	s_cmp_lt_u32 s8, 4
	s_cbranch_scc1 .LBB0_203
	s_lshl_b32 s28, s8, 6
	s_add_i32 s28, s28, s40
	s_addk_i32 s28, 0xff00
	s_ashr_i32 s29, s28, 31
	s_lshl_b64 s[28:29], s[28:29], 14
	s_add_u32 s28, s16, s28
	s_addc_u32 s29, s17, s29
	s_lshl_b32 s41, s31, 1
	s_add_u32 s28, s28, s41
	s_addc_u32 s29, s29, 0
	v_lshlrev_b32_e32 v194, 1, v176
	v_lshl_add_u64 v[170:171], s[28:29], 0, v[194:195]
	s_mov_b64 s[28:29], 0xc00
	v_lshl_add_u64 v[170:171], v[170:171], 0, s[28:29]
	s_mov_b64 s[28:29], 0

; __device__ __forceinline__ u32x4 pack8(const f32x4 v0, const f32x4 v1) { u32x4 w; w.x = cvt_pk_bf16(v0[0], v0[1]); w.y = cvt_pk_bf16(v0[2], v0[3]); w.z = cvt_pk_bf16(v1[0], v1[1]); w.w = cvt_pk_bf16(v1[2], v1[3]); return w; }
;     __device__ __forceinline__ bf16_t* dst(const Unit& u, int row, int bj, int wc, int fq, int col0) const {
;         if (u.pn < 2 || u.pn >= 6) return O + (size_t)row * ldc + col0 + bj * HALF;
;         const int b = row >> 11, t = row & 2047;
;         if (u.pn < 4) { const int hc = (u.pn - 2) * 4 + bj * 2 + (wc >> 1), chunk = (wc & 1) * 4 + fq;
;             return KC + (size_t)((b * 8 + hc) * 32 + (t >> 6)) * 4096 + chunk * 512 + (t & 63) * 8; }
;         const int h = (u.pn - 4) * 2 + bj, piece = wc * 4 + ((t & 63) >> 4);
;         return VC + (size_t)((b * 4 + h) * 32 + (t >> 6)) * 8192 + piece * 512 + (t & 15) * 32 + fq * 8;
;     __device__ __forceinline__ void operator()(const f32x4 (&acc)[2][2][4][2], const Unit& u, int wr, int wc, int fr, int fq) const {
;     ...
;                 for (int m = 0; m < 4; ++m) { const int row = row0 + ai * HALF + m * 16; const float r = rs[ai * 4 + m] * sc;
; #pragma unroll
;                     for (int bj = 0; bj < 2; ++bj) *(u32x4*)dst(u, row, bj, wc, fq, col0) = pack8(acc[ai][bj][m][0] * r, acc[ai][bj][m][1] * r); }
.LBB0_208:
	v_lshl_add_u64 v[170:171], v[194:195], 1, v[170:171]
	v_mov_b32_e32 v169, v168
	global_store_dwordx4 v[170:171], v[128:131], off sc1
	v_pk_mul_f32 v[170:171], v[68:69], v[168:169]
	s_and_b64 vcc, exec, s[0:1]
	v_mov_b32_e32 v128, v168
	v_mov_b32_e32 v129, v168
	v_pk_mul_f32 v[130:131], v[70:71], v[128:129]
	v_pk_mul_f32 v[168:169], v[64:65], v[168:169]
	s_mov_b64 s[28:29], -1
	v_pk_mul_f32 v[178:179], v[66:67], v[128:129]
	v_cvt_pk_bf16_f32 v128, v170, v171
	v_cvt_pk_bf16_f32 v129, v130, v131
	v_cvt_pk_bf16_f32 v130, v168, v169
	s_nop 0
	v_cvt_pk_bf16_f32 v131, v178, v179
	s_cbranch_vccnz .LBB0_214
	s_cmp_lt_u32 s8, 4
	s_cbranch_scc1 .LBB0_211
	s_lshl_b32 s28, s8, 6
	s_add_i32 s28, s28, s40
	s_addk_i32 s28, 0xff20
	s_ashr_i32 s29, s28, 31
	s_lshl_b64 s[28:29], s[28:29], 14
	s_add_u32 s28, s16, s28
	s_addc_u32 s29, s17, s29
	s_lshl_b32 s40, s31, 1
	s_add_u32 s28, s28, s40
	s_addc_u32 s29, s29, 0
	v_lshlrev_b32_e32 v194, 1, v176
	v_lshl_add_u64 v[168:169], s[28:29], 0, v[194:195]
	s_mov_b64 s[28:29], 0xc00
	v_lshl_add_u64 v[168:169], v[168:169], 0, s[28:29]
	s_mov_b64 s[28:29], 0

; __device__ __forceinline__ u32x4 pack8(const f32x4 v0, const f32x4 v1) { u32x4 w; w.x = cvt_pk_bf16(v0[0], v0[1]); w.y = cvt_pk_bf16(v0[2], v0[3]); w.z = cvt_pk_bf16(v1[0], v1[1]); w.w = cvt_pk_bf16(v1[2], v1[3]); return w; }
;     __device__ __forceinline__ bf16_t* dst(const Unit& u, int row, int bj, int wc, int fq, int col0) const {
;         if (u.pn < 2 || u.pn >= 6) return O + (size_t)row * ldc + col0 + bj * HALF;
;         const int b = row >> 11, t = row & 2047;
;         if (u.pn < 4) { const int hc = (u.pn - 2) * 4 + bj * 2 + (wc >> 1), chunk = (wc & 1) * 4 + fq;
;             return KC + (size_t)((b * 8 + hc) * 32 + (t >> 6)) * 4096 + chunk * 512 + (t & 63) * 8; }
;         const int h = (u.pn - 4) * 2 + bj, piece = wc * 4 + ((t & 63) >> 4);
;         return VC + (size_t)((b * 4 + h) * 32 + (t >> 6)) * 8192 + piece * 512 + (t & 15) * 32 + fq * 8;
;     __device__ __forceinline__ void operator()(const f32x4 (&acc)[2][2][4][2], const Unit& u, int wr, int wc, int fr, int fq) const {
;     ...
;                 for (int m = 0; m < 4; ++m) { const int row = row0 + ai * HALF + m * 16; const float r = rs[ai * 4 + m] * sc;
; #pragma unroll
;                     for (int bj = 0; bj < 2; ++bj) *(u32x4*)dst(u, row, bj, wc, fq, col0) = pack8(acc[ai][bj][m][0] * r, acc[ai][bj][m][1] * r); }
.LBB0_216:
	v_lshl_add_u64 v[168:169], v[194:195], 1, v[168:169]
	global_store_dwordx4 v[168:169], v[128:131], off sc1
	v_mul_f32_e32 v168, v149, v159
	v_pk_mul_f32 v[170:171], v[58:59], v[168:169] op_sel_hi:[1,0]
	v_ashrrev_i32_e32 v128, 11, v152
	v_lshlrev_b32_e32 v165, 7, v128
	v_lshlrev_b32_e32 v177, 8, v128
	v_bfe_u32 v128, v152, 6, 5
	v_or_b32_e32 v179, v165, v128
	v_or_b32_e32 v178, v177, v128
	v_pk_mul_f32 v[130:131], v[62:63], v[168:169] op_sel_hi:[1,0]
	v_pk_mul_f32 v[128:129], v[60:61], v[168:169] op_sel_hi:[1,0]
	s_and_b64 vcc, exec, s[0:1]
	s_mov_b64 s[28:29], -1
	v_pk_mul_f32 v[180:181], v[56:57], v[168:169] op_sel_hi:[1,0]
	v_cvt_pk_bf16_f32 v128, v128, v129
	v_cvt_pk_bf16_f32 v129, v130, v131
	s_nop 0
	v_cvt_pk_bf16_f32 v130, v180, v181
	v_cvt_pk_bf16_f32 v131, v170, v171
	s_cbranch_vccnz .LBB0_222
	s_cmp_lt_u32 s8, 4
	s_cbranch_scc1 .LBB0_219
	s_lshl_b32 s28, s8, 6
	s_addk_i32 s28, 0xff00
	v_add_u32_e32 v170, s28, v179
	v_ashrrev_i32_e32 v171, 31, v170
	v_lshlrev_b64 v[170:171], 14, v[170:171]
	v_lshl_add_u64 v[170:171], s[16:17], 0, v[170:171]
	s_lshl_b32 s72, s31, 1
	v_lshl_add_u64 v[170:171], v[170:171], 0, s[72:73]
	v_lshlrev_b32_e32 v194, 1, v176
	v_lshl_add_u64 v[170:171], v[170:171], 0, v[194:195]
	s_mov_b64 s[28:29], 0

; __device__ __forceinline__ u32x4 pack8(const f32x4 v0, const f32x4 v1) { u32x4 w; w.x = cvt_pk_bf16(v0[0], v0[1]); w.y = cvt_pk_bf16(v0[2], v0[3]); w.z = cvt_pk_bf16(v1[0], v1[1]); w.w = cvt_pk_bf16(v1[2], v1[3]); return w; }
;     __device__ __forceinline__ bf16_t* dst(const Unit& u, int row, int bj, int wc, int fq, int col0) const {
;         if (u.pn < 2 || u.pn >= 6) return O + (size_t)row * ldc + col0 + bj * HALF;
;         const int b = row >> 11, t = row & 2047;
;         if (u.pn < 4) { const int hc = (u.pn - 2) * 4 + bj * 2 + (wc >> 1), chunk = (wc & 1) * 4 + fq;
;             return KC + (size_t)((b * 8 + hc) * 32 + (t >> 6)) * 4096 + chunk * 512 + (t & 63) * 8; }
;         const int h = (u.pn - 4) * 2 + bj, piece = wc * 4 + ((t & 63) >> 4);
;         return VC + (size_t)((b * 4 + h) * 32 + (t >> 6)) * 8192 + piece * 512 + (t & 15) * 32 + fq * 8;
;     __device__ __forceinline__ void operator()(const f32x4 (&acc)[2][2][4][2], const Unit& u, int wr, int wc, int fr, int fq) const {
;     ...
;                 for (int m = 0; m < 4; ++m) { const int row = row0 + ai * HALF + m * 16; const float r = rs[ai * 4 + m] * sc;
; #pragma unroll
;                     for (int bj = 0; bj < 2; ++bj) *(u32x4*)dst(u, row, bj, wc, fq, col0) = pack8(acc[ai][bj][m][0] * r, acc[ai][bj][m][1] * r); }
.LBB0_224:
	v_lshl_add_u64 v[170:171], v[194:195], 1, v[170:171]
	v_mov_b32_e32 v169, v168
	global_store_dwordx4 v[170:171], v[128:131], off sc1
	v_pk_mul_f32 v[170:171], v[52:53], v[168:169]
	s_and_b64 vcc, exec, s[0:1]
	v_mov_b32_e32 v128, v168
	v_mov_b32_e32 v129, v168
	v_pk_mul_f32 v[130:131], v[54:55], v[128:129]
	v_pk_mul_f32 v[168:169], v[48:49], v[168:169]
	s_mov_b64 s[28:29], -1
	v_pk_mul_f32 v[180:181], v[50:51], v[128:129]
	v_cvt_pk_bf16_f32 v128, v170, v171
	v_cvt_pk_bf16_f32 v129, v130, v131
	v_cvt_pk_bf16_f32 v130, v168, v169
	s_nop 0
	v_cvt_pk_bf16_f32 v131, v180, v181
	s_cbranch_vccnz .LBB0_230
	s_cmp_lt_u32 s8, 4
	s_cbranch_scc1 .LBB0_227
	s_lshl_b32 s28, s8, 6
	s_addk_i32 s28, 0xff20
	v_add_u32_e32 v168, s28, v179
	v_ashrrev_i32_e32 v169, 31, v168
	v_lshlrev_b64 v[168:169], 14, v[168:169]
	v_lshl_add_u64 v[168:169], s[16:17], 0, v[168:169]
	s_lshl_b32 s72, s31, 1
	v_lshl_add_u64 v[168:169], v[168:169], 0, s[72:73]
	v_lshlrev_b32_e32 v194, 1, v176
	v_lshl_add_u64 v[168:169], v[168:169], 0, v[194:195]
	s_mov_b64 s[28:29], 0

; __device__ __forceinline__ u32x4 pack8(const f32x4 v0, const f32x4 v1) { u32x4 w; w.x = cvt_pk_bf16(v0[0], v0[1]); w.y = cvt_pk_bf16(v0[2], v0[3]); w.z = cvt_pk_bf16(v1[0], v1[1]); w.w = cvt_pk_bf16(v1[2], v1[3]); return w; }
;     __device__ __forceinline__ bf16_t* dst(const Unit& u, int row, int bj, int wc, int fq, int col0) const {
;         if (u.pn < 2 || u.pn >= 6) return O + (size_t)row * ldc + col0 + bj * HALF;
;         const int b = row >> 11, t = row & 2047;
;         if (u.pn < 4) { const int hc = (u.pn - 2) * 4 + bj * 2 + (wc >> 1), chunk = (wc & 1) * 4 + fq;
;             return KC + (size_t)((b * 8 + hc) * 32 + (t >> 6)) * 4096 + chunk * 512 + (t & 63) * 8; }
;         const int h = (u.pn - 4) * 2 + bj, piece = wc * 4 + ((t & 63) >> 4);
;         return VC + (size_t)((b * 4 + h) * 32 + (t >> 6)) * 8192 + piece * 512 + (t & 15) * 32 + fq * 8;
;     __device__ __forceinline__ void operator()(const f32x4 (&acc)[2][2][4][2], const Unit& u, int wr, int wc, int fr, int fq) const {
;     ...
;                 for (int m = 0; m < 4; ++m) { const int row = row0 + ai * HALF + m * 16; const float r = rs[ai * 4 + m] * sc;
; #pragma unroll
;                     for (int bj = 0; bj < 2; ++bj) *(u32x4*)dst(u, row, bj, wc, fq, col0) = pack8(acc[ai][bj][m][0] * r, acc[ai][bj][m][1] * r); }
.LBB0_232:
	v_lshl_add_u64 v[168:169], v[194:195], 1, v[168:169]
	global_store_dwordx4 v[168:169], v[128:131], off sc1
	v_mul_f32_e32 v168, v149, v157
	v_pk_mul_f32 v[170:171], v[42:43], v[168:169] op_sel_hi:[1,0]
	v_bfe_u32 v128, v150, 6, 5
	v_or_b32_e32 v180, v165, v128
	v_or_b32_e32 v179, v177, v128
	v_lshlrev_b32_e32 v128, 3, v150
	v_and_b32_e32 v178, 0xf8, v128
	v_pk_mul_f32 v[130:131], v[46:47], v[168:169] op_sel_hi:[1,0]
	v_pk_mul_f32 v[128:129], v[44:45], v[168:169] op_sel_hi:[1,0]
	s_and_b64 vcc, exec, s[0:1]
	s_mov_b64 s[28:29], -1
	v_pk_mul_f32 v[182:183], v[40:41], v[168:169] op_sel_hi:[1,0]
	v_cvt_pk_bf16_f32 v128, v128, v129
	v_cvt_pk_bf16_f32 v129, v130, v131
	s_nop 0
	v_cvt_pk_bf16_f32 v130, v182, v183
	v_cvt_pk_bf16_f32 v131, v170, v171
	s_cbranch_vccnz .LBB0_238
	s_cmp_lt_u32 s8, 4
	s_cbranch_scc1 .LBB0_235
	s_lshl_b32 s28, s8, 6
	s_addk_i32 s28, 0xff00
	v_add_u32_e32 v170, s28, v180
	v_ashrrev_i32_e32 v171, 31, v170
	v_lshlrev_b64 v[170:171], 14, v[170:171]
	v_lshl_add_u64 v[170:171], s[16:17], 0, v[170:171]
	s_lshl_b32 s72, s31, 1
	v_lshl_add_u64 v[170:171], v[170:171], 0, s[72:73]
	v_lshlrev_b32_e32 v194, 1, v176
	v_lshl_add_u64 v[170:171], v[170:171], 0, v[194:195]
	s_mov_b64 s[28:29], 0x400
	v_lshl_add_u64 v[170:171], v[170:171], 0, s[28:29]
	s_mov_b64 s[28:29], 0

; __device__ __forceinline__ u32x4 pack8(const f32x4 v0, const f32x4 v1) { u32x4 w; w.x = cvt_pk_bf16(v0[0], v0[1]); w.y = cvt_pk_bf16(v0[2], v0[3]); w.z = cvt_pk_bf16(v1[0], v1[1]); w.w = cvt_pk_bf16(v1[2], v1[3]); return w; }
;     __device__ __forceinline__ bf16_t* dst(const Unit& u, int row, int bj, int wc, int fq, int col0) const {
;         if (u.pn < 2 || u.pn >= 6) return O + (size_t)row * ldc + col0 + bj * HALF;
;         const int b = row >> 11, t = row & 2047;
;         if (u.pn < 4) { const int hc = (u.pn - 2) * 4 + bj * 2 + (wc >> 1), chunk = (wc & 1) * 4 + fq;
;             return KC + (size_t)((b * 8 + hc) * 32 + (t >> 6)) * 4096 + chunk * 512 + (t & 63) * 8; }
;         const int h = (u.pn - 4) * 2 + bj, piece = wc * 4 + ((t & 63) >> 4);
;         return VC + (size_t)((b * 4 + h) * 32 + (t >> 6)) * 8192 + piece * 512 + (t & 15) * 32 + fq * 8;
;     __device__ __forceinline__ void operator()(const f32x4 (&acc)[2][2][4][2], const Unit& u, int wr, int wc, int fr, int fq) const {
;     ...
;                 for (int m = 0; m < 4; ++m) { const int row = row0 + ai * HALF + m * 16; const float r = rs[ai * 4 + m] * sc;
; #pragma unroll
;                     for (int bj = 0; bj < 2; ++bj) *(u32x4*)dst(u, row, bj, wc, fq, col0) = pack8(acc[ai][bj][m][0] * r, acc[ai][bj][m][1] * r); }
.LBB0_240:
	v_lshl_add_u64 v[170:171], v[194:195], 1, v[170:171]
	v_mov_b32_e32 v169, v168
	global_store_dwordx4 v[170:171], v[128:131], off sc1
	v_pk_mul_f32 v[170:171], v[36:37], v[168:169]
	s_and_b64 vcc, exec, s[0:1]
	v_mov_b32_e32 v128, v168
	v_mov_b32_e32 v129, v168
	v_pk_mul_f32 v[130:131], v[38:39], v[128:129]
	v_pk_mul_f32 v[168:169], v[32:33], v[168:169]
	s_mov_b64 s[28:29], -1
	v_pk_mul_f32 v[182:183], v[34:35], v[128:129]
	v_cvt_pk_bf16_f32 v128, v170, v171
	v_cvt_pk_bf16_f32 v129, v130, v131
	v_cvt_pk_bf16_f32 v130, v168, v169
	s_nop 0
	v_cvt_pk_bf16_f32 v131, v182, v183
	s_cbranch_vccnz .LBB0_246
	s_cmp_lt_u32 s8, 4
	s_cbranch_scc1 .LBB0_243
	s_lshl_b32 s28, s8, 6
	s_addk_i32 s28, 0xff20
	v_add_u32_e32 v168, s28, v180
	v_ashrrev_i32_e32 v169, 31, v168
	v_lshlrev_b64 v[168:169], 14, v[168:169]
	v_lshl_add_u64 v[168:169], s[16:17], 0, v[168:169]
	s_lshl_b32 s72, s31, 1
	v_lshl_add_u64 v[168:169], v[168:169], 0, s[72:73]
	v_lshlrev_b32_e32 v194, 1, v176
	v_lshl_add_u64 v[168:169], v[168:169], 0, v[194:195]
	s_mov_b64 s[28:29], 0x400
	v_lshl_add_u64 v[168:169], v[168:169], 0, s[28:29]
	s_mov_b64 s[28:29], 0

; __device__ __forceinline__ u32x4 pack8(const f32x4 v0, const f32x4 v1) { u32x4 w; w.x = cvt_pk_bf16(v0[0], v0[1]); w.y = cvt_pk_bf16(v0[2], v0[3]); w.z = cvt_pk_bf16(v1[0], v1[1]); w.w = cvt_pk_bf16(v1[2], v1[3]); return w; }
;     __device__ __forceinline__ bf16_t* dst(const Unit& u, int row, int bj, int wc, int fq, int col0) const {
;         if (u.pn < 2 || u.pn >= 6) return O + (size_t)row * ldc + col0 + bj * HALF;
;         const int b = row >> 11, t = row & 2047;
;         if (u.pn < 4) { const int hc = (u.pn - 2) * 4 + bj * 2 + (wc >> 1), chunk = (wc & 1) * 4 + fq;
;             return KC + (size_t)((b * 8 + hc) * 32 + (t >> 6)) * 4096 + chunk * 512 + (t & 63) * 8; }
;         const int h = (u.pn - 4) * 2 + bj, piece = wc * 4 + ((t & 63) >> 4);
;         return VC + (size_t)((b * 4 + h) * 32 + (t >> 6)) * 8192 + piece * 512 + (t & 15) * 32 + fq * 8;
;     __device__ __forceinline__ void operator()(const f32x4 (&acc)[2][2][4][2], const Unit& u, int wr, int wc, int fr, int fq) const {
;     ...
;                 for (int m = 0; m < 4; ++m) { const int row = row0 + ai * HALF + m * 16; const float r = rs[ai * 4 + m] * sc;
; #pragma unroll
;                     for (int bj = 0; bj < 2; ++bj) *(u32x4*)dst(u, row, bj, wc, fq, col0) = pack8(acc[ai][bj][m][0] * r, acc[ai][bj][m][1] * r); }
.LBB0_248:
	v_lshl_add_u64 v[168:169], v[194:195], 1, v[168:169]
	global_store_dwordx4 v[168:169], v[128:131], off sc1
	v_mul_f32_e32 v168, v149, v153
	v_pk_mul_f32 v[170:171], v[26:27], v[168:169] op_sel_hi:[1,0]
	v_bfe_u32 v128, v148, 6, 5
	v_or_b32_e32 v180, v165, v128
	v_or_b32_e32 v179, v177, v128
	v_lshlrev_b32_e32 v128, 3, v148
	v_and_b32_e32 v178, 0x178, v128
	v_pk_mul_f32 v[130:131], v[30:31], v[168:169] op_sel_hi:[1,0]
	v_pk_mul_f32 v[128:129], v[28:29], v[168:169] op_sel_hi:[1,0]
	s_and_b64 vcc, exec, s[0:1]
	s_mov_b64 s[28:29], -1
	v_pk_mul_f32 v[182:183], v[24:25], v[168:169] op_sel_hi:[1,0]
	v_cvt_pk_bf16_f32 v128, v128, v129
	v_cvt_pk_bf16_f32 v129, v130, v131
	s_nop 0
	v_cvt_pk_bf16_f32 v130, v182, v183
	v_cvt_pk_bf16_f32 v131, v170, v171
	s_cbranch_vccnz .LBB0_254
	s_cmp_lt_u32 s8, 4
	s_cbranch_scc1 .LBB0_251
	s_lshl_b32 s28, s8, 6
	s_addk_i32 s28, 0xff00
	v_add_u32_e32 v170, s28, v180
	v_ashrrev_i32_e32 v171, 31, v170
	v_lshlrev_b64 v[170:171], 14, v[170:171]
	v_lshl_add_u64 v[170:171], s[16:17], 0, v[170:171]
	s_lshl_b32 s72, s31, 1
	v_lshl_add_u64 v[170:171], v[170:171], 0, s[72:73]
	v_lshlrev_b32_e32 v194, 1, v176
	v_lshl_add_u64 v[170:171], v[170:171], 0, v[194:195]
	v_lshl_add_u64 v[170:171], v[170:171], 0, s[78:79]
	s_mov_b64 s[28:29], 0

; __device__ __forceinline__ u32x4 pack8(const f32x4 v0, const f32x4 v1) { u32x4 w; w.x = cvt_pk_bf16(v0[0], v0[1]); w.y = cvt_pk_bf16(v0[2], v0[3]); w.z = cvt_pk_bf16(v1[0], v1[1]); w.w = cvt_pk_bf16(v1[2], v1[3]); return w; }
;     __device__ __forceinline__ bf16_t* dst(const Unit& u, int row, int bj, int wc, int fq, int col0) const {
;         if (u.pn < 2 || u.pn >= 6) return O + (size_t)row * ldc + col0 + bj * HALF;
;         const int b = row >> 11, t = row & 2047;
;         if (u.pn < 4) { const int hc = (u.pn - 2) * 4 + bj * 2 + (wc >> 1), chunk = (wc & 1) * 4 + fq;
;             return KC + (size_t)((b * 8 + hc) * 32 + (t >> 6)) * 4096 + chunk * 512 + (t & 63) * 8; }
;         const int h = (u.pn - 4) * 2 + bj, piece = wc * 4 + ((t & 63) >> 4);
;         return VC + (size_t)((b * 4 + h) * 32 + (t >> 6)) * 8192 + piece * 512 + (t & 15) * 32 + fq * 8;
;     __device__ __forceinline__ void operator()(const f32x4 (&acc)[2][2][4][2], const Unit& u, int wr, int wc, int fr, int fq) const {
;     ...
;                 for (int m = 0; m < 4; ++m) { const int row = row0 + ai * HALF + m * 16; const float r = rs[ai * 4 + m] * sc;
; #pragma unroll
;                     for (int bj = 0; bj < 2; ++bj) *(u32x4*)dst(u, row, bj, wc, fq, col0) = pack8(acc[ai][bj][m][0] * r, acc[ai][bj][m][1] * r); }
.LBB0_256:
	v_lshl_add_u64 v[170:171], v[194:195], 1, v[170:171]
	v_mov_b32_e32 v169, v168
	global_store_dwordx4 v[170:171], v[128:131], off sc1
	v_pk_mul_f32 v[170:171], v[20:21], v[168:169]
	s_and_b64 vcc, exec, s[0:1]
	v_mov_b32_e32 v128, v168
	v_mov_b32_e32 v129, v168
	v_pk_mul_f32 v[130:131], v[22:23], v[128:129]
	v_pk_mul_f32 v[168:169], v[16:17], v[168:169]
	s_mov_b64 s[28:29], -1
	v_pk_mul_f32 v[182:183], v[18:19], v[128:129]
	v_cvt_pk_bf16_f32 v128, v170, v171
	v_cvt_pk_bf16_f32 v129, v130, v131
	v_cvt_pk_bf16_f32 v130, v168, v169
	s_nop 0
	v_cvt_pk_bf16_f32 v131, v182, v183
	s_cbranch_vccnz .LBB0_262
	s_cmp_lt_u32 s8, 4
	s_cbranch_scc1 .LBB0_259
	s_lshl_b32 s28, s8, 6
	s_addk_i32 s28, 0xff20
	v_add_u32_e32 v168, s28, v180
	v_ashrrev_i32_e32 v169, 31, v168
	v_lshlrev_b64 v[168:169], 14, v[168:169]
	v_lshl_add_u64 v[168:169], s[16:17], 0, v[168:169]
	s_lshl_b32 s72, s31, 1
	v_lshl_add_u64 v[168:169], v[168:169], 0, s[72:73]
	v_lshlrev_b32_e32 v194, 1, v176
	v_lshl_add_u64 v[168:169], v[168:169], 0, v[194:195]
	v_lshl_add_u64 v[168:169], v[168:169], 0, s[78:79]
	s_mov_b64 s[28:29], 0

; __device__ __forceinline__ u32x4 pack8(const f32x4 v0, const f32x4 v1) { u32x4 w; w.x = cvt_pk_bf16(v0[0], v0[1]); w.y = cvt_pk_bf16(v0[2], v0[3]); w.z = cvt_pk_bf16(v1[0], v1[1]); w.w = cvt_pk_bf16(v1[2], v1[3]); return w; }
;     __device__ __forceinline__ bf16_t* dst(const Unit& u, int row, int bj, int wc, int fq, int col0) const {
;         if (u.pn < 2 || u.pn >= 6) return O + (size_t)row * ldc + col0 + bj * HALF;
;         const int b = row >> 11, t = row & 2047;
;         if (u.pn < 4) { const int hc = (u.pn - 2) * 4 + bj * 2 + (wc >> 1), chunk = (wc & 1) * 4 + fq;
;             return KC + (size_t)((b * 8 + hc) * 32 + (t >> 6)) * 4096 + chunk * 512 + (t & 63) * 8; }
;         const int h = (u.pn - 4) * 2 + bj, piece = wc * 4 + ((t & 63) >> 4);
;         return VC + (size_t)((b * 4 + h) * 32 + (t >> 6)) * 8192 + piece * 512 + (t & 15) * 32 + fq * 8;
;     __device__ __forceinline__ void operator()(const f32x4 (&acc)[2][2][4][2], const Unit& u, int wr, int wc, int fr, int fq) const {
;     ...
;                 for (int m = 0; m < 4; ++m) { const int row = row0 + ai * HALF + m * 16; const float r = rs[ai * 4 + m] * sc;
; #pragma unroll
;                     for (int bj = 0; bj < 2; ++bj) *(u32x4*)dst(u, row, bj, wc, fq, col0) = pack8(acc[ai][bj][m][0] * r, acc[ai][bj][m][1] * r); }
.LBB0_264:
	v_lshl_add_u64 v[168:169], v[194:195], 1, v[168:169]
	global_store_dwordx4 v[168:169], v[128:131], off sc1
	v_mul_f32_e32 v168, v149, v151
	v_pk_mul_f32 v[170:171], v[10:11], v[168:169] op_sel_hi:[1,0]
	v_bfe_u32 v128, v144, 6, 5
	v_or_b32_e32 v178, v165, v128
	v_or_b32_e32 v177, v177, v128
	v_lshlrev_b32_e32 v128, 3, v144
	v_and_b32_e32 v165, 0x1f8, v128
	v_pk_mul_f32 v[130:131], v[14:15], v[168:169] op_sel_hi:[1,0]
	v_pk_mul_f32 v[128:129], v[12:13], v[168:169] op_sel_hi:[1,0]
	s_and_b64 vcc, exec, s[0:1]
	s_mov_b64 s[28:29], -1
	v_pk_mul_f32 v[180:181], v[8:9], v[168:169] op_sel_hi:[1,0]
	v_cvt_pk_bf16_f32 v128, v128, v129
	v_cvt_pk_bf16_f32 v129, v130, v131
	s_nop 0
	v_cvt_pk_bf16_f32 v130, v180, v181
	v_cvt_pk_bf16_f32 v131, v170, v171
	s_cbranch_vccnz .LBB0_270
	s_cmp_lt_u32 s8, 4
	s_cbranch_scc1 .LBB0_267
	s_lshl_b32 s28, s8, 6
	s_addk_i32 s28, 0xff00
	v_add_u32_e32 v170, s28, v178
	v_ashrrev_i32_e32 v171, 31, v170
	v_lshlrev_b64 v[170:171], 14, v[170:171]
	v_lshl_add_u64 v[170:171], s[16:17], 0, v[170:171]
	s_lshl_b32 s72, s31, 1
	v_lshl_add_u64 v[170:171], v[170:171], 0, s[72:73]
	v_lshlrev_b32_e32 v194, 1, v176
	v_lshl_add_u64 v[170:171], v[170:171], 0, v[194:195]
	s_mov_b64 s[28:29], 0xc00
	v_lshl_add_u64 v[170:171], v[170:171], 0, s[28:29]
	s_mov_b64 s[28:29], 0

; __device__ __forceinline__ u32x4 pack8(const f32x4 v0, const f32x4 v1) { u32x4 w; w.x = cvt_pk_bf16(v0[0], v0[1]); w.y = cvt_pk_bf16(v0[2], v0[3]); w.z = cvt_pk_bf16(v1[0], v1[1]); w.w = cvt_pk_bf16(v1[2], v1[3]); return w; }
;     __device__ __forceinline__ bf16_t* dst(const Unit& u, int row, int bj, int wc, int fq, int col0) const {
;         if (u.pn < 2 || u.pn >= 6) return O + (size_t)row * ldc + col0 + bj * HALF;
;         const int b = row >> 11, t = row & 2047;
;         if (u.pn < 4) { const int hc = (u.pn - 2) * 4 + bj * 2 + (wc >> 1), chunk = (wc & 1) * 4 + fq;
;             return KC + (size_t)((b * 8 + hc) * 32 + (t >> 6)) * 4096 + chunk * 512 + (t & 63) * 8; }
;         const int h = (u.pn - 4) * 2 + bj, piece = wc * 4 + ((t & 63) >> 4);
;         return VC + (size_t)((b * 4 + h) * 32 + (t >> 6)) * 8192 + piece * 512 + (t & 15) * 32 + fq * 8;
;     __device__ __forceinline__ void operator()(const f32x4 (&acc)[2][2][4][2], const Unit& u, int wr, int wc, int fr, int fq) const {
;     ...
;                 for (int m = 0; m < 4; ++m) { const int row = row0 + ai * HALF + m * 16; const float r = rs[ai * 4 + m] * sc;
; #pragma unroll
;                     for (int bj = 0; bj < 2; ++bj) *(u32x4*)dst(u, row, bj, wc, fq, col0) = pack8(acc[ai][bj][m][0] * r, acc[ai][bj][m][1] * r); }
.LBB0_272:
	v_lshl_add_u64 v[170:171], v[194:195], 1, v[170:171]
	v_mov_b32_e32 v169, v168
	global_store_dwordx4 v[170:171], v[128:131], off sc1
	v_pk_mul_f32 v[170:171], v[4:5], v[168:169]
	s_and_b64 vcc, exec, s[0:1]
	v_mov_b32_e32 v128, v168
	v_mov_b32_e32 v129, v168
	v_pk_mul_f32 v[130:131], v[6:7], v[128:129]
	v_pk_mul_f32 v[168:169], v[0:1], v[168:169]
	s_mov_b64 s[0:1], -1
	v_pk_mul_f32 v[180:181], v[2:3], v[128:129]
	v_cvt_pk_bf16_f32 v128, v170, v171
	v_cvt_pk_bf16_f32 v129, v130, v131
	v_cvt_pk_bf16_f32 v130, v168, v169
	s_nop 0
	v_cvt_pk_bf16_f32 v131, v180, v181
	s_cbranch_vccnz .LBB0_278
	s_cmp_lt_u32 s8, 4
	s_cbranch_scc1 .LBB0_275
	s_lshl_b32 s0, s8, 6
	s_addk_i32 s0, 0xff20
	v_add_u32_e32 v168, s0, v178
	v_ashrrev_i32_e32 v169, 31, v168
	v_lshlrev_b64 v[168:169], 14, v[168:169]
	v_lshl_add_u64 v[168:169], s[16:17], 0, v[168:169]
	s_lshl_b32 s72, s31, 1
	v_lshl_add_u64 v[168:169], v[168:169], 0, s[72:73]
	v_lshlrev_b32_e32 v194, 1, v176
	v_lshl_add_u64 v[168:169], v[168:169], 0, v[194:195]
	s_mov_b64 s[0:1], 0xc00
	v_lshl_add_u64 v[168:169], v[168:169], 0, s[0:1]
	s_mov_b64 s[0:1], 0

; __device__ __forceinline__ u32x4 pack8(const f32x4 v0, const f32x4 v1) { u32x4 w; w.x = cvt_pk_bf16(v0[0], v0[1]); w.y = cvt_pk_bf16(v0[2], v0[3]); w.z = cvt_pk_bf16(v1[0], v1[1]); w.w = cvt_pk_bf16(v1[2], v1[3]); return w; }
;     __device__ __forceinline__ bf16_t* dst(const Unit& u, int row, int bj, int wc, int fq, int col0) const {
;     ...
;         if (u.pn < 4) { const int hc = (u.pn - 2) * 4 + bj * 2 + (wc >> 1), chunk = (wc & 1) * 4 + fq;
;             return KC + (size_t)((b * 8 + hc) * 32 + (t >> 6)) * 4096 + chunk * 512 + (t & 63) * 8; }
;     __device__ __forceinline__ void operator()(const f32x4 (&acc)[2][2][4][2], const Unit& u, int wr, int wc, int fr, int fq) const {
;     ...
;                     for (int bj = 0; bj < 2; ++bj) { f32x4 v0 = acc[ai][bj][m][0] * r, v1 = acc[ai][bj][m][1] * r; f32x4 p0, p1;
; #pragma unroll
;                         for (int e = 0; e < 4; ++e) { p0[e] = __shfl_xor(v0[e], 16); p1[e] = __shfl_xor(v1[e], 16); }
; #pragma unroll
;                         for (int e = 0; e < 4; ++e) { v0[e] = v0[e] * c[e] + p0[e] * sn[e]; v1[e] = v1[e] * c[4 + e] + p1[e] * sn[4 + e]; }
;                         *(u32x4*)dst(u, row, bj, wc, fq, col0) = pack8(v0, v1); } }
.LBB0_286:
	v_mov_b32_e32 v165, v164
	v_lshl_add_u64 v[124:125], v[126:127], 1, v[124:125]
	global_store_dwordx4 v[124:125], v[120:123], off sc1
	v_pk_mul_f32 v[116:117], v[116:117], v[164:165]
	v_pk_mul_f32 v[112:113], v[112:113], v[164:165]
	v_mov_b32_e32 v120, v164
	v_mov_b32_e32 v121, v164
	v_pk_mul_f32 v[118:119], v[118:119], v[120:121]
	v_pk_mul_f32 v[114:115], v[114:115], v[120:121]
	ds_bpermute_b32 v120, v145, v116
	ds_bpermute_b32 v121, v145, v112
	ds_bpermute_b32 v122, v145, v117
	ds_bpermute_b32 v123, v145, v113
	ds_bpermute_b32 v124, v145, v118
	ds_bpermute_b32 v125, v145, v114
	s_waitcnt lgkmcnt(5)
	v_mul_f32_e32 v120, v175, v120
	ds_bpermute_b32 v126, v145, v119
	v_fmac_f32_e32 v120, v116, v169
	s_waitcnt lgkmcnt(5)
	v_mul_f32_e32 v116, v183, v121
	v_fmac_f32_e32 v116, v112, v180
	s_waitcnt lgkmcnt(4)
	v_mul_f32_e32 v112, v177, v122
	ds_bpermute_b32 v127, v145, v115
	v_fmac_f32_e32 v112, v117, v170
	s_waitcnt lgkmcnt(4)
	v_mul_f32_e32 v117, v185, v123
	v_fmac_f32_e32 v117, v113, v181
	s_waitcnt lgkmcnt(3)
	v_mul_f32_e32 v113, v178, v124
	v_fmac_f32_e32 v113, v118, v171
	s_waitcnt lgkmcnt(2)
	v_mul_f32_e32 v118, v186, v125
	v_fmac_f32_e32 v118, v114, v182
	s_waitcnt lgkmcnt(1)
	v_mul_f32_e32 v114, v179, v126
	v_fmac_f32_e32 v114, v119, v176
	s_waitcnt lgkmcnt(0)
	v_mul_f32_e32 v119, v187, v127
	v_cvt_pk_bf16_f32 v112, v120, v112
	v_cvt_pk_bf16_f32 v113, v113, v114
	v_cvt_pk_bf16_f32 v114, v116, v117
	v_cndmask_b32_e64 v116, 0, 1, s[28:29]
	v_fmac_f32_e32 v119, v115, v184
	v_cmp_ne_u32_e64 s[42:43], 1, v116
	s_andn2_b64 vcc, exec, s[28:29]
	s_mov_b64 s[28:29], -1
	v_cvt_pk_bf16_f32 v115, v118, v119
	s_cbranch_vccnz .LBB0_288
	s_lshl_b32 s28, s19, 5
	s_lshl_b32 s29, s8, 7
	s_or_b32 s28, s29, s28
	s_add_i32 s28, s28, s21
	s_addk_i32 s28, 0xff40
	s_ashr_i32 s29, s28, 31
	s_lshl_b64 s[28:29], s[28:29], 13
	s_add_u32 s28, s14, s28
	s_addc_u32 s29, s15, s29
	v_mov_b32_e32 v155, v195
	v_lshl_add_u64 v[116:117], s[28:29], 0, v[194:195]
	s_mov_b64 s[28:29], 0
	v_mov_b64_e32 v[118:119], v[154:155]

; __device__ __forceinline__ u32x4 pack8(const f32x4 v0, const f32x4 v1) { u32x4 w; w.x = cvt_pk_bf16(v0[0], v0[1]); w.y = cvt_pk_bf16(v0[2], v0[3]); w.z = cvt_pk_bf16(v1[0], v1[1]); w.w = cvt_pk_bf16(v1[2], v1[3]); return w; }
;     __device__ __forceinline__ void operator()(const f32x4 (&acc)[2][2][4][2], const Unit& u, int wr, int wc, int fr, int fq) const {
;     ...
;                 for (int m = 0; m < 4; ++m) { const int row = row0 + ai * HALF + m * 16; const float r = rs[ai * 4 + m] * sc; const float pf = (float)ps[ai * 4 + m];
;                     float c[8], sn[8];
; #pragma unroll
;                     for (int e = 0; e < 8; ++e) { const float rev = __builtin_amdgcn_fractf((pf * invf[e]) * 0.15915494309189535f); c[e] = mine ? __builtin_amdgcn_cosf(rev) : 1.f; sn[e] = mine ? __builtin_amdgcn_sinf(rev) * sgn : 0.f; }
; #pragma unroll
;                     for (int bj = 0; bj < 2; ++bj) { f32x4 v0 = acc[ai][bj][m][0] * r, v1 = acc[ai][bj][m][1] * r; f32x4 p0, p1;
; #pragma unroll
;                         for (int e = 0; e < 4; ++e) { p0[e] = __shfl_xor(v0[e], 16); p1[e] = __shfl_xor(v1[e], 16); }
; #pragma unroll
;                         for (int e = 0; e < 4; ++e) { v0[e] = v0[e] * c[e] + p0[e] * sn[e]; v1[e] = v1[e] * c[4 + e] + p1[e] * sn[4 + e]; }
;                         *(u32x4*)dst(u, row, bj, wc, fq, col0) = pack8(v0, v1); } }
.LBB0_290:
	s_waitcnt vmcnt(7)
	v_cvt_f32_i32_e32 v155, v168
	v_lshl_add_u64 v[116:117], v[118:119], 1, v[116:117]
	global_store_dwordx4 v[116:117], v[112:115], off sc1
	s_and_b64 vcc, exec, s[42:43]
	s_mov_b64 s[28:29], -1
	v_mul_f32_e32 v112, 0.15915494, v155
	v_fract_f32_e32 v112, v112
	v_cos_f32_e32 v114, v112
	v_mul_f32_e32 v113, 0x3e4693af, v155
	v_mul_f32_e32 v113, 0.15915494, v113
	v_sin_f32_e32 v112, v112
	v_fract_f32_e32 v113, v113
	v_cndmask_b32_e64 v116, 1.0, v114, s[0:1]
	v_cos_f32_e32 v114, v113
	v_sin_f32_e32 v113, v113
	v_cndmask_b32_e64 v112, v112, -v112, s[40:41]
	v_cndmask_b32_e64 v120, 0, v112, s[0:1]
	v_cndmask_b32_e64 v117, 1.0, v114, s[0:1]
	v_cndmask_b32_e64 v112, v113, -v113, s[40:41]
	v_cndmask_b32_e64 v118, 0, v112, s[0:1]
	v_mul_f32_e32 v112, 0x3d1a08c8, v155
	v_mul_f32_e32 v112, 0.15915494, v112
	v_fract_f32_e32 v112, v112
	v_cos_f32_e32 v113, v112
	v_sin_f32_e32 v112, v112
	v_mul_f32_e32 v114, 0x3beef74e, v155
	v_mul_f32_e32 v114, 0.15915494, v114
	v_cndmask_b32_e64 v121, 1.0, v113, s[0:1]
	v_mul_f32_e32 v113, 0x3ab95d22, v155
	v_fract_f32_e32 v114, v114
	v_cndmask_b32_e64 v112, v112, -v112, s[40:41]
	v_mul_f32_e32 v113, 0.15915494, v113
	v_cndmask_b32_e64 v122, 0, v112, s[0:1]
	v_sin_f32_e32 v112, v114
	v_fract_f32_e32 v113, v113
	v_cos_f32_e32 v115, v114
	v_cos_f32_e32 v114, v113
	v_sin_f32_e32 v113, v113
	v_cndmask_b32_e64 v112, v112, -v112, s[40:41]
	v_cndmask_b32_e64 v123, 0, v112, s[0:1]
	v_cndmask_b32_e64 v124, 1.0, v114, s[0:1]
	v_cndmask_b32_e64 v112, v113, -v113, s[40:41]
	v_cndmask_b32_e64 v125, 0, v112, s[0:1]
	v_mul_f32_e32 v112, 0x398fc8f8, v155
	v_mul_f32_e32 v112, 0.15915494, v112
	v_fract_f32_e32 v112, v112
	v_cos_f32_e32 v113, v112
	v_sin_f32_e32 v112, v112
	v_mul_f32_e32 v114, 0x385f10c4, v155
	v_mul_f32_e32 v114, 0.15915494, v114
	v_cndmask_b32_e64 v127, 1.0, v113, s[0:1]
	v_mul_f32_e32 v113, 0x372d07a7, v155
	v_mul_f32_e32 v113, 0.15915494, v113
	v_fract_f32_e32 v114, v114
	v_cndmask_b32_e64 v112, v112, -v112, s[40:41]
	v_fract_f32_e32 v113, v113
	v_cndmask_b32_e64 v119, 1.0, v115, s[0:1]
	v_cos_f32_e32 v115, v114
	v_cndmask_b32_e64 v162, 0, v112, s[0:1]
	v_sin_f32_e32 v112, v114
	v_cos_f32_e32 v114, v113
	v_sin_f32_e32 v113, v113
	v_cndmask_b32_e64 v126, 1.0, v115, s[0:1]
	v_cndmask_b32_e64 v112, v112, -v112, s[40:41]
	v_cndmask_b32_e64 v155, 1.0, v114, s[0:1]
	v_mul_f32_e32 v114, v149, v174
	v_pk_mul_f32 v[108:109], v[108:109], v[114:115] op_sel_hi:[1,0]
	v_cndmask_b32_e64 v165, 0, v112, s[0:1]
	v_cndmask_b32_e64 v112, v113, -v113, s[40:41]
	v_pk_mul_f32 v[104:105], v[104:105], v[114:115] op_sel_hi:[1,0]
	ds_bpermute_b32 v113, v145, v108
	v_pk_mul_f32 v[110:111], v[110:111], v[114:115] op_sel_hi:[1,0]
	v_pk_mul_f32 v[106:107], v[106:107], v[114:115] op_sel_hi:[1,0]
	ds_bpermute_b32 v115, v145, v104
	ds_bpermute_b32 v168, v145, v109
	ds_bpermute_b32 v169, v145, v105
	ds_bpermute_b32 v170, v145, v110
	ds_bpermute_b32 v171, v145, v106
	s_waitcnt lgkmcnt(5)
	v_mul_f32_e32 v113, v120, v113
	ds_bpermute_b32 v174, v145, v111
	v_fmac_f32_e32 v113, v108, v116
	s_waitcnt lgkmcnt(5)
	v_mul_f32_e32 v108, v125, v115
	ds_bpermute_b32 v175, v145, v107
	v_fmac_f32_e32 v108, v104, v124
	s_waitcnt lgkmcnt(5)
	v_mul_f32_e32 v104, v118, v168
	v_fmac_f32_e32 v104, v109, v117
	s_waitcnt lgkmcnt(4)
	v_mul_f32_e32 v109, v162, v169
	v_fmac_f32_e32 v109, v105, v127
	s_waitcnt lgkmcnt(3)
	v_mul_f32_e32 v105, v122, v170
	v_fmac_f32_e32 v105, v110, v121
	s_waitcnt lgkmcnt(2)
	v_mul_f32_e32 v110, v165, v171
	v_cndmask_b32_e64 v164, 0, v112, s[0:1]
	v_fmac_f32_e32 v110, v106, v126
	s_waitcnt lgkmcnt(1)
	v_mul_f32_e32 v106, v123, v174
	v_lshlrev_b32_e32 v112, 3, v160
	v_fmac_f32_e32 v106, v111, v119
	s_waitcnt lgkmcnt(0)
	v_mul_f32_e32 v111, v164, v175
	v_and_b32_e32 v112, 0xf8, v112
	v_fmac_f32_e32 v111, v107, v155
	v_cvt_pk_bf16_f32 v104, v113, v104
	v_cvt_pk_bf16_f32 v105, v105, v106
	v_cvt_pk_bf16_f32 v106, v108, v109
	v_cvt_pk_bf16_f32 v107, v110, v111
	s_cbranch_vccnz .LBB0_292
	s_lshl_b32 s28, s19, 5
	s_lshl_b32 s29, s8, 7
	s_or_b32 s28, s29, s28
	s_add_i32 s28, s28, s21
	s_addk_i32 s28, 0xff00
	s_ashr_i32 s29, s28, 31
	s_lshl_b64 s[28:29], s[28:29], 13
	s_add_u32 s28, s14, s28
	s_addc_u32 s29, s15, s29
	v_mov_b32_e32 v113, v195
	v_lshl_add_u64 v[108:109], s[28:29], 0, v[194:195]
	s_mov_b64 s[28:29], 0
	v_mov_b64_e32 v[110:111], v[112:113]

; __device__ __forceinline__ u32x4 pack8(const f32x4 v0, const f32x4 v1) { u32x4 w; w.x = cvt_pk_bf16(v0[0], v0[1]); w.y = cvt_pk_bf16(v0[2], v0[3]); w.z = cvt_pk_bf16(v1[0], v1[1]); w.w = cvt_pk_bf16(v1[2], v1[3]); return w; }
;     __device__ __forceinline__ bf16_t* dst(const Unit& u, int row, int bj, int wc, int fq, int col0) const {
;         if (u.pn < 2 || u.pn >= 6) return O + (size_t)row * ldc + col0 + bj * HALF;
;         const int b = row >> 11, t = row & 2047;
;         if (u.pn < 4) { const int hc = (u.pn - 2) * 4 + bj * 2 + (wc >> 1), chunk = (wc & 1) * 4 + fq;
;             return KC + (size_t)((b * 8 + hc) * 32 + (t >> 6)) * 4096 + chunk * 512 + (t & 63) * 8; }
;         const int h = (u.pn - 4) * 2 + bj, piece = wc * 4 + ((t & 63) >> 4);
;         return VC + (size_t)((b * 4 + h) * 32 + (t >> 6)) * 8192 + piece * 512 + (t & 15) * 32 + fq * 8;
;     __device__ __forceinline__ void operator()(const f32x4 (&acc)[2][2][4][2], const Unit& u, int wr, int wc, int fr, int fq) const {
;     ...
;                     for (int bj = 0; bj < 2; ++bj) { f32x4 v0 = acc[ai][bj][m][0] * r, v1 = acc[ai][bj][m][1] * r; f32x4 p0, p1;
; #pragma unroll
;                         for (int e = 0; e < 4; ++e) { p0[e] = __shfl_xor(v0[e], 16); p1[e] = __shfl_xor(v1[e], 16); }
; #pragma unroll
;                         for (int e = 0; e < 4; ++e) { v0[e] = v0[e] * c[e] + p0[e] * sn[e]; v1[e] = v1[e] * c[4 + e] + p1[e] * sn[4 + e]; }
;                         *(u32x4*)dst(u, row, bj, wc, fq, col0) = pack8(v0, v1); } }
.LBB0_294:
	v_mov_b32_e32 v115, v114
	v_lshl_add_u64 v[108:109], v[110:111], 1, v[108:109]
	global_store_dwordx4 v[108:109], v[104:107], off sc1
	v_pk_mul_f32 v[100:101], v[100:101], v[114:115]
	v_pk_mul_f32 v[96:97], v[96:97], v[114:115]
	v_mov_b32_e32 v104, v114
	v_mov_b32_e32 v105, v114
	v_pk_mul_f32 v[102:103], v[102:103], v[104:105]
	v_pk_mul_f32 v[98:99], v[98:99], v[104:105]
	ds_bpermute_b32 v104, v145, v100
	ds_bpermute_b32 v105, v145, v96
	ds_bpermute_b32 v106, v145, v101
	ds_bpermute_b32 v107, v145, v97
	ds_bpermute_b32 v108, v145, v102
	ds_bpermute_b32 v109, v145, v98
	s_waitcnt lgkmcnt(5)
	v_mul_f32_e32 v104, v120, v104
	ds_bpermute_b32 v110, v145, v103
	v_fmac_f32_e32 v104, v100, v116
	s_waitcnt lgkmcnt(5)
	v_mul_f32_e32 v100, v125, v105
	ds_bpermute_b32 v111, v145, v99
	v_fmac_f32_e32 v100, v96, v124
	s_waitcnt lgkmcnt(5)
	v_mul_f32_e32 v96, v118, v106
	v_fmac_f32_e32 v96, v101, v117
	s_waitcnt lgkmcnt(4)
	v_mul_f32_e32 v101, v162, v107
	v_fmac_f32_e32 v101, v97, v127
	s_waitcnt lgkmcnt(3)
	v_mul_f32_e32 v97, v122, v108
	v_fmac_f32_e32 v97, v102, v121
	s_waitcnt lgkmcnt(2)
	v_mul_f32_e32 v102, v165, v109
	v_fmac_f32_e32 v102, v98, v126
	s_waitcnt lgkmcnt(1)
	v_mul_f32_e32 v98, v123, v110
	v_fmac_f32_e32 v98, v103, v119
	s_waitcnt lgkmcnt(0)
	v_mul_f32_e32 v103, v164, v111
	s_and_b64 vcc, exec, s[42:43]
	s_mov_b64 s[28:29], -1
	v_fmac_f32_e32 v103, v99, v155
	v_cvt_pk_bf16_f32 v96, v104, v96
	v_cvt_pk_bf16_f32 v97, v97, v98
	v_cvt_pk_bf16_f32 v98, v100, v101
	v_cvt_pk_bf16_f32 v99, v102, v103
	s_cbranch_vccnz .LBB0_296
	s_lshl_b32 s28, s19, 5
	s_lshl_b32 s29, s8, 7
	s_or_b32 s28, s29, s28
	s_add_i32 s28, s28, s21
	s_addk_i32 s28, 0xff40
	s_ashr_i32 s29, s28, 31
	s_lshl_b64 s[28:29], s[28:29], 13
	s_add_u32 s28, s14, s28
	s_addc_u32 s29, s15, s29
	v_lshl_add_u64 v[100:101], s[28:29], 0, v[194:195]
	v_mov_b32_e32 v113, v195
	s_mov_b64 s[28:29], 0

; __device__ __forceinline__ u32x4 pack8(const f32x4 v0, const f32x4 v1) { u32x4 w; w.x = cvt_pk_bf16(v0[0], v0[1]); w.y = cvt_pk_bf16(v0[2], v0[3]); w.z = cvt_pk_bf16(v1[0], v1[1]); w.w = cvt_pk_bf16(v1[2], v1[3]); return w; }
;     __device__ __forceinline__ void operator()(const f32x4 (&acc)[2][2][4][2], const Unit& u, int wr, int wc, int fr, int fq) const {
;     ...
;                 for (int m = 0; m < 4; ++m) { const int row = row0 + ai * HALF + m * 16; const float r = rs[ai * 4 + m] * sc; const float pf = (float)ps[ai * 4 + m];
;                     float c[8], sn[8];
; #pragma unroll
;                     for (int e = 0; e < 8; ++e) { const float rev = __builtin_amdgcn_fractf((pf * invf[e]) * 0.15915494309189535f); c[e] = mine ? __builtin_amdgcn_cosf(rev) : 1.f; sn[e] = mine ? __builtin_amdgcn_sinf(rev) * sgn : 0.f; }
; #pragma unroll
;                     for (int bj = 0; bj < 2; ++bj) { f32x4 v0 = acc[ai][bj][m][0] * r, v1 = acc[ai][bj][m][1] * r; f32x4 p0, p1;
; #pragma unroll
;                         for (int e = 0; e < 4; ++e) { p0[e] = __shfl_xor(v0[e], 16); p1[e] = __shfl_xor(v1[e], 16); }
; #pragma unroll
;                         for (int e = 0; e < 4; ++e) { v0[e] = v0[e] * c[e] + p0[e] * sn[e]; v1[e] = v1[e] * c[4 + e] + p1[e] * sn[4 + e]; }
;                         *(u32x4*)dst(u, row, bj, wc, fq, col0) = pack8(v0, v1); } }
.LBB0_298:
	s_waitcnt vmcnt(8)
	v_cvt_f32_i32_e32 v114, v166
	v_lshl_add_u64 v[100:101], v[112:113], 1, v[100:101]
	global_store_dwordx4 v[100:101], v[96:99], off sc1
	s_and_b64 vcc, exec, s[42:43]
	s_mov_b64 s[28:29], -1
	v_mul_f32_e32 v96, 0.15915494, v114
	v_fract_f32_e32 v96, v96
	v_cos_f32_e32 v98, v96
	v_mul_f32_e32 v97, 0x3e4693af, v114
	v_mul_f32_e32 v97, 0.15915494, v97
	v_sin_f32_e32 v96, v96
	v_fract_f32_e32 v97, v97
	v_cndmask_b32_e64 v100, 1.0, v98, s[0:1]
	v_cos_f32_e32 v98, v97
	v_sin_f32_e32 v97, v97
	v_cndmask_b32_e64 v96, v96, -v96, s[40:41]
	v_cndmask_b32_e64 v104, 0, v96, s[0:1]
	v_cndmask_b32_e64 v101, 1.0, v98, s[0:1]
	v_cndmask_b32_e64 v96, v97, -v97, s[40:41]
	v_cndmask_b32_e64 v102, 0, v96, s[0:1]
	v_mul_f32_e32 v96, 0x3d1a08c8, v114
	v_mul_f32_e32 v96, 0.15915494, v96
	v_fract_f32_e32 v96, v96
	v_cos_f32_e32 v97, v96
	v_sin_f32_e32 v96, v96
	v_mul_f32_e32 v98, 0x3beef74e, v114
	v_mul_f32_e32 v98, 0.15915494, v98
	v_cndmask_b32_e64 v105, 1.0, v97, s[0:1]
	v_mul_f32_e32 v97, 0x3ab95d22, v114
	v_fract_f32_e32 v98, v98
	v_cndmask_b32_e64 v96, v96, -v96, s[40:41]
	v_mul_f32_e32 v97, 0.15915494, v97
	v_cndmask_b32_e64 v106, 0, v96, s[0:1]
	v_sin_f32_e32 v96, v98
	v_fract_f32_e32 v97, v97
	v_cos_f32_e32 v99, v98
	v_cos_f32_e32 v98, v97
	v_sin_f32_e32 v97, v97
	v_cndmask_b32_e64 v96, v96, -v96, s[40:41]
	v_cndmask_b32_e64 v107, 0, v96, s[0:1]
	v_cndmask_b32_e64 v108, 1.0, v98, s[0:1]
	v_cndmask_b32_e64 v96, v97, -v97, s[40:41]
	v_cndmask_b32_e64 v109, 0, v96, s[0:1]
	v_mul_f32_e32 v96, 0x398fc8f8, v114
	v_mul_f32_e32 v96, 0.15915494, v96
	v_fract_f32_e32 v96, v96
	v_cos_f32_e32 v97, v96
	v_sin_f32_e32 v96, v96
	v_mul_f32_e32 v98, 0x385f10c4, v114
	v_mul_f32_e32 v98, 0.15915494, v98
	v_cndmask_b32_e64 v111, 1.0, v97, s[0:1]
	v_mul_f32_e32 v97, 0x372d07a7, v114
	v_mul_f32_e32 v97, 0.15915494, v97
	v_fract_f32_e32 v98, v98
	v_cndmask_b32_e64 v96, v96, -v96, s[40:41]
	v_fract_f32_e32 v97, v97
	v_cndmask_b32_e64 v103, 1.0, v99, s[0:1]
	v_cos_f32_e32 v99, v98
	v_cndmask_b32_e64 v113, 0, v96, s[0:1]
	v_sin_f32_e32 v96, v98
	v_cos_f32_e32 v98, v97
	v_sin_f32_e32 v97, v97
	v_cndmask_b32_e64 v110, 1.0, v99, s[0:1]
	v_cndmask_b32_e64 v96, v96, -v96, s[40:41]
	v_cndmask_b32_e64 v112, 1.0, v98, s[0:1]
	v_mul_f32_e32 v98, v149, v167
	v_pk_mul_f32 v[92:93], v[92:93], v[98:99] op_sel_hi:[1,0]
	v_cndmask_b32_e64 v115, 0, v96, s[0:1]
	v_cndmask_b32_e64 v96, v97, -v97, s[40:41]
	v_pk_mul_f32 v[88:89], v[88:89], v[98:99] op_sel_hi:[1,0]
	ds_bpermute_b32 v97, v145, v92
	v_pk_mul_f32 v[94:95], v[94:95], v[98:99] op_sel_hi:[1,0]
	v_pk_mul_f32 v[90:91], v[90:91], v[98:99] op_sel_hi:[1,0]
	ds_bpermute_b32 v99, v145, v88
	ds_bpermute_b32 v116, v145, v93
	ds_bpermute_b32 v117, v145, v89
	ds_bpermute_b32 v118, v145, v94
	ds_bpermute_b32 v119, v145, v90
	s_waitcnt lgkmcnt(5)
	v_mul_f32_e32 v97, v104, v97
	ds_bpermute_b32 v120, v145, v95
	v_fmac_f32_e32 v97, v92, v100
	s_waitcnt lgkmcnt(5)
	v_mul_f32_e32 v92, v109, v99
	ds_bpermute_b32 v121, v145, v91
	v_fmac_f32_e32 v92, v88, v108
	s_waitcnt lgkmcnt(5)
	v_mul_f32_e32 v88, v102, v116
	v_fmac_f32_e32 v88, v93, v101
	s_waitcnt lgkmcnt(4)
	v_mul_f32_e32 v93, v113, v117
	v_fmac_f32_e32 v93, v89, v111
	s_waitcnt lgkmcnt(3)
	v_mul_f32_e32 v89, v106, v118
	v_fmac_f32_e32 v89, v94, v105
	s_waitcnt lgkmcnt(2)
	v_mul_f32_e32 v94, v115, v119
	v_cndmask_b32_e64 v114, 0, v96, s[0:1]
	v_fmac_f32_e32 v94, v90, v110
	s_waitcnt lgkmcnt(1)
	v_mul_f32_e32 v90, v107, v120
	v_lshlrev_b32_e32 v96, 3, v158
	v_fmac_f32_e32 v90, v95, v103
	s_waitcnt lgkmcnt(0)
	v_mul_f32_e32 v95, v114, v121
	v_and_b32_e32 v96, 0x178, v96
	v_fmac_f32_e32 v95, v91, v112
	v_cvt_pk_bf16_f32 v88, v97, v88
	v_cvt_pk_bf16_f32 v89, v89, v90
	v_cvt_pk_bf16_f32 v90, v92, v93
	v_cvt_pk_bf16_f32 v91, v94, v95
	s_cbranch_vccnz .LBB0_300
	s_lshl_b32 s28, s19, 5
	s_lshl_b32 s29, s8, 7
	s_or_b32 s28, s29, s28
	s_add_i32 s28, s28, s21
	s_addk_i32 s28, 0xff00
	s_ashr_i32 s29, s28, 31
	s_lshl_b64 s[28:29], s[28:29], 13
	s_add_u32 s28, s14, s28
	s_addc_u32 s29, s15, s29
	v_mov_b32_e32 v97, v195
	v_lshl_add_u64 v[92:93], s[28:29], 0, v[194:195]
	s_mov_b64 s[28:29], 0
	v_mov_b64_e32 v[94:95], v[96:97]

; __device__ __forceinline__ u32x4 pack8(const f32x4 v0, const f32x4 v1) { u32x4 w; w.x = cvt_pk_bf16(v0[0], v0[1]); w.y = cvt_pk_bf16(v0[2], v0[3]); w.z = cvt_pk_bf16(v1[0], v1[1]); w.w = cvt_pk_bf16(v1[2], v1[3]); return w; }
;     __device__ __forceinline__ bf16_t* dst(const Unit& u, int row, int bj, int wc, int fq, int col0) const {
;         if (u.pn < 2 || u.pn >= 6) return O + (size_t)row * ldc + col0 + bj * HALF;
;         const int b = row >> 11, t = row & 2047;
;         if (u.pn < 4) { const int hc = (u.pn - 2) * 4 + bj * 2 + (wc >> 1), chunk = (wc & 1) * 4 + fq;
;             return KC + (size_t)((b * 8 + hc) * 32 + (t >> 6)) * 4096 + chunk * 512 + (t & 63) * 8; }
;         const int h = (u.pn - 4) * 2 + bj, piece = wc * 4 + ((t & 63) >> 4);
;         return VC + (size_t)((b * 4 + h) * 32 + (t >> 6)) * 8192 + piece * 512 + (t & 15) * 32 + fq * 8;
;     __device__ __forceinline__ void operator()(const f32x4 (&acc)[2][2][4][2], const Unit& u, int wr, int wc, int fr, int fq) const {
;     ...
;                     for (int bj = 0; bj < 2; ++bj) { f32x4 v0 = acc[ai][bj][m][0] * r, v1 = acc[ai][bj][m][1] * r; f32x4 p0, p1;
; #pragma unroll
;                         for (int e = 0; e < 4; ++e) { p0[e] = __shfl_xor(v0[e], 16); p1[e] = __shfl_xor(v1[e], 16); }
; #pragma unroll
;                         for (int e = 0; e < 4; ++e) { v0[e] = v0[e] * c[e] + p0[e] * sn[e]; v1[e] = v1[e] * c[4 + e] + p1[e] * sn[4 + e]; }
;                         *(u32x4*)dst(u, row, bj, wc, fq, col0) = pack8(v0, v1); } }
.LBB0_302:
	v_mov_b32_e32 v99, v98
	v_lshl_add_u64 v[92:93], v[94:95], 1, v[92:93]
	global_store_dwordx4 v[92:93], v[88:91], off sc1
	v_pk_mul_f32 v[84:85], v[84:85], v[98:99]
	v_pk_mul_f32 v[80:81], v[80:81], v[98:99]
	v_mov_b32_e32 v88, v98
	v_mov_b32_e32 v89, v98
	v_pk_mul_f32 v[86:87], v[86:87], v[88:89]
	v_pk_mul_f32 v[82:83], v[82:83], v[88:89]
	ds_bpermute_b32 v88, v145, v84
	ds_bpermute_b32 v89, v145, v80
	ds_bpermute_b32 v90, v145, v85
	ds_bpermute_b32 v91, v145, v81
	ds_bpermute_b32 v92, v145, v86
	ds_bpermute_b32 v93, v145, v82
	s_waitcnt lgkmcnt(5)
	v_mul_f32_e32 v88, v104, v88
	ds_bpermute_b32 v94, v145, v87
	v_fmac_f32_e32 v88, v84, v100
	s_waitcnt lgkmcnt(5)
	v_mul_f32_e32 v84, v109, v89
	ds_bpermute_b32 v95, v145, v83
	v_fmac_f32_e32 v84, v80, v108
	s_waitcnt lgkmcnt(5)
	v_mul_f32_e32 v80, v102, v90
	v_fmac_f32_e32 v80, v85, v101
	s_waitcnt lgkmcnt(4)
	v_mul_f32_e32 v85, v113, v91
	v_fmac_f32_e32 v85, v81, v111
	s_waitcnt lgkmcnt(3)
	v_mul_f32_e32 v81, v106, v92
	v_fmac_f32_e32 v81, v86, v105
	s_waitcnt lgkmcnt(2)
	v_mul_f32_e32 v86, v115, v93
	v_fmac_f32_e32 v86, v82, v110
	s_waitcnt lgkmcnt(1)
	v_mul_f32_e32 v82, v107, v94
	v_fmac_f32_e32 v82, v87, v103
	s_waitcnt lgkmcnt(0)
	v_mul_f32_e32 v87, v114, v95
	s_and_b64 vcc, exec, s[42:43]
	s_mov_b64 s[28:29], -1
	v_fmac_f32_e32 v87, v83, v112
	v_cvt_pk_bf16_f32 v80, v88, v80
	v_cvt_pk_bf16_f32 v81, v81, v82
	v_cvt_pk_bf16_f32 v82, v84, v85
	v_cvt_pk_bf16_f32 v83, v86, v87
	s_cbranch_vccnz .LBB0_304
	s_lshl_b32 s28, s19, 5
	s_lshl_b32 s29, s8, 7
	s_or_b32 s28, s29, s28
	s_add_i32 s28, s28, s21
	s_addk_i32 s28, 0xff40
	s_ashr_i32 s29, s28, 31
	s_lshl_b64 s[28:29], s[28:29], 13
	s_add_u32 s28, s14, s28
	s_addc_u32 s29, s15, s29
	v_lshl_add_u64 v[84:85], s[28:29], 0, v[194:195]
	v_mov_b32_e32 v97, v195
	s_mov_b64 s[28:29], 0

; __device__ __forceinline__ u32x4 pack8(const f32x4 v0, const f32x4 v1) { u32x4 w; w.x = cvt_pk_bf16(v0[0], v0[1]); w.y = cvt_pk_bf16(v0[2], v0[3]); w.z = cvt_pk_bf16(v1[0], v1[1]); w.w = cvt_pk_bf16(v1[2], v1[3]); return w; }
;     __device__ __forceinline__ void operator()(const f32x4 (&acc)[2][2][4][2], const Unit& u, int wr, int wc, int fr, int fq) const {
;     ...
;                 for (int m = 0; m < 4; ++m) { const int row = row0 + ai * HALF + m * 16; const float r = rs[ai * 4 + m] * sc; const float pf = (float)ps[ai * 4 + m];
;                     float c[8], sn[8];
; #pragma unroll
;                     for (int e = 0; e < 8; ++e) { const float rev = __builtin_amdgcn_fractf((pf * invf[e]) * 0.15915494309189535f); c[e] = mine ? __builtin_amdgcn_cosf(rev) : 1.f; sn[e] = mine ? __builtin_amdgcn_sinf(rev) * sgn : 0.f; }
; #pragma unroll
;                     for (int bj = 0; bj < 2; ++bj) { f32x4 v0 = acc[ai][bj][m][0] * r, v1 = acc[ai][bj][m][1] * r; f32x4 p0, p1;
; #pragma unroll
;                         for (int e = 0; e < 4; ++e) { p0[e] = __shfl_xor(v0[e], 16); p1[e] = __shfl_xor(v1[e], 16); }
; #pragma unroll
;                         for (int e = 0; e < 4; ++e) { v0[e] = v0[e] * c[e] + p0[e] * sn[e]; v1[e] = v1[e] * c[4 + e] + p1[e] * sn[4 + e]; }
;                         *(u32x4*)dst(u, row, bj, wc, fq, col0) = pack8(v0, v1); } }
.LBB0_306:
	s_waitcnt vmcnt(9)
	v_cvt_f32_i32_e32 v98, v163
	v_lshl_add_u64 v[84:85], v[96:97], 1, v[84:85]
	global_store_dwordx4 v[84:85], v[80:83], off sc1
	s_and_b64 vcc, exec, s[42:43]
	s_mov_b64 s[28:29], -1
	v_mul_f32_e32 v80, 0.15915494, v98
	v_fract_f32_e32 v80, v80
	v_cos_f32_e32 v82, v80
	v_mul_f32_e32 v81, 0x3e4693af, v98
	v_mul_f32_e32 v81, 0.15915494, v81
	v_sin_f32_e32 v80, v80
	v_fract_f32_e32 v81, v81
	v_cndmask_b32_e64 v84, 1.0, v82, s[0:1]
	v_cos_f32_e32 v82, v81
	v_sin_f32_e32 v81, v81
	v_cndmask_b32_e64 v80, v80, -v80, s[40:41]
	v_cndmask_b32_e64 v88, 0, v80, s[0:1]
	v_cndmask_b32_e64 v85, 1.0, v82, s[0:1]
	v_cndmask_b32_e64 v80, v81, -v81, s[40:41]
	v_cndmask_b32_e64 v86, 0, v80, s[0:1]
	v_mul_f32_e32 v80, 0x3d1a08c8, v98
	v_mul_f32_e32 v80, 0.15915494, v80
	v_fract_f32_e32 v80, v80
	v_cos_f32_e32 v81, v80
	v_sin_f32_e32 v80, v80
	v_mul_f32_e32 v82, 0x3beef74e, v98
	v_mul_f32_e32 v82, 0.15915494, v82
	v_cndmask_b32_e64 v89, 1.0, v81, s[0:1]
	v_mul_f32_e32 v81, 0x3ab95d22, v98
	v_fract_f32_e32 v82, v82
	v_cndmask_b32_e64 v80, v80, -v80, s[40:41]
	v_mul_f32_e32 v81, 0.15915494, v81
	v_cndmask_b32_e64 v90, 0, v80, s[0:1]
	v_sin_f32_e32 v80, v82
	v_fract_f32_e32 v81, v81
	v_cos_f32_e32 v83, v82
	v_cos_f32_e32 v82, v81
	v_sin_f32_e32 v81, v81
	v_cndmask_b32_e64 v80, v80, -v80, s[40:41]
	v_cndmask_b32_e64 v91, 0, v80, s[0:1]
	v_cndmask_b32_e64 v92, 1.0, v82, s[0:1]
	v_cndmask_b32_e64 v80, v81, -v81, s[40:41]
	v_cndmask_b32_e64 v93, 0, v80, s[0:1]
	v_mul_f32_e32 v80, 0x398fc8f8, v98
	v_mul_f32_e32 v80, 0.15915494, v80
	v_fract_f32_e32 v80, v80
	v_cos_f32_e32 v81, v80
	v_sin_f32_e32 v80, v80
	v_mul_f32_e32 v82, 0x385f10c4, v98
	v_mul_f32_e32 v82, 0.15915494, v82
	v_cndmask_b32_e64 v95, 1.0, v81, s[0:1]
	v_mul_f32_e32 v81, 0x372d07a7, v98
	v_mul_f32_e32 v81, 0.15915494, v81
	v_fract_f32_e32 v82, v82
	v_cndmask_b32_e64 v80, v80, -v80, s[40:41]
	v_fract_f32_e32 v81, v81
	v_cndmask_b32_e64 v87, 1.0, v83, s[0:1]
	v_cos_f32_e32 v83, v82
	v_cndmask_b32_e64 v97, 0, v80, s[0:1]
	v_sin_f32_e32 v80, v82
	v_cos_f32_e32 v82, v81
	v_sin_f32_e32 v81, v81
	v_cndmask_b32_e64 v94, 1.0, v83, s[0:1]
	v_cndmask_b32_e64 v80, v80, -v80, s[40:41]
	v_cndmask_b32_e64 v96, 1.0, v82, s[0:1]
	v_mul_f32_e32 v82, v149, v161
	v_pk_mul_f32 v[76:77], v[76:77], v[82:83] op_sel_hi:[1,0]
	v_cndmask_b32_e64 v99, 0, v80, s[0:1]
	v_cndmask_b32_e64 v80, v81, -v81, s[40:41]
	v_pk_mul_f32 v[72:73], v[72:73], v[82:83] op_sel_hi:[1,0]
	ds_bpermute_b32 v81, v145, v76
	v_pk_mul_f32 v[78:79], v[78:79], v[82:83] op_sel_hi:[1,0]
	v_pk_mul_f32 v[74:75], v[74:75], v[82:83] op_sel_hi:[1,0]
	ds_bpermute_b32 v83, v145, v72
	ds_bpermute_b32 v100, v145, v77
	ds_bpermute_b32 v101, v145, v73
	ds_bpermute_b32 v102, v145, v78
	ds_bpermute_b32 v103, v145, v74
	s_waitcnt lgkmcnt(5)
	v_mul_f32_e32 v81, v88, v81
	ds_bpermute_b32 v104, v145, v79
	v_fmac_f32_e32 v81, v76, v84
	s_waitcnt lgkmcnt(5)
	v_mul_f32_e32 v76, v93, v83
	ds_bpermute_b32 v105, v145, v75
	v_fmac_f32_e32 v76, v72, v92
	s_waitcnt lgkmcnt(5)
	v_mul_f32_e32 v72, v86, v100
	v_fmac_f32_e32 v72, v77, v85
	s_waitcnt lgkmcnt(4)
	v_mul_f32_e32 v77, v97, v101
	v_fmac_f32_e32 v77, v73, v95
	s_waitcnt lgkmcnt(3)
	v_mul_f32_e32 v73, v90, v102
	v_fmac_f32_e32 v73, v78, v89
	s_waitcnt lgkmcnt(2)
	v_mul_f32_e32 v78, v99, v103
	v_cndmask_b32_e64 v98, 0, v80, s[0:1]
	v_fmac_f32_e32 v78, v74, v94
	s_waitcnt lgkmcnt(1)
	v_mul_f32_e32 v74, v91, v104
	v_lshlrev_b32_e32 v80, 3, v156
	v_fmac_f32_e32 v74, v79, v87
	s_waitcnt lgkmcnt(0)
	v_mul_f32_e32 v79, v98, v105
	v_and_b32_e32 v80, 0x1f8, v80
	v_fmac_f32_e32 v79, v75, v96
	v_cvt_pk_bf16_f32 v72, v81, v72
	v_cvt_pk_bf16_f32 v73, v73, v74
	v_cvt_pk_bf16_f32 v74, v76, v77
	v_cvt_pk_bf16_f32 v75, v78, v79
	s_cbranch_vccnz .LBB0_308
	s_lshl_b32 s28, s19, 5
	s_lshl_b32 s29, s8, 7
	s_or_b32 s28, s29, s28
	s_add_i32 s28, s28, s21
	s_addk_i32 s28, 0xff00
	s_ashr_i32 s29, s28, 31
	s_lshl_b64 s[28:29], s[28:29], 13
	s_add_u32 s28, s14, s28
	s_addc_u32 s29, s15, s29
	v_mov_b32_e32 v81, v195
	v_lshl_add_u64 v[76:77], s[28:29], 0, v[194:195]
	s_mov_b64 s[28:29], 0
	v_mov_b64_e32 v[78:79], v[80:81]

; __device__ __forceinline__ u32x4 pack8(const f32x4 v0, const f32x4 v1) { u32x4 w; w.x = cvt_pk_bf16(v0[0], v0[1]); w.y = cvt_pk_bf16(v0[2], v0[3]); w.z = cvt_pk_bf16(v1[0], v1[1]); w.w = cvt_pk_bf16(v1[2], v1[3]); return w; }
;     __device__ __forceinline__ bf16_t* dst(const Unit& u, int row, int bj, int wc, int fq, int col0) const {
;         if (u.pn < 2 || u.pn >= 6) return O + (size_t)row * ldc + col0 + bj * HALF;
;         const int b = row >> 11, t = row & 2047;
;         if (u.pn < 4) { const int hc = (u.pn - 2) * 4 + bj * 2 + (wc >> 1), chunk = (wc & 1) * 4 + fq;
;             return KC + (size_t)((b * 8 + hc) * 32 + (t >> 6)) * 4096 + chunk * 512 + (t & 63) * 8; }
;         const int h = (u.pn - 4) * 2 + bj, piece = wc * 4 + ((t & 63) >> 4);
;         return VC + (size_t)((b * 4 + h) * 32 + (t >> 6)) * 8192 + piece * 512 + (t & 15) * 32 + fq * 8;
;     __device__ __forceinline__ void operator()(const f32x4 (&acc)[2][2][4][2], const Unit& u, int wr, int wc, int fr, int fq) const {
;     ...
;                     for (int bj = 0; bj < 2; ++bj) { f32x4 v0 = acc[ai][bj][m][0] * r, v1 = acc[ai][bj][m][1] * r; f32x4 p0, p1;
; #pragma unroll
;                         for (int e = 0; e < 4; ++e) { p0[e] = __shfl_xor(v0[e], 16); p1[e] = __shfl_xor(v1[e], 16); }
; #pragma unroll
;                         for (int e = 0; e < 4; ++e) { v0[e] = v0[e] * c[e] + p0[e] * sn[e]; v1[e] = v1[e] * c[4 + e] + p1[e] * sn[4 + e]; }
;                         *(u32x4*)dst(u, row, bj, wc, fq, col0) = pack8(v0, v1); } }
.LBB0_310:
	v_mov_b32_e32 v83, v82
	v_lshl_add_u64 v[76:77], v[78:79], 1, v[76:77]
	global_store_dwordx4 v[76:77], v[72:75], off sc1
	v_pk_mul_f32 v[68:69], v[68:69], v[82:83]
	v_pk_mul_f32 v[64:65], v[64:65], v[82:83]
	v_mov_b32_e32 v72, v82
	v_mov_b32_e32 v73, v82
	v_pk_mul_f32 v[70:71], v[70:71], v[72:73]
	v_pk_mul_f32 v[66:67], v[66:67], v[72:73]
	ds_bpermute_b32 v72, v145, v68
	ds_bpermute_b32 v73, v145, v64
	ds_bpermute_b32 v74, v145, v69
	ds_bpermute_b32 v75, v145, v65
	ds_bpermute_b32 v76, v145, v70
	ds_bpermute_b32 v77, v145, v66
	s_waitcnt lgkmcnt(5)
	v_mul_f32_e32 v72, v88, v72
	ds_bpermute_b32 v78, v145, v71
	v_fmac_f32_e32 v72, v68, v84
	s_waitcnt lgkmcnt(5)
	v_mul_f32_e32 v68, v93, v73
	ds_bpermute_b32 v79, v145, v67
	v_fmac_f32_e32 v68, v64, v92
	s_waitcnt lgkmcnt(5)
	v_mul_f32_e32 v64, v86, v74
	v_fmac_f32_e32 v64, v69, v85
	s_waitcnt lgkmcnt(4)
	v_mul_f32_e32 v69, v97, v75
	v_fmac_f32_e32 v69, v65, v95
	s_waitcnt lgkmcnt(3)
	v_mul_f32_e32 v65, v90, v76
	v_fmac_f32_e32 v65, v70, v89
	s_waitcnt lgkmcnt(2)
	v_mul_f32_e32 v70, v99, v77
	v_fmac_f32_e32 v70, v66, v94
	s_waitcnt lgkmcnt(1)
	v_mul_f32_e32 v66, v91, v78
	v_fmac_f32_e32 v66, v71, v87
	s_waitcnt lgkmcnt(0)
	v_mul_f32_e32 v71, v98, v79
	s_and_b64 vcc, exec, s[42:43]
	s_mov_b64 s[28:29], -1
	v_fmac_f32_e32 v71, v67, v96
	v_cvt_pk_bf16_f32 v64, v72, v64
	v_cvt_pk_bf16_f32 v65, v65, v66
	v_cvt_pk_bf16_f32 v66, v68, v69
	v_cvt_pk_bf16_f32 v67, v70, v71
	s_cbranch_vccnz .LBB0_312
	s_lshl_b32 s28, s19, 5
	s_lshl_b32 s29, s8, 7
	s_or_b32 s28, s29, s28
	s_add_i32 s21, s28, s21
	s_add_i32 s28, s21, 0xffffff40
	s_ashr_i32 s29, s28, 31
	s_lshl_b64 s[28:29], s[28:29], 13
	s_add_u32 s28, s14, s28
	s_addc_u32 s29, s15, s29
	v_lshl_add_u64 v[68:69], s[28:29], 0, v[194:195]
	v_mov_b32_e32 v81, v195
	s_mov_b64 s[28:29], 0

; __device__ __forceinline__ u32x4 pack8(const f32x4 v0, const f32x4 v1) { u32x4 w; w.x = cvt_pk_bf16(v0[0], v0[1]); w.y = cvt_pk_bf16(v0[2], v0[3]); w.z = cvt_pk_bf16(v1[0], v1[1]); w.w = cvt_pk_bf16(v1[2], v1[3]); return w; }
;     __device__ __forceinline__ void operator()(const f32x4 (&acc)[2][2][4][2], const Unit& u, int wr, int wc, int fr, int fq) const {
;     ...
;                 for (int m = 0; m < 4; ++m) { const int row = row0 + ai * HALF + m * 16; const float r = rs[ai * 4 + m] * sc; const float pf = (float)ps[ai * 4 + m];
;                     float c[8], sn[8];
; #pragma unroll
;                     for (int e = 0; e < 8; ++e) { const float rev = __builtin_amdgcn_fractf((pf * invf[e]) * 0.15915494309189535f); c[e] = mine ? __builtin_amdgcn_cosf(rev) : 1.f; sn[e] = mine ? __builtin_amdgcn_sinf(rev) * sgn : 0.f; }
; #pragma unroll
;                     for (int bj = 0; bj < 2; ++bj) { f32x4 v0 = acc[ai][bj][m][0] * r, v1 = acc[ai][bj][m][1] * r; f32x4 p0, p1;
; #pragma unroll
;                         for (int e = 0; e < 4; ++e) { p0[e] = __shfl_xor(v0[e], 16); p1[e] = __shfl_xor(v1[e], 16); }
; #pragma unroll
;                         for (int e = 0; e < 4; ++e) { v0[e] = v0[e] * c[e] + p0[e] * sn[e]; v1[e] = v1[e] * c[4 + e] + p1[e] * sn[4 + e]; }
;                         *(u32x4*)dst(u, row, bj, wc, fq, col0) = pack8(v0, v1); } }
.LBB0_314:
	s_waitcnt vmcnt(10)
	v_cvt_f32_i32_e32 v75, v131
	v_lshl_add_u64 v[68:69], v[80:81], 1, v[68:69]
	global_store_dwordx4 v[68:69], v[64:67], off sc1
	v_ashrrev_i32_e32 v70, 3, v152
	v_mul_f32_e32 v68, 0x3e4693af, v75
	v_mul_f32_e32 v64, 0.15915494, v75
	v_fract_f32_e32 v64, v64
	v_cos_f32_e32 v65, v64
	v_sin_f32_e32 v64, v64
	v_and_b32_e32 v66, 0xffffff00, v70
	v_mul_f32_e32 v70, 0x3beef74e, v75
	v_cndmask_b32_e64 v67, 1.0, v65, s[0:1]
	v_mul_f32_e32 v65, 0.15915494, v68
	v_fract_f32_e32 v65, v65
	v_cos_f32_e32 v68, v65
	v_sin_f32_e32 v65, v65
	v_cndmask_b32_e64 v64, v64, -v64, s[40:41]
	v_cndmask_b32_e64 v71, 0, v64, s[0:1]
	v_mul_f32_e32 v70, 0.15915494, v70
	v_cndmask_b32_e64 v64, v65, -v65, s[40:41]
	v_cndmask_b32_e64 v69, 0, v64, s[0:1]
	v_mul_f32_e32 v64, 0x3d1a08c8, v75
	v_mul_f32_e32 v64, 0.15915494, v64
	v_fract_f32_e32 v64, v64
	v_cos_f32_e32 v65, v64
	v_sin_f32_e32 v64, v64
	v_fract_f32_e32 v74, v70
	v_cos_f32_e32 v70, v74
	v_cndmask_b32_e64 v72, 1.0, v65, s[0:1]
	v_mul_f32_e32 v65, 0x3ab95d22, v75
	v_cndmask_b32_e64 v64, v64, -v64, s[40:41]
	v_mul_f32_e32 v65, 0.15915494, v65
	v_cndmask_b32_e64 v73, 0, v64, s[0:1]
	v_sin_f32_e32 v64, v74
	v_fract_f32_e32 v65, v65
	v_cos_f32_e32 v76, v65
	v_sin_f32_e32 v65, v65
	v_cndmask_b32_e64 v64, v64, -v64, s[40:41]
	v_cndmask_b32_e64 v74, 0, v64, s[0:1]
	v_mul_f32_e32 v78, 0x385f10c4, v75
	v_cndmask_b32_e64 v64, v65, -v65, s[40:41]
	v_cndmask_b32_e64 v77, 0, v64, s[0:1]
	v_mul_f32_e32 v64, 0x398fc8f8, v75
	v_mul_f32_e32 v64, 0.15915494, v64
	v_fract_f32_e32 v64, v64
	v_cos_f32_e32 v65, v64
	v_sin_f32_e32 v64, v64
	v_mul_f32_e32 v78, 0.15915494, v78
	v_fract_f32_e32 v80, v78
	v_cndmask_b32_e64 v79, 1.0, v65, s[0:1]
	v_mul_f32_e32 v65, 0x372d07a7, v75
	v_cndmask_b32_e64 v64, v64, -v64, s[40:41]
	v_mul_f32_e32 v65, 0.15915494, v65
	v_cndmask_b32_e64 v81, 0, v64, s[0:1]
	v_sin_f32_e32 v64, v80
	v_fract_f32_e32 v65, v65
	v_cos_f32_e32 v75, v65
	v_sin_f32_e32 v65, v65
	v_cndmask_b32_e64 v64, v64, -v64, s[40:41]
	v_cndmask_b32_e64 v83, 0, v64, s[0:1]
	v_cos_f32_e32 v78, v80
	v_cndmask_b32_e64 v64, v65, -v65, s[40:41]
	v_cndmask_b32_e64 v82, 0, v64, s[0:1]
	v_mul_f32_e32 v64, v149, v159
	v_lshrrev_b32_e32 v65, 6, v152
	v_pk_mul_f32 v[60:61], v[60:61], v[64:65] op_sel_hi:[1,0]
	v_cndmask_b32_e64 v80, 1.0, v75, s[0:1]
	v_and_or_b32 v75, v65, 31, v66
	v_pk_mul_f32 v[62:63], v[62:63], v[64:65] op_sel_hi:[1,0]
	v_pk_mul_f32 v[58:59], v[58:59], v[64:65] op_sel_hi:[1,0]
	v_pk_mul_f32 v[56:57], v[56:57], v[64:65] op_sel_hi:[1,0]
	ds_bpermute_b32 v65, v145, v60
	ds_bpermute_b32 v84, v145, v56
	ds_bpermute_b32 v85, v145, v61
	ds_bpermute_b32 v86, v145, v57
	ds_bpermute_b32 v87, v145, v62
	ds_bpermute_b32 v88, v145, v58
	s_waitcnt lgkmcnt(5)
	v_mul_f32_e32 v65, v71, v65
	v_cndmask_b32_e64 v76, 1.0, v76, s[0:1]
	ds_bpermute_b32 v89, v145, v63
	v_fmac_f32_e32 v65, v60, v67
	s_waitcnt lgkmcnt(5)
	v_mul_f32_e32 v60, v77, v84
	v_cndmask_b32_e64 v68, 1.0, v68, s[0:1]
	ds_bpermute_b32 v90, v145, v59
	v_fmac_f32_e32 v60, v56, v76
	s_waitcnt lgkmcnt(5)
	v_mul_f32_e32 v56, v69, v85
	v_fmac_f32_e32 v56, v61, v68
	s_waitcnt lgkmcnt(4)
	v_mul_f32_e32 v61, v81, v86
	v_fmac_f32_e32 v61, v57, v79
	s_waitcnt lgkmcnt(3)
	v_mul_f32_e32 v57, v73, v87
	v_cndmask_b32_e64 v78, 1.0, v78, s[0:1]
	v_fmac_f32_e32 v57, v62, v72
	s_waitcnt lgkmcnt(2)
	v_mul_f32_e32 v62, v83, v88
	v_cndmask_b32_e64 v70, 1.0, v70, s[0:1]
	v_fmac_f32_e32 v62, v58, v78
	s_waitcnt lgkmcnt(1)
	v_mul_f32_e32 v58, v74, v89
	v_fmac_f32_e32 v58, v63, v70
	s_waitcnt lgkmcnt(0)
	v_mul_f32_e32 v63, v82, v90
	v_fmac_f32_e32 v63, v59, v80
	s_and_b64 vcc, exec, s[42:43]
	s_mov_b64 s[28:29], -1
	v_cvt_pk_bf16_f32 v56, v65, v56
	v_cvt_pk_bf16_f32 v57, v57, v58
	v_cvt_pk_bf16_f32 v58, v60, v61
	v_cvt_pk_bf16_f32 v59, v62, v63
	s_cbranch_vccnz .LBB0_316
	s_lshl_b32 s21, s19, 5
	s_lshl_b32 s28, s8, 7
	s_or_b32 s21, s28, s21
	s_addk_i32 s21, 0xff00
	v_add_u32_e32 v60, s21, v75
	v_ashrrev_i32_e32 v61, 31, v60
	v_lshlrev_b64 v[60:61], 13, v[60:61]
	v_lshl_add_u64 v[60:61], s[14:15], 0, v[60:61]
	v_mov_b32_e32 v155, v195
	v_lshl_add_u64 v[60:61], v[60:61], 0, v[194:195]
	s_mov_b64 s[28:29], 0
	v_mov_b64_e32 v[62:63], v[154:155]

; __device__ __forceinline__ u32x4 pack8(const f32x4 v0, const f32x4 v1) { u32x4 w; w.x = cvt_pk_bf16(v0[0], v0[1]); w.y = cvt_pk_bf16(v0[2], v0[3]); w.z = cvt_pk_bf16(v1[0], v1[1]); w.w = cvt_pk_bf16(v1[2], v1[3]); return w; }
;     __device__ __forceinline__ bf16_t* dst(const Unit& u, int row, int bj, int wc, int fq, int col0) const {
;         if (u.pn < 2 || u.pn >= 6) return O + (size_t)row * ldc + col0 + bj * HALF;
;         const int b = row >> 11, t = row & 2047;
;         if (u.pn < 4) { const int hc = (u.pn - 2) * 4 + bj * 2 + (wc >> 1), chunk = (wc & 1) * 4 + fq;
;             return KC + (size_t)((b * 8 + hc) * 32 + (t >> 6)) * 4096 + chunk * 512 + (t & 63) * 8; }
;         const int h = (u.pn - 4) * 2 + bj, piece = wc * 4 + ((t & 63) >> 4);
;         return VC + (size_t)((b * 4 + h) * 32 + (t >> 6)) * 8192 + piece * 512 + (t & 15) * 32 + fq * 8;
;     __device__ __forceinline__ void operator()(const f32x4 (&acc)[2][2][4][2], const Unit& u, int wr, int wc, int fr, int fq) const {
;     ...
;                     for (int bj = 0; bj < 2; ++bj) { f32x4 v0 = acc[ai][bj][m][0] * r, v1 = acc[ai][bj][m][1] * r; f32x4 p0, p1;
; #pragma unroll
;                         for (int e = 0; e < 4; ++e) { p0[e] = __shfl_xor(v0[e], 16); p1[e] = __shfl_xor(v1[e], 16); }
; #pragma unroll
;                         for (int e = 0; e < 4; ++e) { v0[e] = v0[e] * c[e] + p0[e] * sn[e]; v1[e] = v1[e] * c[4 + e] + p1[e] * sn[4 + e]; }
;                         *(u32x4*)dst(u, row, bj, wc, fq, col0) = pack8(v0, v1); } }
.LBB0_318:
	v_mov_b32_e32 v65, v64
	v_lshl_add_u64 v[60:61], v[62:63], 1, v[60:61]
	global_store_dwordx4 v[60:61], v[56:59], off sc1
	v_pk_mul_f32 v[52:53], v[52:53], v[64:65]
	v_pk_mul_f32 v[48:49], v[48:49], v[64:65]
	v_mov_b32_e32 v56, v64
	v_mov_b32_e32 v57, v64
	v_pk_mul_f32 v[54:55], v[54:55], v[56:57]
	v_pk_mul_f32 v[50:51], v[50:51], v[56:57]
	ds_bpermute_b32 v56, v145, v52
	ds_bpermute_b32 v57, v145, v48
	ds_bpermute_b32 v58, v145, v53
	ds_bpermute_b32 v59, v145, v49
	ds_bpermute_b32 v60, v145, v54
	ds_bpermute_b32 v61, v145, v50
	s_waitcnt lgkmcnt(5)
	v_mul_f32_e32 v56, v71, v56
	ds_bpermute_b32 v62, v145, v55
	v_fmac_f32_e32 v56, v52, v67
	s_waitcnt lgkmcnt(5)
	v_mul_f32_e32 v52, v77, v57
	ds_bpermute_b32 v63, v145, v51
	v_fmac_f32_e32 v52, v48, v76
	s_waitcnt lgkmcnt(5)
	v_mul_f32_e32 v48, v69, v58
	v_fmac_f32_e32 v48, v53, v68
	s_waitcnt lgkmcnt(4)
	v_mul_f32_e32 v53, v81, v59
	v_fmac_f32_e32 v53, v49, v79
	s_waitcnt lgkmcnt(3)
	v_mul_f32_e32 v49, v73, v60
	v_fmac_f32_e32 v49, v54, v72
	s_waitcnt lgkmcnt(2)
	v_mul_f32_e32 v54, v83, v61
	v_fmac_f32_e32 v54, v50, v78
	s_waitcnt lgkmcnt(1)
	v_mul_f32_e32 v50, v74, v62
	v_fmac_f32_e32 v50, v55, v70
	s_waitcnt lgkmcnt(0)
	v_mul_f32_e32 v55, v82, v63
	s_and_b64 vcc, exec, s[42:43]
	s_mov_b64 s[28:29], -1
	v_fmac_f32_e32 v55, v51, v80
	v_cvt_pk_bf16_f32 v48, v56, v48
	v_cvt_pk_bf16_f32 v49, v49, v50
	v_cvt_pk_bf16_f32 v50, v52, v53
	v_cvt_pk_bf16_f32 v51, v54, v55
	s_cbranch_vccnz .LBB0_320
	s_lshl_b32 s21, s19, 5
	s_lshl_b32 s28, s8, 7
	s_or_b32 s21, s28, s21
	s_addk_i32 s21, 0xff40
	v_add_u32_e32 v52, s21, v75
	v_ashrrev_i32_e32 v53, 31, v52
	v_lshlrev_b64 v[52:53], 13, v[52:53]
	v_lshl_add_u64 v[52:53], s[14:15], 0, v[52:53]
	v_lshl_add_u64 v[52:53], v[52:53], 0, v[194:195]
	v_mov_b32_e32 v155, v195
	s_mov_b64 s[28:29], 0

; __device__ __forceinline__ u32x4 pack8(const f32x4 v0, const f32x4 v1) { u32x4 w; w.x = cvt_pk_bf16(v0[0], v0[1]); w.y = cvt_pk_bf16(v0[2], v0[3]); w.z = cvt_pk_bf16(v1[0], v1[1]); w.w = cvt_pk_bf16(v1[2], v1[3]); return w; }
;     __device__ __forceinline__ void operator()(const f32x4 (&acc)[2][2][4][2], const Unit& u, int wr, int wc, int fr, int fq) const {
;     ...
;                 for (int m = 0; m < 4; ++m) { const int row = row0 + ai * HALF + m * 16; const float r = rs[ai * 4 + m] * sc; const float pf = (float)ps[ai * 4 + m];
;                     float c[8], sn[8];
; #pragma unroll
;                     for (int e = 0; e < 8; ++e) { const float rev = __builtin_amdgcn_fractf((pf * invf[e]) * 0.15915494309189535f); c[e] = mine ? __builtin_amdgcn_cosf(rev) : 1.f; sn[e] = mine ? __builtin_amdgcn_sinf(rev) * sgn : 0.f; }
; #pragma unroll
;                     for (int bj = 0; bj < 2; ++bj) { f32x4 v0 = acc[ai][bj][m][0] * r, v1 = acc[ai][bj][m][1] * r; f32x4 p0, p1;
; #pragma unroll
;                         for (int e = 0; e < 4; ++e) { p0[e] = __shfl_xor(v0[e], 16); p1[e] = __shfl_xor(v1[e], 16); }
; #pragma unroll
;                         for (int e = 0; e < 4; ++e) { v0[e] = v0[e] * c[e] + p0[e] * sn[e]; v1[e] = v1[e] * c[4 + e] + p1[e] * sn[4 + e]; }
;                         *(u32x4*)dst(u, row, bj, wc, fq, col0) = pack8(v0, v1); } }
.LBB0_322:
	s_waitcnt vmcnt(11)
	v_cvt_f32_i32_e32 v60, v130
	v_lshl_add_u64 v[52:53], v[154:155], 1, v[52:53]
	global_store_dwordx4 v[52:53], v[48:51], off sc1
	s_and_b64 vcc, exec, s[42:43]
	s_mov_b64 s[28:29], -1
	v_mul_f32_e32 v48, 0.15915494, v60
	v_fract_f32_e32 v48, v48
	v_cos_f32_e32 v50, v48
	v_mul_f32_e32 v49, 0x3e4693af, v60
	v_mul_f32_e32 v49, 0.15915494, v49
	v_sin_f32_e32 v48, v48
	v_fract_f32_e32 v49, v49
	v_cndmask_b32_e64 v52, 1.0, v50, s[0:1]
	v_cos_f32_e32 v50, v49
	v_sin_f32_e32 v49, v49
	v_cndmask_b32_e64 v48, v48, -v48, s[40:41]
	v_cndmask_b32_e64 v56, 0, v48, s[0:1]
	v_cndmask_b32_e64 v53, 1.0, v50, s[0:1]
	v_cndmask_b32_e64 v48, v49, -v49, s[40:41]
	v_cndmask_b32_e64 v54, 0, v48, s[0:1]
	v_mul_f32_e32 v48, 0x3d1a08c8, v60
	v_mul_f32_e32 v48, 0.15915494, v48
	v_fract_f32_e32 v48, v48
	v_cos_f32_e32 v49, v48
	v_sin_f32_e32 v48, v48
	v_mul_f32_e32 v50, 0x3beef74e, v60
	v_mul_f32_e32 v50, 0.15915494, v50
	v_cndmask_b32_e64 v57, 1.0, v49, s[0:1]
	v_mul_f32_e32 v49, 0x3ab95d22, v60
	v_fract_f32_e32 v50, v50
	v_cndmask_b32_e64 v48, v48, -v48, s[40:41]
	v_mul_f32_e32 v49, 0.15915494, v49
	v_cndmask_b32_e64 v58, 0, v48, s[0:1]
	v_sin_f32_e32 v48, v50
	v_fract_f32_e32 v49, v49
	v_cos_f32_e32 v51, v50
	v_cos_f32_e32 v50, v49
	v_sin_f32_e32 v49, v49
	v_cndmask_b32_e64 v48, v48, -v48, s[40:41]
	v_cndmask_b32_e64 v59, 0, v48, s[0:1]
	v_cndmask_b32_e64 v61, 1.0, v50, s[0:1]
	v_cndmask_b32_e64 v48, v49, -v49, s[40:41]
	v_cndmask_b32_e64 v62, 0, v48, s[0:1]
	v_mul_f32_e32 v48, 0x398fc8f8, v60
	v_mul_f32_e32 v48, 0.15915494, v48
	v_fract_f32_e32 v48, v48
	v_cos_f32_e32 v49, v48
	v_sin_f32_e32 v48, v48
	v_mul_f32_e32 v50, 0x385f10c4, v60
	v_mul_f32_e32 v50, 0.15915494, v50
	v_cndmask_b32_e64 v64, 1.0, v49, s[0:1]
	v_mul_f32_e32 v49, 0x372d07a7, v60
	v_mul_f32_e32 v49, 0.15915494, v49
	v_fract_f32_e32 v50, v50
	v_cndmask_b32_e64 v48, v48, -v48, s[40:41]
	v_fract_f32_e32 v49, v49
	v_cndmask_b32_e64 v55, 1.0, v51, s[0:1]
	v_cos_f32_e32 v51, v50
	v_cndmask_b32_e64 v67, 0, v48, s[0:1]
	v_sin_f32_e32 v48, v50
	v_cos_f32_e32 v50, v49
	v_sin_f32_e32 v49, v49
	v_cndmask_b32_e64 v63, 1.0, v51, s[0:1]
	v_cndmask_b32_e64 v48, v48, -v48, s[40:41]
	v_cndmask_b32_e64 v65, 1.0, v50, s[0:1]
	v_mul_f32_e32 v50, v149, v157
	v_pk_mul_f32 v[44:45], v[44:45], v[50:51] op_sel_hi:[1,0]
	v_cndmask_b32_e64 v69, 0, v48, s[0:1]
	v_cndmask_b32_e64 v48, v49, -v49, s[40:41]
	v_pk_mul_f32 v[40:41], v[40:41], v[50:51] op_sel_hi:[1,0]
	ds_bpermute_b32 v49, v145, v44
	v_pk_mul_f32 v[46:47], v[46:47], v[50:51] op_sel_hi:[1,0]
	v_pk_mul_f32 v[42:43], v[42:43], v[50:51] op_sel_hi:[1,0]
	ds_bpermute_b32 v51, v145, v40
	ds_bpermute_b32 v70, v145, v45
	ds_bpermute_b32 v71, v145, v41
	ds_bpermute_b32 v72, v145, v46
	ds_bpermute_b32 v73, v145, v42
	s_waitcnt lgkmcnt(5)
	v_mul_f32_e32 v49, v56, v49
	ds_bpermute_b32 v74, v145, v47
	v_fmac_f32_e32 v49, v44, v52
	s_waitcnt lgkmcnt(5)
	v_mul_f32_e32 v44, v62, v51
	ds_bpermute_b32 v75, v145, v43
	v_fmac_f32_e32 v44, v40, v61
	s_waitcnt lgkmcnt(5)
	v_mul_f32_e32 v40, v54, v70
	v_fmac_f32_e32 v40, v45, v53
	s_waitcnt lgkmcnt(4)
	v_mul_f32_e32 v45, v67, v71
	v_fmac_f32_e32 v45, v41, v64
	s_waitcnt lgkmcnt(3)
	v_mul_f32_e32 v41, v58, v72
	v_fmac_f32_e32 v41, v46, v57
	s_waitcnt lgkmcnt(2)
	v_mul_f32_e32 v46, v69, v73
	v_cndmask_b32_e64 v68, 0, v48, s[0:1]
	v_lshrrev_b32_e32 v48, 6, v150
	v_fmac_f32_e32 v46, v42, v63
	s_waitcnt lgkmcnt(1)
	v_mul_f32_e32 v42, v59, v74
	v_and_or_b32 v60, v48, 31, v66
	v_lshlrev_b32_e32 v48, 3, v150
	v_fmac_f32_e32 v42, v47, v55
	s_waitcnt lgkmcnt(0)
	v_mul_f32_e32 v47, v68, v75
	v_and_b32_e32 v48, 0xf8, v48
	v_fmac_f32_e32 v47, v43, v65
	v_cvt_pk_bf16_f32 v40, v49, v40
	v_cvt_pk_bf16_f32 v41, v41, v42
	v_cvt_pk_bf16_f32 v42, v44, v45
	v_cvt_pk_bf16_f32 v43, v46, v47
	s_cbranch_vccnz .LBB0_324
	s_lshl_b32 s21, s19, 5
	s_lshl_b32 s28, s8, 7
	s_or_b32 s21, s28, s21
	s_addk_i32 s21, 0xff00
	v_add_u32_e32 v44, s21, v60
	v_ashrrev_i32_e32 v45, 31, v44
	v_lshlrev_b64 v[44:45], 13, v[44:45]
	v_lshl_add_u64 v[44:45], s[14:15], 0, v[44:45]
	v_mov_b32_e32 v49, v195
	v_lshl_add_u64 v[44:45], v[44:45], 0, v[194:195]
	s_mov_b64 s[28:29], 0
	v_mov_b64_e32 v[46:47], v[48:49]

; __device__ __forceinline__ u32x4 pack8(const f32x4 v0, const f32x4 v1) { u32x4 w; w.x = cvt_pk_bf16(v0[0], v0[1]); w.y = cvt_pk_bf16(v0[2], v0[3]); w.z = cvt_pk_bf16(v1[0], v1[1]); w.w = cvt_pk_bf16(v1[2], v1[3]); return w; }
;     __device__ __forceinline__ bf16_t* dst(const Unit& u, int row, int bj, int wc, int fq, int col0) const {
;         if (u.pn < 2 || u.pn >= 6) return O + (size_t)row * ldc + col0 + bj * HALF;
;         const int b = row >> 11, t = row & 2047;
;         if (u.pn < 4) { const int hc = (u.pn - 2) * 4 + bj * 2 + (wc >> 1), chunk = (wc & 1) * 4 + fq;
;             return KC + (size_t)((b * 8 + hc) * 32 + (t >> 6)) * 4096 + chunk * 512 + (t & 63) * 8; }
;         const int h = (u.pn - 4) * 2 + bj, piece = wc * 4 + ((t & 63) >> 4);
;         return VC + (size_t)((b * 4 + h) * 32 + (t >> 6)) * 8192 + piece * 512 + (t & 15) * 32 + fq * 8;
;     __device__ __forceinline__ void operator()(const f32x4 (&acc)[2][2][4][2], const Unit& u, int wr, int wc, int fr, int fq) const {
;     ...
;                     for (int bj = 0; bj < 2; ++bj) { f32x4 v0 = acc[ai][bj][m][0] * r, v1 = acc[ai][bj][m][1] * r; f32x4 p0, p1;
; #pragma unroll
;                         for (int e = 0; e < 4; ++e) { p0[e] = __shfl_xor(v0[e], 16); p1[e] = __shfl_xor(v1[e], 16); }
; #pragma unroll
;                         for (int e = 0; e < 4; ++e) { v0[e] = v0[e] * c[e] + p0[e] * sn[e]; v1[e] = v1[e] * c[4 + e] + p1[e] * sn[4 + e]; }
;                         *(u32x4*)dst(u, row, bj, wc, fq, col0) = pack8(v0, v1); } }
.LBB0_326:
	v_mov_b32_e32 v51, v50
	v_lshl_add_u64 v[44:45], v[46:47], 1, v[44:45]
	global_store_dwordx4 v[44:45], v[40:43], off sc1
	v_pk_mul_f32 v[36:37], v[36:37], v[50:51]
	v_pk_mul_f32 v[32:33], v[32:33], v[50:51]
	v_mov_b32_e32 v40, v50
	v_mov_b32_e32 v41, v50
	v_pk_mul_f32 v[38:39], v[38:39], v[40:41]
	v_pk_mul_f32 v[34:35], v[34:35], v[40:41]
	ds_bpermute_b32 v40, v145, v36
	ds_bpermute_b32 v41, v145, v32
	ds_bpermute_b32 v42, v145, v37
	ds_bpermute_b32 v43, v145, v33
	ds_bpermute_b32 v44, v145, v38
	ds_bpermute_b32 v45, v145, v34
	s_waitcnt lgkmcnt(5)
	v_mul_f32_e32 v40, v56, v40
	ds_bpermute_b32 v46, v145, v39
	v_fmac_f32_e32 v40, v36, v52
	s_waitcnt lgkmcnt(5)
	v_mul_f32_e32 v36, v62, v41
	ds_bpermute_b32 v47, v145, v35
	v_fmac_f32_e32 v36, v32, v61
	s_waitcnt lgkmcnt(5)
	v_mul_f32_e32 v32, v54, v42
	v_fmac_f32_e32 v32, v37, v53
	s_waitcnt lgkmcnt(4)
	v_mul_f32_e32 v37, v67, v43
	v_fmac_f32_e32 v37, v33, v64
	s_waitcnt lgkmcnt(3)
	v_mul_f32_e32 v33, v58, v44
	v_fmac_f32_e32 v33, v38, v57
	s_waitcnt lgkmcnt(2)
	v_mul_f32_e32 v38, v69, v45
	v_fmac_f32_e32 v38, v34, v63
	s_waitcnt lgkmcnt(1)
	v_mul_f32_e32 v34, v59, v46
	v_fmac_f32_e32 v34, v39, v55
	s_waitcnt lgkmcnt(0)
	v_mul_f32_e32 v39, v68, v47
	s_and_b64 vcc, exec, s[42:43]
	s_mov_b64 s[28:29], -1
	v_fmac_f32_e32 v39, v35, v65
	v_cvt_pk_bf16_f32 v32, v40, v32
	v_cvt_pk_bf16_f32 v33, v33, v34
	v_cvt_pk_bf16_f32 v34, v36, v37
	v_cvt_pk_bf16_f32 v35, v38, v39
	s_cbranch_vccnz .LBB0_328
	s_lshl_b32 s21, s19, 5
	s_lshl_b32 s28, s8, 7
	s_or_b32 s21, s28, s21
	s_addk_i32 s21, 0xff40
	v_add_u32_e32 v36, s21, v60
	v_ashrrev_i32_e32 v37, 31, v36
	v_lshlrev_b64 v[36:37], 13, v[36:37]
	v_lshl_add_u64 v[36:37], s[14:15], 0, v[36:37]
	v_lshl_add_u64 v[36:37], v[36:37], 0, v[194:195]
	v_mov_b32_e32 v49, v195
	s_mov_b64 s[28:29], 0

; __device__ __forceinline__ u32x4 pack8(const f32x4 v0, const f32x4 v1) { u32x4 w; w.x = cvt_pk_bf16(v0[0], v0[1]); w.y = cvt_pk_bf16(v0[2], v0[3]); w.z = cvt_pk_bf16(v1[0], v1[1]); w.w = cvt_pk_bf16(v1[2], v1[3]); return w; }
;     __device__ __forceinline__ void operator()(const f32x4 (&acc)[2][2][4][2], const Unit& u, int wr, int wc, int fr, int fq) const {
;     ...
;                 for (int m = 0; m < 4; ++m) { const int row = row0 + ai * HALF + m * 16; const float r = rs[ai * 4 + m] * sc; const float pf = (float)ps[ai * 4 + m];
;                     float c[8], sn[8];
; #pragma unroll
;                     for (int e = 0; e < 8; ++e) { const float rev = __builtin_amdgcn_fractf((pf * invf[e]) * 0.15915494309189535f); c[e] = mine ? __builtin_amdgcn_cosf(rev) : 1.f; sn[e] = mine ? __builtin_amdgcn_sinf(rev) * sgn : 0.f; }
; #pragma unroll
;                     for (int bj = 0; bj < 2; ++bj) { f32x4 v0 = acc[ai][bj][m][0] * r, v1 = acc[ai][bj][m][1] * r; f32x4 p0, p1;
; #pragma unroll
;                         for (int e = 0; e < 4; ++e) { p0[e] = __shfl_xor(v0[e], 16); p1[e] = __shfl_xor(v1[e], 16); }
; #pragma unroll
;                         for (int e = 0; e < 4; ++e) { v0[e] = v0[e] * c[e] + p0[e] * sn[e]; v1[e] = v1[e] * c[4 + e] + p1[e] * sn[4 + e]; }
;                         *(u32x4*)dst(u, row, bj, wc, fq, col0) = pack8(v0, v1); } }
.LBB0_330:
	s_waitcnt vmcnt(12)
	v_cvt_f32_i32_e32 v44, v129
	v_lshl_add_u64 v[36:37], v[48:49], 1, v[36:37]
	global_store_dwordx4 v[36:37], v[32:35], off sc1
	s_and_b64 vcc, exec, s[42:43]
	s_mov_b64 s[28:29], -1
	v_mul_f32_e32 v32, 0.15915494, v44
	v_fract_f32_e32 v32, v32
	v_cos_f32_e32 v34, v32
	v_mul_f32_e32 v33, 0x3e4693af, v44
	v_mul_f32_e32 v33, 0.15915494, v33
	v_sin_f32_e32 v32, v32
	v_fract_f32_e32 v33, v33
	v_cndmask_b32_e64 v36, 1.0, v34, s[0:1]
	v_cos_f32_e32 v34, v33
	v_sin_f32_e32 v33, v33
	v_cndmask_b32_e64 v32, v32, -v32, s[40:41]
	v_cndmask_b32_e64 v40, 0, v32, s[0:1]
	v_cndmask_b32_e64 v37, 1.0, v34, s[0:1]
	v_cndmask_b32_e64 v32, v33, -v33, s[40:41]
	v_cndmask_b32_e64 v38, 0, v32, s[0:1]
	v_mul_f32_e32 v32, 0x3d1a08c8, v44
	v_mul_f32_e32 v32, 0.15915494, v32
	v_fract_f32_e32 v32, v32
	v_cos_f32_e32 v33, v32
	v_sin_f32_e32 v32, v32
	v_mul_f32_e32 v34, 0x3beef74e, v44
	v_mul_f32_e32 v34, 0.15915494, v34
	v_cndmask_b32_e64 v41, 1.0, v33, s[0:1]
	v_mul_f32_e32 v33, 0x3ab95d22, v44
	v_fract_f32_e32 v34, v34
	v_cndmask_b32_e64 v32, v32, -v32, s[40:41]
	v_mul_f32_e32 v33, 0.15915494, v33
	v_cndmask_b32_e64 v42, 0, v32, s[0:1]
	v_sin_f32_e32 v32, v34
	v_fract_f32_e32 v33, v33
	v_cos_f32_e32 v35, v34
	v_cos_f32_e32 v34, v33
	v_sin_f32_e32 v33, v33
	v_cndmask_b32_e64 v32, v32, -v32, s[40:41]
	v_cndmask_b32_e64 v43, 0, v32, s[0:1]
	v_cndmask_b32_e64 v45, 1.0, v34, s[0:1]
	v_cndmask_b32_e64 v32, v33, -v33, s[40:41]
	v_cndmask_b32_e64 v46, 0, v32, s[0:1]
	v_mul_f32_e32 v32, 0x398fc8f8, v44
	v_mul_f32_e32 v32, 0.15915494, v32
	v_fract_f32_e32 v32, v32
	v_cos_f32_e32 v33, v32
	v_sin_f32_e32 v32, v32
	v_mul_f32_e32 v34, 0x385f10c4, v44
	v_mul_f32_e32 v34, 0.15915494, v34
	v_cndmask_b32_e64 v48, 1.0, v33, s[0:1]
	v_mul_f32_e32 v33, 0x372d07a7, v44
	v_mul_f32_e32 v33, 0.15915494, v33
	v_fract_f32_e32 v34, v34
	v_cndmask_b32_e64 v32, v32, -v32, s[40:41]
	v_fract_f32_e32 v33, v33
	v_cndmask_b32_e64 v39, 1.0, v35, s[0:1]
	v_cos_f32_e32 v35, v34
	v_cndmask_b32_e64 v50, 0, v32, s[0:1]
	v_sin_f32_e32 v32, v34
	v_cos_f32_e32 v34, v33
	v_sin_f32_e32 v33, v33
	v_cndmask_b32_e64 v47, 1.0, v35, s[0:1]
	v_cndmask_b32_e64 v32, v32, -v32, s[40:41]
	v_cndmask_b32_e64 v49, 1.0, v34, s[0:1]
	v_mul_f32_e32 v34, v149, v153
	v_pk_mul_f32 v[28:29], v[28:29], v[34:35] op_sel_hi:[1,0]
	v_cndmask_b32_e64 v52, 0, v32, s[0:1]
	v_cndmask_b32_e64 v32, v33, -v33, s[40:41]
	v_pk_mul_f32 v[24:25], v[24:25], v[34:35] op_sel_hi:[1,0]
	ds_bpermute_b32 v33, v145, v28
	v_pk_mul_f32 v[30:31], v[30:31], v[34:35] op_sel_hi:[1,0]
	v_pk_mul_f32 v[26:27], v[26:27], v[34:35] op_sel_hi:[1,0]
	ds_bpermute_b32 v35, v145, v24
	ds_bpermute_b32 v53, v145, v29
	ds_bpermute_b32 v54, v145, v25
	ds_bpermute_b32 v55, v145, v30
	ds_bpermute_b32 v56, v145, v26
	s_waitcnt lgkmcnt(5)
	v_mul_f32_e32 v33, v40, v33
	ds_bpermute_b32 v57, v145, v31
	v_fmac_f32_e32 v33, v28, v36
	s_waitcnt lgkmcnt(5)
	v_mul_f32_e32 v28, v46, v35
	ds_bpermute_b32 v58, v145, v27
	v_fmac_f32_e32 v28, v24, v45
	s_waitcnt lgkmcnt(5)
	v_mul_f32_e32 v24, v38, v53
	v_fmac_f32_e32 v24, v29, v37
	s_waitcnt lgkmcnt(4)
	v_mul_f32_e32 v29, v50, v54
	v_fmac_f32_e32 v29, v25, v48
	s_waitcnt lgkmcnt(3)
	v_mul_f32_e32 v25, v42, v55
	v_fmac_f32_e32 v25, v30, v41
	s_waitcnt lgkmcnt(2)
	v_mul_f32_e32 v30, v52, v56
	v_cndmask_b32_e64 v51, 0, v32, s[0:1]
	v_lshrrev_b32_e32 v32, 6, v148
	v_fmac_f32_e32 v30, v26, v47
	s_waitcnt lgkmcnt(1)
	v_mul_f32_e32 v26, v43, v57
	v_and_or_b32 v44, v32, 31, v66
	v_lshlrev_b32_e32 v32, 3, v148
	v_fmac_f32_e32 v26, v31, v39
	s_waitcnt lgkmcnt(0)
	v_mul_f32_e32 v31, v51, v58
	v_and_b32_e32 v32, 0x178, v32
	v_fmac_f32_e32 v31, v27, v49
	v_cvt_pk_bf16_f32 v24, v33, v24
	v_cvt_pk_bf16_f32 v25, v25, v26
	v_cvt_pk_bf16_f32 v26, v28, v29
	v_cvt_pk_bf16_f32 v27, v30, v31
	s_cbranch_vccnz .LBB0_332
	s_lshl_b32 s21, s19, 5
	s_lshl_b32 s28, s8, 7
	s_or_b32 s21, s28, s21
	s_addk_i32 s21, 0xff00
	v_add_u32_e32 v28, s21, v44
	v_ashrrev_i32_e32 v29, 31, v28
	v_lshlrev_b64 v[28:29], 13, v[28:29]
	v_lshl_add_u64 v[28:29], s[14:15], 0, v[28:29]
	v_mov_b32_e32 v33, v195
	v_lshl_add_u64 v[28:29], v[28:29], 0, v[194:195]
	s_mov_b64 s[28:29], 0
	v_mov_b64_e32 v[30:31], v[32:33]

; __device__ __forceinline__ u32x4 pack8(const f32x4 v0, const f32x4 v1) { u32x4 w; w.x = cvt_pk_bf16(v0[0], v0[1]); w.y = cvt_pk_bf16(v0[2], v0[3]); w.z = cvt_pk_bf16(v1[0], v1[1]); w.w = cvt_pk_bf16(v1[2], v1[3]); return w; }
;     __device__ __forceinline__ bf16_t* dst(const Unit& u, int row, int bj, int wc, int fq, int col0) const {
;         if (u.pn < 2 || u.pn >= 6) return O + (size_t)row * ldc + col0 + bj * HALF;
;         const int b = row >> 11, t = row & 2047;
;         if (u.pn < 4) { const int hc = (u.pn - 2) * 4 + bj * 2 + (wc >> 1), chunk = (wc & 1) * 4 + fq;
;             return KC + (size_t)((b * 8 + hc) * 32 + (t >> 6)) * 4096 + chunk * 512 + (t & 63) * 8; }
;         const int h = (u.pn - 4) * 2 + bj, piece = wc * 4 + ((t & 63) >> 4);
;         return VC + (size_t)((b * 4 + h) * 32 + (t >> 6)) * 8192 + piece * 512 + (t & 15) * 32 + fq * 8;
;     __device__ __forceinline__ void operator()(const f32x4 (&acc)[2][2][4][2], const Unit& u, int wr, int wc, int fr, int fq) const {
;     ...
;                     for (int bj = 0; bj < 2; ++bj) { f32x4 v0 = acc[ai][bj][m][0] * r, v1 = acc[ai][bj][m][1] * r; f32x4 p0, p1;
; #pragma unroll
;                         for (int e = 0; e < 4; ++e) { p0[e] = __shfl_xor(v0[e], 16); p1[e] = __shfl_xor(v1[e], 16); }
; #pragma unroll
;                         for (int e = 0; e < 4; ++e) { v0[e] = v0[e] * c[e] + p0[e] * sn[e]; v1[e] = v1[e] * c[4 + e] + p1[e] * sn[4 + e]; }
;                         *(u32x4*)dst(u, row, bj, wc, fq, col0) = pack8(v0, v1); } }
.LBB0_334:
	v_mov_b32_e32 v35, v34
	v_lshl_add_u64 v[28:29], v[30:31], 1, v[28:29]
	global_store_dwordx4 v[28:29], v[24:27], off sc1
	v_pk_mul_f32 v[20:21], v[20:21], v[34:35]
	v_pk_mul_f32 v[16:17], v[16:17], v[34:35]
	v_mov_b32_e32 v24, v34
	v_mov_b32_e32 v25, v34
	v_pk_mul_f32 v[22:23], v[22:23], v[24:25]
	v_pk_mul_f32 v[18:19], v[18:19], v[24:25]
	ds_bpermute_b32 v24, v145, v20
	ds_bpermute_b32 v25, v145, v16
	ds_bpermute_b32 v26, v145, v21
	ds_bpermute_b32 v27, v145, v17
	ds_bpermute_b32 v28, v145, v22
	ds_bpermute_b32 v29, v145, v18
	s_waitcnt lgkmcnt(5)
	v_mul_f32_e32 v24, v40, v24
	ds_bpermute_b32 v30, v145, v23
	v_fmac_f32_e32 v24, v20, v36
	s_waitcnt lgkmcnt(5)
	v_mul_f32_e32 v20, v46, v25
	ds_bpermute_b32 v31, v145, v19
	v_fmac_f32_e32 v20, v16, v45
	s_waitcnt lgkmcnt(5)
	v_mul_f32_e32 v16, v38, v26
	v_fmac_f32_e32 v16, v21, v37
	s_waitcnt lgkmcnt(4)
	v_mul_f32_e32 v21, v50, v27
	v_fmac_f32_e32 v21, v17, v48
	s_waitcnt lgkmcnt(3)
	v_mul_f32_e32 v17, v42, v28
	v_fmac_f32_e32 v17, v22, v41
	s_waitcnt lgkmcnt(2)
	v_mul_f32_e32 v22, v52, v29
	v_fmac_f32_e32 v22, v18, v47
	s_waitcnt lgkmcnt(1)
	v_mul_f32_e32 v18, v43, v30
	v_fmac_f32_e32 v18, v23, v39
	s_waitcnt lgkmcnt(0)
	v_mul_f32_e32 v23, v51, v31
	s_and_b64 vcc, exec, s[42:43]
	s_mov_b64 s[28:29], -1
	v_fmac_f32_e32 v23, v19, v49
	v_cvt_pk_bf16_f32 v16, v24, v16
	v_cvt_pk_bf16_f32 v17, v17, v18
	v_cvt_pk_bf16_f32 v18, v20, v21
	v_cvt_pk_bf16_f32 v19, v22, v23
	s_cbranch_vccnz .LBB0_336
	s_lshl_b32 s21, s19, 5
	s_lshl_b32 s28, s8, 7
	s_or_b32 s21, s28, s21
	s_addk_i32 s21, 0xff40
	v_add_u32_e32 v20, s21, v44
	v_ashrrev_i32_e32 v21, 31, v20
	v_lshlrev_b64 v[20:21], 13, v[20:21]
	v_lshl_add_u64 v[20:21], s[14:15], 0, v[20:21]
	v_lshl_add_u64 v[20:21], v[20:21], 0, v[194:195]
	v_mov_b32_e32 v33, v195
	s_mov_b64 s[28:29], 0

; __device__ __forceinline__ u32x4 pack8(const f32x4 v0, const f32x4 v1) { u32x4 w; w.x = cvt_pk_bf16(v0[0], v0[1]); w.y = cvt_pk_bf16(v0[2], v0[3]); w.z = cvt_pk_bf16(v1[0], v1[1]); w.w = cvt_pk_bf16(v1[2], v1[3]); return w; }
;     __device__ __forceinline__ void operator()(const f32x4 (&acc)[2][2][4][2], const Unit& u, int wr, int wc, int fr, int fq) const {
;     ...
;                 for (int m = 0; m < 4; ++m) { const int row = row0 + ai * HALF + m * 16; const float r = rs[ai * 4 + m] * sc; const float pf = (float)ps[ai * 4 + m];
;                     float c[8], sn[8];
; #pragma unroll
;                     for (int e = 0; e < 8; ++e) { const float rev = __builtin_amdgcn_fractf((pf * invf[e]) * 0.15915494309189535f); c[e] = mine ? __builtin_amdgcn_cosf(rev) : 1.f; sn[e] = mine ? __builtin_amdgcn_sinf(rev) * sgn : 0.f; }
; #pragma unroll
;                     for (int bj = 0; bj < 2; ++bj) { f32x4 v0 = acc[ai][bj][m][0] * r, v1 = acc[ai][bj][m][1] * r; f32x4 p0, p1;
; #pragma unroll
;                         for (int e = 0; e < 4; ++e) { p0[e] = __shfl_xor(v0[e], 16); p1[e] = __shfl_xor(v1[e], 16); }
; #pragma unroll
;                         for (int e = 0; e < 4; ++e) { v0[e] = v0[e] * c[e] + p0[e] * sn[e]; v1[e] = v1[e] * c[4 + e] + p1[e] * sn[4 + e]; }
;                         *(u32x4*)dst(u, row, bj, wc, fq, col0) = pack8(v0, v1); } }
.LBB0_338:
	s_waitcnt vmcnt(13)
	v_cvt_f32_i32_e32 v27, v128
	v_lshl_add_u64 v[20:21], v[32:33], 1, v[20:21]
	global_store_dwordx4 v[20:21], v[16:19], off sc1
	s_and_b64 vcc, exec, s[42:43]
	v_mul_f32_e32 v21, 0x3beef74e, v27
	v_mul_f32_e32 v16, 0.15915494, v27
	v_mul_f32_e32 v17, 0x3e4693af, v27
	v_fract_f32_e32 v16, v16
	v_mul_f32_e32 v17, 0.15915494, v17
	v_cos_f32_e32 v18, v16
	v_sin_f32_e32 v16, v16
	v_fract_f32_e32 v17, v17
	v_cos_f32_e32 v19, v17
	v_sin_f32_e32 v17, v17
	v_cndmask_b32_e64 v16, v16, -v16, s[40:41]
	v_cndmask_b32_e64 v22, 0, v16, s[0:1]
	v_mul_f32_e32 v21, 0.15915494, v21
	v_cndmask_b32_e64 v16, v17, -v17, s[40:41]
	v_cndmask_b32_e64 v20, 0, v16, s[0:1]
	v_mul_f32_e32 v16, 0x3d1a08c8, v27
	v_mul_f32_e32 v16, 0.15915494, v16
	v_fract_f32_e32 v16, v16
	v_cos_f32_e32 v17, v16
	v_sin_f32_e32 v16, v16
	v_fract_f32_e32 v25, v21
	v_cos_f32_e32 v21, v25
	v_cndmask_b32_e64 v23, 1.0, v17, s[0:1]
	v_mul_f32_e32 v17, 0x3ab95d22, v27
	v_cndmask_b32_e64 v16, v16, -v16, s[40:41]
	v_mul_f32_e32 v17, 0.15915494, v17
	v_cndmask_b32_e64 v24, 0, v16, s[0:1]
	v_sin_f32_e32 v16, v25
	v_fract_f32_e32 v17, v17
	v_cos_f32_e32 v26, v17
	v_sin_f32_e32 v17, v17
	v_cndmask_b32_e64 v16, v16, -v16, s[40:41]
	v_cndmask_b32_e64 v25, 0, v16, s[0:1]
	v_mul_f32_e32 v29, 0x385f10c4, v27
	v_cndmask_b32_e64 v16, v17, -v17, s[40:41]
	v_cndmask_b32_e64 v28, 0, v16, s[0:1]
	v_mul_f32_e32 v16, 0x398fc8f8, v27
	v_mul_f32_e32 v16, 0.15915494, v16
	v_fract_f32_e32 v16, v16
	v_cos_f32_e32 v17, v16
	v_sin_f32_e32 v16, v16
	v_mul_f32_e32 v29, 0.15915494, v29
	v_fract_f32_e32 v31, v29
	v_cndmask_b32_e64 v30, 1.0, v17, s[0:1]
	v_mul_f32_e32 v17, 0x372d07a7, v27
	v_cndmask_b32_e64 v16, v16, -v16, s[40:41]
	v_mul_f32_e32 v17, 0.15915494, v17
	v_cndmask_b32_e64 v32, 0, v16, s[0:1]
	v_sin_f32_e32 v16, v31
	v_fract_f32_e32 v17, v17
	v_cos_f32_e32 v27, v17
	v_sin_f32_e32 v17, v17
	v_cndmask_b32_e64 v16, v16, -v16, s[40:41]
	v_cndmask_b32_e64 v34, 0, v16, s[0:1]
	v_cos_f32_e32 v29, v31
	v_cndmask_b32_e64 v16, v17, -v17, s[40:41]
	v_lshrrev_b32_e32 v17, 6, v144
	v_cndmask_b32_e64 v31, 1.0, v27, s[0:1]
	v_cndmask_b32_e64 v33, 0, v16, s[0:1]
	v_mul_f32_e32 v16, v149, v151
	v_and_or_b32 v27, v17, 31, v66
	v_lshlrev_b32_e32 v17, 3, v144
	v_pk_mul_f32 v[12:13], v[12:13], v[16:17] op_sel_hi:[1,0]
	v_and_b32_e32 v166, 0x1f8, v17
	v_pk_mul_f32 v[14:15], v[14:15], v[16:17] op_sel_hi:[1,0]
	v_pk_mul_f32 v[10:11], v[10:11], v[16:17] op_sel_hi:[1,0]
	v_pk_mul_f32 v[8:9], v[8:9], v[16:17] op_sel_hi:[1,0]
	ds_bpermute_b32 v17, v145, v12
	ds_bpermute_b32 v35, v145, v8
	ds_bpermute_b32 v36, v145, v13
	ds_bpermute_b32 v37, v145, v9
	ds_bpermute_b32 v38, v145, v14
	v_cndmask_b32_e64 v18, 1.0, v18, s[0:1]
	ds_bpermute_b32 v39, v145, v10
	s_waitcnt lgkmcnt(5)
	v_mul_f32_e32 v17, v22, v17
	v_cndmask_b32_e64 v26, 1.0, v26, s[0:1]
	ds_bpermute_b32 v40, v145, v15
	v_fmac_f32_e32 v17, v12, v18
	s_waitcnt lgkmcnt(5)
	v_mul_f32_e32 v12, v28, v35
	v_cndmask_b32_e64 v19, 1.0, v19, s[0:1]
	ds_bpermute_b32 v41, v145, v11
	v_fmac_f32_e32 v12, v8, v26
	s_waitcnt lgkmcnt(5)
	v_mul_f32_e32 v8, v20, v36
	v_fmac_f32_e32 v8, v13, v19
	s_waitcnt lgkmcnt(4)
	v_mul_f32_e32 v13, v32, v37
	v_fmac_f32_e32 v13, v9, v30
	s_waitcnt lgkmcnt(3)
	v_mul_f32_e32 v9, v24, v38
	v_cndmask_b32_e64 v29, 1.0, v29, s[0:1]
	v_fmac_f32_e32 v9, v14, v23
	s_waitcnt lgkmcnt(2)
	v_mul_f32_e32 v14, v34, v39
	v_cndmask_b32_e64 v21, 1.0, v21, s[0:1]
	v_fmac_f32_e32 v14, v10, v29
	s_waitcnt lgkmcnt(1)
	v_mul_f32_e32 v10, v25, v40
	v_fmac_f32_e32 v10, v15, v21
	s_waitcnt lgkmcnt(0)
	v_mul_f32_e32 v15, v33, v41
	v_fmac_f32_e32 v15, v11, v31
	s_mov_b64 s[0:1], -1
	v_cvt_pk_bf16_f32 v8, v17, v8
	v_cvt_pk_bf16_f32 v9, v9, v10
	v_cvt_pk_bf16_f32 v10, v12, v13
	v_cvt_pk_bf16_f32 v11, v14, v15
	s_cbranch_vccnz .LBB0_340
	s_lshl_b32 s0, s19, 5
	s_lshl_b32 s1, s8, 7
	s_or_b32 s0, s1, s0
	s_addk_i32 s0, 0xff00
	v_add_u32_e32 v12, s0, v27
	v_ashrrev_i32_e32 v13, 31, v12
	v_lshlrev_b64 v[12:13], 13, v[12:13]
	v_lshl_add_u64 v[12:13], s[14:15], 0, v[12:13]
	v_mov_b32_e32 v167, v195
	v_lshl_add_u64 v[12:13], v[12:13], 0, v[194:195]
	s_mov_b64 s[0:1], 0
	v_mov_b64_e32 v[14:15], v[166:167]

; __device__ __forceinline__ u32x4 pack8(const f32x4 v0, const f32x4 v1) { u32x4 w; w.x = cvt_pk_bf16(v0[0], v0[1]); w.y = cvt_pk_bf16(v0[2], v0[3]); w.z = cvt_pk_bf16(v1[0], v1[1]); w.w = cvt_pk_bf16(v1[2], v1[3]); return w; }
;     __device__ __forceinline__ bf16_t* dst(const Unit& u, int row, int bj, int wc, int fq, int col0) const {
;         if (u.pn < 2 || u.pn >= 6) return O + (size_t)row * ldc + col0 + bj * HALF;
;         const int b = row >> 11, t = row & 2047;
;         if (u.pn < 4) { const int hc = (u.pn - 2) * 4 + bj * 2 + (wc >> 1), chunk = (wc & 1) * 4 + fq;
;             return KC + (size_t)((b * 8 + hc) * 32 + (t >> 6)) * 4096 + chunk * 512 + (t & 63) * 8; }
;         const int h = (u.pn - 4) * 2 + bj, piece = wc * 4 + ((t & 63) >> 4);
;         return VC + (size_t)((b * 4 + h) * 32 + (t >> 6)) * 8192 + piece * 512 + (t & 15) * 32 + fq * 8;
;     __device__ __forceinline__ void operator()(const f32x4 (&acc)[2][2][4][2], const Unit& u, int wr, int wc, int fr, int fq) const {
;     ...
;                     for (int bj = 0; bj < 2; ++bj) { f32x4 v0 = acc[ai][bj][m][0] * r, v1 = acc[ai][bj][m][1] * r; f32x4 p0, p1;
; #pragma unroll
;                         for (int e = 0; e < 4; ++e) { p0[e] = __shfl_xor(v0[e], 16); p1[e] = __shfl_xor(v1[e], 16); }
; #pragma unroll
;                         for (int e = 0; e < 4; ++e) { v0[e] = v0[e] * c[e] + p0[e] * sn[e]; v1[e] = v1[e] * c[4 + e] + p1[e] * sn[4 + e]; }
;                         *(u32x4*)dst(u, row, bj, wc, fq, col0) = pack8(v0, v1); } }
.LBB0_342:
	v_mov_b32_e32 v17, v16
	v_lshl_add_u64 v[12:13], v[14:15], 1, v[12:13]
	global_store_dwordx4 v[12:13], v[8:11], off sc1
	v_pk_mul_f32 v[4:5], v[4:5], v[16:17]
	v_pk_mul_f32 v[0:1], v[0:1], v[16:17]
	v_mov_b32_e32 v8, v16
	v_mov_b32_e32 v9, v16
	v_pk_mul_f32 v[6:7], v[6:7], v[8:9]
	v_pk_mul_f32 v[2:3], v[2:3], v[8:9]
	ds_bpermute_b32 v8, v145, v4
	ds_bpermute_b32 v9, v145, v0
	ds_bpermute_b32 v10, v145, v5
	ds_bpermute_b32 v11, v145, v1
	ds_bpermute_b32 v12, v145, v6
	ds_bpermute_b32 v13, v145, v2
	s_waitcnt lgkmcnt(5)
	v_mul_f32_e32 v8, v22, v8
	ds_bpermute_b32 v14, v145, v7
	v_fmac_f32_e32 v8, v4, v18
	s_waitcnt lgkmcnt(5)
	v_mul_f32_e32 v4, v28, v9
	ds_bpermute_b32 v15, v145, v3
	v_fmac_f32_e32 v4, v0, v26
	s_waitcnt lgkmcnt(5)
	v_mul_f32_e32 v0, v20, v10
	v_fmac_f32_e32 v0, v5, v19
	s_waitcnt lgkmcnt(4)
	v_mul_f32_e32 v5, v32, v11
	v_fmac_f32_e32 v5, v1, v30
	s_waitcnt lgkmcnt(3)
	v_mul_f32_e32 v1, v24, v12
	v_fmac_f32_e32 v1, v6, v23
	s_waitcnt lgkmcnt(2)
	v_mul_f32_e32 v6, v34, v13
	v_fmac_f32_e32 v6, v2, v29
	s_waitcnt lgkmcnt(1)
	v_mul_f32_e32 v2, v25, v14
	v_fmac_f32_e32 v2, v7, v21
	s_waitcnt lgkmcnt(0)
	v_mul_f32_e32 v7, v33, v15
	s_and_b64 vcc, exec, s[42:43]
	s_mov_b64 s[0:1], -1
	v_fmac_f32_e32 v7, v3, v31
	v_cvt_pk_bf16_f32 v128, v8, v0
	v_cvt_pk_bf16_f32 v129, v1, v2
	v_cvt_pk_bf16_f32 v130, v4, v5
	v_cvt_pk_bf16_f32 v131, v6, v7
	s_cbranch_vccnz .LBB0_344
	s_lshl_b32 s0, s19, 5
	s_lshl_b32 s1, s8, 7
	s_or_b32 s0, s1, s0
	s_addk_i32 s0, 0xff40
	v_add_u32_e32 v0, s0, v27
	v_ashrrev_i32_e32 v1, 31, v0
	v_lshlrev_b64 v[0:1], 13, v[0:1]
	v_lshl_add_u64 v[0:1], s[14:15], 0, v[0:1]
	v_lshl_add_u64 v[168:169], v[0:1], 0, v[194:195]
	s_mov_b64 s[0:1], 0

; __device__ __forceinline__ u32x4 pack8(const f32x4 v0, const f32x4 v1) { u32x4 w; w.x = cvt_pk_bf16(v0[0], v0[1]); w.y = cvt_pk_bf16(v0[2], v0[3]); w.z = cvt_pk_bf16(v1[0], v1[1]); w.w = cvt_pk_bf16(v1[2], v1[3]); return w; }
; #define PG8_BAR __builtin_amdgcn_s_barrier()
;     __device__ __forceinline__ void operator()(const f32x4 (&acc)[2][2][4][2], const Unit& u, int wr, int wc, int fr, int fq) const {
;     ...
; #pragma unroll
;                         for (int e = 0; e < 4; ++e) { v0[e] = v0[e] * c[e] + p0[e] * sn[e]; v1[e] = v1[e] * c[4 + e] + p1[e] * sn[4 + e]; }
;                         *(u32x4*)dst(u, row, bj, wc, fq, col0) = pack8(v0, v1); } }
; template <class Epi, class Sched, bool ALIGN_EPI = false, bool SP2 = false>
; __device__ __forceinline__ void gemm_phase(PG8_LAS unsigned char* lds, const Gemm g, const Sched& S, const Epi& E) {
;     ...
;         if (!has_next) break;
; #pragma unroll
;         for (int a = 0; a < 2; ++a)
; #pragma unroll
;             for (int b = 0; b < 2; ++b)
; #pragma unroll
;                 for (int m = 0; m < 4; ++m)
; #pragma unroll
;                     for (int n = 0; n < 2; ++n) acc[a][b][m][n] = (f32x4){0.f, 0.f, 0.f, 0.f};
;         cur = nxt; cA = nA; cB = nB; ++ui; relax = Epi::LOADS_BEFORE_STORES && !Epi::AFTER_DRAIN && SP2;
;         if constexpr (ALIGN_EPI) { if (wr == 1) PG8_BAR; }
.LBB0_346:
	v_mov_b32_e32 v167, v195
	v_lshl_add_u64 v[0:1], v[166:167], 1, v[168:169]
	s_mov_b64 s[42:43], -1
	s_andn2_b64 vcc, exec, s[22:23]
	s_mov_b64 s[0:1], -1
	global_store_dwordx4 v[0:1], v[128:131], off sc1
	s_cbranch_vccnz .LBB0_142
	s_andn2_b64 vcc, exec, s[10:11]
	s_cbranch_vccnz .LBB0_141
	s_barrier
	s_branch .LBB0_141

; __device__ __forceinline__ u32x4 pack8(const f32x4 v0, const f32x4 v1) { u32x4 w; w.x = cvt_pk_bf16(v0[0], v0[1]); w.y = cvt_pk_bf16(v0[2], v0[3]); w.z = cvt_pk_bf16(v1[0], v1[1]); w.w = cvt_pk_bf16(v1[2], v1[3]); return w; }
; __device__ __forceinline__ float sumsq8(const f32x4 a, const f32x4 b) { return ((a[0] * a[0] + a[1] * a[1]) + (a[2] * a[2] + a[3] * a[3])) + ((b[0] * b[0] + b[1] * b[1]) + (b[2] * b[2] + b[3] * b[3])); }
; __device__ __forceinline__ void unpack8(const u32x4 w, f32x4& a, f32x4& b) { a = (f32x4){bf_lo(w.x), bf_hi(w.x), bf_lo(w.y), bf_hi(w.y)}; b = (f32x4){bf_lo(w.z), bf_hi(w.z), bf_lo(w.w), bf_hi(w.w)}; }
;     __device__ __forceinline__ void operator()(const f32x4 (&acc)[2][2][4][2], const Unit& u, int wr, int wc, int fr, int fq) const {
;         const int row0 = u.pm * BM + wr * 64 + fr, col0 = u.pn * BM + wc * 32 + 8 * fq;
;         u32x4 rv[8][2];
; #pragma unroll
;         for (int i = 0; i < 8; ++i)
; #pragma unroll
;             for (int bj = 0; bj < 2; ++bj) rv[i][bj] = *(const u32x4*)(Rin + (size_t)(row0 + (i >> 2) * HALF + (i & 3) * 16) * DMODEL + col0 + bj * HALF);
; #pragma unroll
;         for (int ai = 0; ai < 2; ++ai)
; #pragma unroll
;             for (int m = 0; m < 4; ++m) { const int row = row0 + ai * HALF + m * 16; float part = 0.f;
; #pragma unroll
;                 for (int bj = 0; bj < 2; ++bj) { f32x4 r0, r1; unpack8(rv[ai * 4 + m][bj], r0, r1);
;                     const f32x4 h0 = r0 + acc[ai][bj][m][0], h1 = r1 + acc[ai][bj][m][1]; part += sumsq8(h0, h1);
;                     *(u32x4*)(XBo + (size_t)row * DMODEL + col0 + bj * HALF) = pack8(h0, h1); }
;                 part += __shfl_xor(part, 16); part += __shfl_xor(part, 32);
;                 if (fq == 0) ssq[(size_t)row * 16 + u.pn * 4 + wc] = part; }
.LBB0_517:
	v_mov_b32_e32 v116, v192
	s_lshl_b32 s1, s40, 8
	v_readfirstlane_b32 s0, v116
	s_bfe_u32 s17, s0, 0x20006
	s_ashr_i32 s0, s0, 2
	s_andn2_b32 s0, s0, 63
	s_add_i32 s0, s0, s1
	v_and_or_b32 v216, v116, 15, s0
	s_lshl_b32 s0, s26, 8
	s_lshl_b32 s1, s17, 5
	v_bfe_u32 v249, v116, 4, 2
	s_or_b32 s0, s1, s0
	v_lshl_or_b32 v214, v249, 3, s0
	v_ashrrev_i32_e32 v215, 31, v214
	v_lshlrev_b64 v[234:235], 1, v[214:215]
	v_ashrrev_i32_e32 v217, 31, v216
	v_lshl_add_u64 v[120:121], s[6:7], 0, v[234:235]
	v_lshlrev_b64 v[236:237], 11, v[216:217]
	v_lshl_add_u64 v[116:117], v[120:121], 0, v[236:237]
	global_load_dwordx4 v[188:191], v[116:117], off
	global_load_dwordx4 v[184:187], v[116:117], off offset:256
	v_or_b32_e32 v230, 16, v216
	v_ashrrev_i32_e32 v231, 31, v230
	v_or_b32_e32 v226, 32, v216
	v_lshlrev_b64 v[232:233], 11, v[230:231]
	v_ashrrev_i32_e32 v227, 31, v226
	v_or_b32_e32 v222, 48, v216
	v_lshl_add_u64 v[116:117], v[120:121], 0, v[232:233]
	v_lshlrev_b64 v[228:229], 11, v[226:227]
	v_ashrrev_i32_e32 v223, 31, v222
	v_add_u32_e32 v218, 0x80, v216
	global_load_dwordx4 v[180:183], v[116:117], off
	global_load_dwordx4 v[176:179], v[116:117], off offset:256
	v_lshl_add_u64 v[116:117], v[120:121], 0, v[228:229]
	v_lshlrev_b64 v[224:225], 11, v[222:223]
	v_ashrrev_i32_e32 v219, 31, v218
	global_load_dwordx4 v[172:175], v[116:117], off
	global_load_dwordx4 v[168:171], v[116:117], off offset:256
	v_lshl_add_u64 v[116:117], v[120:121], 0, v[224:225]
	v_lshlrev_b64 v[220:221], 11, v[218:219]
	global_load_dwordx4 v[164:167], v[116:117], off
	global_load_dwordx4 v[160:163], v[116:117], off offset:256
	v_lshl_add_u64 v[116:117], v[120:121], 0, v[220:221]
	global_load_dwordx4 v[156:159], v[116:117], off
	global_load_dwordx4 v[144:147], v[116:117], off offset:256
	v_add_u32_e32 v116, 0x90, v216
	v_ashrrev_i32_e32 v117, 31, v116
	v_lshlrev_b64 v[116:117], 11, v[116:117]
	v_lshl_add_u64 v[116:117], v[120:121], 0, v[116:117]
	global_load_dwordx4 v[140:143], v[116:117], off
	global_load_dwordx4 v[136:139], v[116:117], off offset:256
	v_add_u32_e32 v116, 0xa0, v216
	v_add_u32_e32 v122, 0xb0, v216
	v_ashrrev_i32_e32 v117, 31, v116
	v_ashrrev_i32_e32 v123, 31, v122
	v_lshlrev_b64 v[116:117], 11, v[116:117]
	v_lshlrev_b64 v[122:123], 11, v[122:123]
	v_lshl_add_u64 v[116:117], v[120:121], 0, v[116:117]
	v_lshl_add_u64 v[120:121], v[120:121], 0, v[122:123]
	global_load_dwordx4 v[128:131], v[116:117], off
	s_nop 0
	global_load_dwordx4 v[116:119], v[116:117], off offset:256
	s_nop 0
	global_load_dwordx4 v[132:135], v[120:121], off
	s_nop 0
	global_load_dwordx4 v[120:123], v[120:121], off offset:256
	s_lshl_b32 s26, s26, 2
	v_cmp_eq_u32_e32 vcc, 0, v249
	s_ashr_i32 s27, s26, 31
	s_waitcnt vmcnt(14)
	v_lshlrev_b32_e32 v250, 16, v188
	v_and_b32_e32 v251, 0xffff0000, v188
	v_lshlrev_b32_e32 v188, 16, v189
	v_and_b32_e32 v189, 0xffff0000, v189
	v_lshlrev_b32_e32 v252, 16, v190
	v_and_b32_e32 v253, 0xffff0000, v190
	v_lshlrev_b32_e32 v190, 16, v191
	v_and_b32_e32 v191, 0xffff0000, v191
	v_pk_add_f32 v[154:155], v[154:155], v[188:189]
	v_pk_add_f32 v[152:153], v[152:153], v[250:251]
	v_pk_add_f32 v[188:189], v[150:151], v[190:191]
	v_pk_add_f32 v[150:151], v[148:149], v[252:253]
	v_mul_f32_e32 v148, v153, v153
	v_mul_f32_e32 v149, v155, v155
	v_fmac_f32_e32 v148, v152, v152
	v_fmac_f32_e32 v149, v154, v154
	v_add_f32_e32 v148, v148, v149
	v_mul_f32_e32 v149, v151, v151
	v_mul_f32_e32 v190, v189, v189
	v_fmac_f32_e32 v149, v150, v150
	v_fmac_f32_e32 v190, v188, v188
	v_add_f32_e32 v149, v149, v190
	v_add_f32_e32 v190, v148, v149
	v_cvt_pk_bf16_f32 v148, v152, v153
	v_lshl_add_u64 v[152:153], s[10:11], 0, v[236:237]
	v_cvt_pk_bf16_f32 v149, v154, v155
	v_cvt_pk_bf16_f32 v150, v150, v151
	v_cvt_pk_bf16_f32 v151, v188, v189
	v_lshl_add_u64 v[152:153], v[152:153], 0, v[234:235]
	global_store_dwordx4 v[152:153], v[148:151], off sc1
	v_lshlrev_b32_e32 v154, 16, v186
	v_and_b32_e32 v155, 0xffff0000, v186
	v_lshlrev_b32_e32 v148, 16, v184
	v_and_b32_e32 v149, 0xffff0000, v184
	v_lshlrev_b32_e32 v150, 16, v185
	v_and_b32_e32 v151, 0xffff0000, v185
	v_lshlrev_b32_e32 v184, 16, v187
	v_and_b32_e32 v185, 0xffff0000, v187
	v_pk_add_f32 v[126:127], v[126:127], v[150:151]
	v_pk_add_f32 v[124:125], v[124:125], v[148:149]
	v_pk_add_f32 v[148:149], v[114:115], v[184:185]
	v_pk_add_f32 v[114:115], v[112:113], v[154:155]
	v_mul_f32_e32 v112, v125, v125
	v_mul_f32_e32 v113, v127, v127
	v_fmac_f32_e32 v112, v124, v124
	v_fmac_f32_e32 v113, v126, v126
	v_add_f32_e32 v112, v112, v113
	v_mul_f32_e32 v113, v115, v115
	v_mul_f32_e32 v150, v149, v149
	v_fmac_f32_e32 v113, v114, v114
	v_fmac_f32_e32 v150, v148, v148
	v_add_f32_e32 v113, v113, v150
	v_add_f32_e32 v112, v112, v113
	v_add_f32_e32 v150, v190, v112
	v_cvt_pk_bf16_f32 v112, v124, v125
	v_cvt_pk_bf16_f32 v113, v126, v127
	v_cvt_pk_bf16_f32 v114, v114, v115
	v_cvt_pk_bf16_f32 v115, v148, v149
	global_store_dwordx4 v[152:153], v[112:115], off offset:256 sc1
	s_nop 1
	v_and_b32_e32 v113, 64, v241
	v_xor_b32_e32 v112, 16, v241
	v_add_u32_e32 v113, 64, v113
	v_cmp_lt_i32_e64 s[0:1], v112, v113
	v_xor_b32_e32 v115, 32, v241
	s_nop 0
	v_cndmask_b32_e64 v112, v241, v112, s[0:1]
	v_lshlrev_b32_e32 v112, 2, v112
	ds_bpermute_b32 v114, v112, v150
	v_cmp_lt_i32_e64 s[0:1], v115, v113
	s_waitcnt lgkmcnt(0)
	v_add_f32_e32 v114, v150, v114
	v_cndmask_b32_e64 v113, v241, v115, s[0:1]
	v_lshlrev_b32_e32 v113, 2, v113
	ds_bpermute_b32 v115, v113, v114
	s_and_saveexec_b64 s[0:1], vcc
	s_cbranch_execz .LBB0_519
	v_lshlrev_b64 v[124:125], 6, v[216:217]
	v_lshl_add_u64 v[124:125], s[12:13], 0, v[124:125]
	v_lshl_add_u64 v[124:125], s[26:27], 2, v[124:125]
	s_lshl_b32 s72, s17, 2
	v_lshl_add_u64 v[124:125], v[124:125], 0, s[72:73]
	s_waitcnt lgkmcnt(0)
	v_add_f32_e32 v114, v114, v115
	global_store_dword v[124:125], v114, off
; __device__ __forceinline__ u32x4 pack8(const f32x4 v0, const f32x4 v1) { u32x4 w; w.x = cvt_pk_bf16(v0[0], v0[1]); w.y = cvt_pk_bf16(v0[2], v0[3]); w.z = cvt_pk_bf16(v1[0], v1[1]); w.w = cvt_pk_bf16(v1[2], v1[3]); return w; }
; __device__ __forceinline__ float sumsq8(const f32x4 a, const f32x4 b) { return ((a[0] * a[0] + a[1] * a[1]) + (a[2] * a[2] + a[3] * a[3])) + ((b[0] * b[0] + b[1] * b[1]) + (b[2] * b[2] + b[3] * b[3])); }
; __device__ __forceinline__ void unpack8(const u32x4 w, f32x4& a, f32x4& b) { a = (f32x4){bf_lo(w.x), bf_hi(w.x), bf_lo(w.y), bf_hi(w.y)}; b = (f32x4){bf_lo(w.z), bf_hi(w.z), bf_lo(w.w), bf_hi(w.w)}; }
;     __device__ __forceinline__ void operator()(const f32x4 (&acc)[2][2][4][2], const Unit& u, int wr, int wc, int fr, int fq) const {
;     ...
; #pragma unroll
;         for (int ai = 0; ai < 2; ++ai)
; #pragma unroll
;             for (int m = 0; m < 4; ++m) { const int row = row0 + ai * HALF + m * 16; float part = 0.f;
; #pragma unroll
;                 for (int bj = 0; bj < 2; ++bj) { f32x4 r0, r1; unpack8(rv[ai * 4 + m][bj], r0, r1);
;                     const f32x4 h0 = r0 + acc[ai][bj][m][0], h1 = r1 + acc[ai][bj][m][1]; part += sumsq8(h0, h1);
;                     *(u32x4*)(XBo + (size_t)row * DMODEL + col0 + bj * HALF) = pack8(h0, h1); }
;                 part += __shfl_xor(part, 16); part += __shfl_xor(part, 32);
;                 if (fq == 0) ssq[(size_t)row * 16 + u.pn * 4 + wc] = part; }
.LBB0_519:
	s_or_b64 exec, exec, s[0:1]
	s_waitcnt vmcnt(15)
	v_lshlrev_b32_e32 v114, 16, v180
	s_waitcnt lgkmcnt(0)
	v_and_b32_e32 v115, 0xffff0000, v180
	v_lshlrev_b32_e32 v124, 16, v181
	v_and_b32_e32 v125, 0xffff0000, v181
	v_lshlrev_b32_e32 v126, 16, v182
	v_and_b32_e32 v127, 0xffff0000, v182
	v_lshlrev_b32_e32 v148, 16, v183
	v_and_b32_e32 v149, 0xffff0000, v183
	v_pk_add_f32 v[110:111], v[110:111], v[124:125]
	v_pk_add_f32 v[108:109], v[108:109], v[114:115]
	v_pk_add_f32 v[114:115], v[106:107], v[148:149]
	v_pk_add_f32 v[106:107], v[104:105], v[126:127]
	v_mul_f32_e32 v104, v109, v109
	v_mul_f32_e32 v105, v111, v111
	v_fmac_f32_e32 v104, v108, v108
	v_fmac_f32_e32 v105, v110, v110
	v_add_f32_e32 v104, v104, v105
	v_mul_f32_e32 v105, v107, v107
	v_mul_f32_e32 v124, v115, v115
	v_fmac_f32_e32 v105, v106, v106
	v_fmac_f32_e32 v124, v114, v114
	v_add_f32_e32 v105, v105, v124
	v_add_f32_e32 v126, v104, v105
	v_cvt_pk_bf16_f32 v104, v108, v109
	v_cvt_pk_bf16_f32 v105, v110, v111
	v_lshlrev_b32_e32 v108, 16, v176
	v_and_b32_e32 v109, 0xffff0000, v176
	v_lshlrev_b32_e32 v110, 16, v177
	v_and_b32_e32 v111, 0xffff0000, v177
	v_cvt_pk_bf16_f32 v106, v106, v107
	v_cvt_pk_bf16_f32 v107, v114, v115
	v_lshlrev_b32_e32 v114, 16, v178
	v_and_b32_e32 v115, 0xffff0000, v178
	v_pk_add_f32 v[102:103], v[102:103], v[110:111]
	v_pk_add_f32 v[100:101], v[100:101], v[108:109]
	v_lshlrev_b32_e32 v124, 16, v179
	v_and_b32_e32 v125, 0xffff0000, v179
	v_pk_add_f32 v[110:111], v[96:97], v[114:115]
	v_mul_f32_e32 v96, v101, v101
	v_mul_f32_e32 v97, v103, v103
	v_pk_add_f32 v[108:109], v[98:99], v[124:125]
	v_fmac_f32_e32 v96, v100, v100
	v_fmac_f32_e32 v97, v102, v102
	v_add_f32_e32 v96, v96, v97
	v_mul_f32_e32 v97, v111, v111
	v_mul_f32_e32 v98, v109, v109
	v_fmac_f32_e32 v97, v110, v110
	v_fmac_f32_e32 v98, v108, v108
	v_add_f32_e32 v97, v97, v98
	v_add_f32_e32 v96, v96, v97
	v_add_f32_e32 v99, v126, v96
	ds_bpermute_b32 v124, v112, v99
	v_lshl_add_u64 v[96:97], s[10:11], 0, v[232:233]
	v_lshl_add_u64 v[114:115], v[214:215], 1, v[96:97]
	global_store_dwordx4 v[114:115], v[104:107], off sc1
	v_cvt_pk_bf16_f32 v98, v100, v101
	s_waitcnt lgkmcnt(0)
	v_add_f32_e32 v96, v99, v124
	ds_bpermute_b32 v97, v113, v96
	v_cvt_pk_bf16_f32 v99, v102, v103
	v_cvt_pk_bf16_f32 v100, v110, v111
	v_cvt_pk_bf16_f32 v101, v108, v109
	global_store_dwordx4 v[114:115], v[98:101], off offset:256 sc1
	s_and_saveexec_b64 s[0:1], vcc
	s_cbranch_execz .LBB0_521
	v_lshlrev_b64 v[98:99], 6, v[230:231]
	v_lshl_add_u64 v[98:99], s[12:13], 0, v[98:99]
	v_lshl_add_u64 v[98:99], s[26:27], 2, v[98:99]
	s_lshl_b32 s72, s17, 2
	v_lshl_add_u64 v[98:99], v[98:99], 0, s[72:73]
	s_waitcnt lgkmcnt(0)
	v_add_f32_e32 v96, v96, v97
	global_store_dword v[98:99], v96, off
.LBB0_521:
	s_or_b64 exec, exec, s[0:1]
	s_waitcnt vmcnt(16)
	v_lshlrev_b32_e32 v96, 16, v172
	s_waitcnt lgkmcnt(0)
	v_and_b32_e32 v97, 0xffff0000, v172
	v_lshlrev_b32_e32 v98, 16, v173
	v_and_b32_e32 v99, 0xffff0000, v173
	v_lshlrev_b32_e32 v100, 16, v174
	v_and_b32_e32 v101, 0xffff0000, v174
	v_lshlrev_b32_e32 v102, 16, v175
	v_and_b32_e32 v103, 0xffff0000, v175
	v_pk_add_f32 v[94:95], v[94:95], v[98:99]
	v_pk_add_f32 v[92:93], v[92:93], v[96:97]
	v_pk_add_f32 v[96:97], v[90:91], v[102:103]
	v_pk_add_f32 v[90:91], v[88:89], v[100:101]
	v_mul_f32_e32 v88, v93, v93
	v_mul_f32_e32 v89, v95, v95
	v_fmac_f32_e32 v88, v92, v92
	v_fmac_f32_e32 v89, v94, v94
	v_add_f32_e32 v88, v88, v89
	v_mul_f32_e32 v89, v91, v91
	v_mul_f32_e32 v98, v97, v97
	v_fmac_f32_e32 v89, v90, v90
	v_fmac_f32_e32 v98, v96, v96
	v_add_f32_e32 v89, v89, v98
	v_add_f32_e32 v100, v88, v89
	v_cvt_pk_bf16_f32 v88, v92, v93
	v_cvt_pk_bf16_f32 v89, v94, v95
	v_lshlrev_b32_e32 v92, 16, v168
	v_and_b32_e32 v93, 0xffff0000, v168
	v_lshlrev_b32_e32 v94, 16, v169
	v_and_b32_e32 v95, 0xffff0000, v169
	v_cvt_pk_bf16_f32 v90, v90, v91
	v_cvt_pk_bf16_f32 v91, v96, v97
	v_lshlrev_b32_e32 v96, 16, v170
	v_and_b32_e32 v97, 0xffff0000, v170
	v_pk_add_f32 v[86:87], v[86:87], v[94:95]
	v_pk_add_f32 v[84:85], v[84:85], v[92:93]
	v_lshlrev_b32_e32 v98, 16, v171
	v_and_b32_e32 v99, 0xffff0000, v171
	v_pk_add_f32 v[94:95], v[80:81], v[96:97]
	v_mul_f32_e32 v80, v85, v85
	v_mul_f32_e32 v81, v87, v87
	v_pk_add_f32 v[92:93], v[82:83], v[98:99]
	v_fmac_f32_e32 v80, v84, v84
	v_fmac_f32_e32 v81, v86, v86
	v_add_f32_e32 v80, v80, v81
	v_mul_f32_e32 v81, v95, v95
	v_mul_f32_e32 v82, v93, v93
	v_fmac_f32_e32 v81, v94, v94
	v_fmac_f32_e32 v82, v92, v92
	v_add_f32_e32 v81, v81, v82
	v_add_f32_e32 v80, v80, v81
	v_add_f32_e32 v83, v100, v80
	ds_bpermute_b32 v98, v112, v83
	v_lshl_add_u64 v[80:81], s[10:11], 0, v[228:229]
	v_lshl_add_u64 v[96:97], v[214:215], 1, v[80:81]
	global_store_dwordx4 v[96:97], v[88:91], off sc1
	v_cvt_pk_bf16_f32 v82, v84, v85
	s_waitcnt lgkmcnt(0)
	v_add_f32_e32 v80, v83, v98
	ds_bpermute_b32 v81, v113, v80
	v_cvt_pk_bf16_f32 v83, v86, v87
	v_cvt_pk_bf16_f32 v84, v94, v95
	v_cvt_pk_bf16_f32 v85, v92, v93
	global_store_dwordx4 v[96:97], v[82:85], off offset:256 sc1
	s_and_saveexec_b64 s[0:1], vcc
	s_cbranch_execz .LBB0_523
	v_lshlrev_b64 v[82:83], 6, v[226:227]
	v_lshl_add_u64 v[82:83], s[12:13], 0, v[82:83]
	v_lshl_add_u64 v[82:83], s[26:27], 2, v[82:83]
	s_lshl_b32 s72, s17, 2
	v_lshl_add_u64 v[82:83], v[82:83], 0, s[72:73]
	s_waitcnt lgkmcnt(0)
	v_add_f32_e32 v80, v80, v81
	global_store_dword v[82:83], v80, off
; __device__ __forceinline__ u32x4 pack8(const f32x4 v0, const f32x4 v1) { u32x4 w; w.x = cvt_pk_bf16(v0[0], v0[1]); w.y = cvt_pk_bf16(v0[2], v0[3]); w.z = cvt_pk_bf16(v1[0], v1[1]); w.w = cvt_pk_bf16(v1[2], v1[3]); return w; }
; __device__ __forceinline__ float sumsq8(const f32x4 a, const f32x4 b) { return ((a[0] * a[0] + a[1] * a[1]) + (a[2] * a[2] + a[3] * a[3])) + ((b[0] * b[0] + b[1] * b[1]) + (b[2] * b[2] + b[3] * b[3])); }
; __device__ __forceinline__ void unpack8(const u32x4 w, f32x4& a, f32x4& b) { a = (f32x4){bf_lo(w.x), bf_hi(w.x), bf_lo(w.y), bf_hi(w.y)}; b = (f32x4){bf_lo(w.z), bf_hi(w.z), bf_lo(w.w), bf_hi(w.w)}; }
;     __device__ __forceinline__ void operator()(const f32x4 (&acc)[2][2][4][2], const Unit& u, int wr, int wc, int fr, int fq) const {
;     ...
; #pragma unroll
;         for (int ai = 0; ai < 2; ++ai)
; #pragma unroll
;             for (int m = 0; m < 4; ++m) { const int row = row0 + ai * HALF + m * 16; float part = 0.f;
; #pragma unroll
;                 for (int bj = 0; bj < 2; ++bj) { f32x4 r0, r1; unpack8(rv[ai * 4 + m][bj], r0, r1);
;                     const f32x4 h0 = r0 + acc[ai][bj][m][0], h1 = r1 + acc[ai][bj][m][1]; part += sumsq8(h0, h1);
;                     *(u32x4*)(XBo + (size_t)row * DMODEL + col0 + bj * HALF) = pack8(h0, h1); }
;                 part += __shfl_xor(part, 16); part += __shfl_xor(part, 32);
;                 if (fq == 0) ssq[(size_t)row * 16 + u.pn * 4 + wc] = part; }
.LBB0_523:
	s_or_b64 exec, exec, s[0:1]
	s_waitcnt vmcnt(17)
	v_lshlrev_b32_e32 v80, 16, v164
	s_waitcnt lgkmcnt(0)
	v_and_b32_e32 v81, 0xffff0000, v164
	v_lshlrev_b32_e32 v82, 16, v165
	v_and_b32_e32 v83, 0xffff0000, v165
	v_lshlrev_b32_e32 v84, 16, v166
	v_and_b32_e32 v85, 0xffff0000, v166
	v_lshlrev_b32_e32 v86, 16, v167
	v_and_b32_e32 v87, 0xffff0000, v167
	v_pk_add_f32 v[78:79], v[78:79], v[82:83]
	v_pk_add_f32 v[76:77], v[76:77], v[80:81]
	v_pk_add_f32 v[80:81], v[74:75], v[86:87]
	v_pk_add_f32 v[74:75], v[72:73], v[84:85]
	v_mul_f32_e32 v72, v77, v77
	v_mul_f32_e32 v73, v79, v79
	v_fmac_f32_e32 v72, v76, v76
	v_fmac_f32_e32 v73, v78, v78
	v_add_f32_e32 v72, v72, v73
	v_mul_f32_e32 v73, v75, v75
	v_mul_f32_e32 v82, v81, v81
	v_fmac_f32_e32 v73, v74, v74
	v_fmac_f32_e32 v82, v80, v80
	v_add_f32_e32 v73, v73, v82
	v_add_f32_e32 v84, v72, v73
	v_cvt_pk_bf16_f32 v72, v76, v77
	v_cvt_pk_bf16_f32 v73, v78, v79
	v_lshlrev_b32_e32 v76, 16, v160
	v_and_b32_e32 v77, 0xffff0000, v160
	v_lshlrev_b32_e32 v78, 16, v161
	v_and_b32_e32 v79, 0xffff0000, v161
	v_cvt_pk_bf16_f32 v74, v74, v75
	v_cvt_pk_bf16_f32 v75, v80, v81
	v_lshlrev_b32_e32 v80, 16, v162
	v_and_b32_e32 v81, 0xffff0000, v162
	v_pk_add_f32 v[70:71], v[70:71], v[78:79]
	v_pk_add_f32 v[68:69], v[68:69], v[76:77]
	v_lshlrev_b32_e32 v82, 16, v163
	v_and_b32_e32 v83, 0xffff0000, v163
	v_pk_add_f32 v[78:79], v[64:65], v[80:81]
	v_mul_f32_e32 v64, v69, v69
	v_mul_f32_e32 v65, v71, v71
	v_pk_add_f32 v[76:77], v[66:67], v[82:83]
	v_fmac_f32_e32 v64, v68, v68
	v_fmac_f32_e32 v65, v70, v70
	v_add_f32_e32 v64, v64, v65
	v_mul_f32_e32 v65, v79, v79
	v_mul_f32_e32 v66, v77, v77
	v_fmac_f32_e32 v65, v78, v78
	v_fmac_f32_e32 v66, v76, v76
	v_add_f32_e32 v65, v65, v66
	v_add_f32_e32 v64, v64, v65
	v_add_f32_e32 v67, v84, v64
	ds_bpermute_b32 v82, v112, v67
	v_lshl_add_u64 v[64:65], s[10:11], 0, v[224:225]
	v_lshl_add_u64 v[80:81], v[214:215], 1, v[64:65]
	global_store_dwordx4 v[80:81], v[72:75], off sc1
	v_cvt_pk_bf16_f32 v66, v68, v69
	s_waitcnt lgkmcnt(0)
	v_add_f32_e32 v64, v67, v82
	ds_bpermute_b32 v65, v113, v64
	v_cvt_pk_bf16_f32 v67, v70, v71
	v_cvt_pk_bf16_f32 v68, v78, v79
	v_cvt_pk_bf16_f32 v69, v76, v77
	global_store_dwordx4 v[80:81], v[66:69], off offset:256 sc1
	s_and_saveexec_b64 s[0:1], vcc
	s_cbranch_execz .LBB0_525
	v_lshlrev_b64 v[66:67], 6, v[222:223]
	v_lshl_add_u64 v[66:67], s[12:13], 0, v[66:67]
	v_lshl_add_u64 v[66:67], s[26:27], 2, v[66:67]
	s_lshl_b32 s72, s17, 2
	v_lshl_add_u64 v[66:67], v[66:67], 0, s[72:73]
	s_waitcnt lgkmcnt(0)
	v_add_f32_e32 v64, v64, v65
	global_store_dword v[66:67], v64, off
.LBB0_525:
	s_or_b64 exec, exec, s[0:1]
	s_waitcnt vmcnt(18)
	v_lshlrev_b32_e32 v64, 16, v156
	s_waitcnt lgkmcnt(0)
	v_and_b32_e32 v65, 0xffff0000, v156
	v_lshlrev_b32_e32 v66, 16, v157
	v_and_b32_e32 v67, 0xffff0000, v157
	v_lshlrev_b32_e32 v68, 16, v158
	v_and_b32_e32 v69, 0xffff0000, v158
	v_lshlrev_b32_e32 v70, 16, v159
	v_and_b32_e32 v71, 0xffff0000, v159
	v_pk_add_f32 v[62:63], v[62:63], v[66:67]
	v_pk_add_f32 v[60:61], v[60:61], v[64:65]
	v_pk_add_f32 v[64:65], v[58:59], v[70:71]
	v_pk_add_f32 v[58:59], v[56:57], v[68:69]
	v_mul_f32_e32 v56, v61, v61
	v_mul_f32_e32 v57, v63, v63
	v_fmac_f32_e32 v56, v60, v60
	v_fmac_f32_e32 v57, v62, v62
	v_add_f32_e32 v56, v56, v57
	v_mul_f32_e32 v57, v59, v59
	v_mul_f32_e32 v66, v65, v65
	v_fmac_f32_e32 v57, v58, v58
	v_fmac_f32_e32 v66, v64, v64
	v_add_f32_e32 v57, v57, v66
	v_add_f32_e32 v68, v56, v57
	v_cvt_pk_bf16_f32 v56, v60, v61
	v_cvt_pk_bf16_f32 v57, v62, v63
	v_lshlrev_b32_e32 v60, 16, v144
	v_and_b32_e32 v61, 0xffff0000, v144
	v_lshlrev_b32_e32 v62, 16, v145
	v_and_b32_e32 v63, 0xffff0000, v145
	v_cvt_pk_bf16_f32 v58, v58, v59
	v_cvt_pk_bf16_f32 v59, v64, v65
	v_lshlrev_b32_e32 v64, 16, v146
	v_and_b32_e32 v65, 0xffff0000, v146
	v_pk_add_f32 v[54:55], v[54:55], v[62:63]
	v_pk_add_f32 v[52:53], v[52:53], v[60:61]
	v_lshlrev_b32_e32 v66, 16, v147
	v_and_b32_e32 v67, 0xffff0000, v147
	v_pk_add_f32 v[62:63], v[48:49], v[64:65]
	v_mul_f32_e32 v48, v53, v53
	v_mul_f32_e32 v49, v55, v55
	v_pk_add_f32 v[60:61], v[50:51], v[66:67]
	v_fmac_f32_e32 v48, v52, v52
	v_fmac_f32_e32 v49, v54, v54
	v_add_f32_e32 v48, v48, v49
	v_mul_f32_e32 v49, v63, v63
	v_mul_f32_e32 v50, v61, v61
	v_fmac_f32_e32 v49, v62, v62
	v_fmac_f32_e32 v50, v60, v60
	v_add_f32_e32 v49, v49, v50
	v_add_f32_e32 v48, v48, v49
	v_add_f32_e32 v51, v68, v48
	ds_bpermute_b32 v66, v112, v51
	v_lshl_add_u64 v[48:49], s[10:11], 0, v[220:221]
	v_lshl_add_u64 v[64:65], v[214:215], 1, v[48:49]
	global_store_dwordx4 v[64:65], v[56:59], off sc1
	v_cvt_pk_bf16_f32 v50, v52, v53
	s_waitcnt lgkmcnt(0)
	v_add_f32_e32 v48, v51, v66
	ds_bpermute_b32 v49, v113, v48
	v_cvt_pk_bf16_f32 v51, v54, v55
	v_cvt_pk_bf16_f32 v52, v62, v63
	v_cvt_pk_bf16_f32 v53, v60, v61
	global_store_dwordx4 v[64:65], v[50:53], off offset:256 sc1
	s_and_saveexec_b64 s[0:1], vcc
	s_cbranch_execz .LBB0_527
	v_lshlrev_b64 v[50:51], 6, v[218:219]
	v_lshl_add_u64 v[50:51], s[12:13], 0, v[50:51]
	v_lshl_add_u64 v[50:51], s[26:27], 2, v[50:51]
	s_lshl_b32 s72, s17, 2
	v_lshl_add_u64 v[50:51], v[50:51], 0, s[72:73]
	s_waitcnt lgkmcnt(0)
	v_add_f32_e32 v48, v48, v49
	global_store_dword v[50:51], v48, off
; __device__ __forceinline__ u32x4 pack8(const f32x4 v0, const f32x4 v1) { u32x4 w; w.x = cvt_pk_bf16(v0[0], v0[1]); w.y = cvt_pk_bf16(v0[2], v0[3]); w.z = cvt_pk_bf16(v1[0], v1[1]); w.w = cvt_pk_bf16(v1[2], v1[3]); return w; }
; __device__ __forceinline__ float sumsq8(const f32x4 a, const f32x4 b) { return ((a[0] * a[0] + a[1] * a[1]) + (a[2] * a[2] + a[3] * a[3])) + ((b[0] * b[0] + b[1] * b[1]) + (b[2] * b[2] + b[3] * b[3])); }
; __device__ __forceinline__ void unpack8(const u32x4 w, f32x4& a, f32x4& b) { a = (f32x4){bf_lo(w.x), bf_hi(w.x), bf_lo(w.y), bf_hi(w.y)}; b = (f32x4){bf_lo(w.z), bf_hi(w.z), bf_lo(w.w), bf_hi(w.w)}; }
;     __device__ __forceinline__ void operator()(const f32x4 (&acc)[2][2][4][2], const Unit& u, int wr, int wc, int fr, int fq) const {
;     ...
; #pragma unroll
;         for (int ai = 0; ai < 2; ++ai)
; #pragma unroll
;             for (int m = 0; m < 4; ++m) { const int row = row0 + ai * HALF + m * 16; float part = 0.f;
; #pragma unroll
;                 for (int bj = 0; bj < 2; ++bj) { f32x4 r0, r1; unpack8(rv[ai * 4 + m][bj], r0, r1);
;                     const f32x4 h0 = r0 + acc[ai][bj][m][0], h1 = r1 + acc[ai][bj][m][1]; part += sumsq8(h0, h1);
;                     *(u32x4*)(XBo + (size_t)row * DMODEL + col0 + bj * HALF) = pack8(h0, h1); }
;                 part += __shfl_xor(part, 16); part += __shfl_xor(part, 32);
;                 if (fq == 0) ssq[(size_t)row * 16 + u.pn * 4 + wc] = part; }
.LBB0_527:
	s_or_b64 exec, exec, s[0:1]
	s_waitcnt vmcnt(19)
	v_lshlrev_b32_e32 v52, 16, v140
	v_and_b32_e32 v53, 0xffff0000, v140
	v_lshlrev_b32_e32 v54, 16, v141
	v_and_b32_e32 v55, 0xffff0000, v141
	v_lshlrev_b32_e32 v56, 16, v142
	v_and_b32_e32 v57, 0xffff0000, v142
	v_lshlrev_b32_e32 v58, 16, v143
	v_and_b32_e32 v59, 0xffff0000, v143
	v_pk_add_f32 v[46:47], v[46:47], v[54:55]
	v_pk_add_f32 v[44:45], v[44:45], v[52:53]
	v_pk_add_f32 v[52:53], v[42:43], v[58:59]
	v_pk_add_f32 v[42:43], v[40:41], v[56:57]
	v_mul_f32_e32 v40, v45, v45
	v_mul_f32_e32 v41, v47, v47
	v_fmac_f32_e32 v40, v44, v44
	v_fmac_f32_e32 v41, v46, v46
	v_add_f32_e32 v40, v40, v41
	v_mul_f32_e32 v41, v43, v43
	v_mul_f32_e32 v54, v53, v53
	v_fmac_f32_e32 v41, v42, v42
	v_fmac_f32_e32 v54, v52, v52
	v_add_f32_e32 v41, v41, v54
	v_add_f32_e32 v56, v40, v41
	v_cvt_pk_bf16_f32 v40, v44, v45
	v_cvt_pk_bf16_f32 v41, v46, v47
	v_lshlrev_b32_e32 v44, 16, v136
	v_and_b32_e32 v45, 0xffff0000, v136
	v_lshlrev_b32_e32 v46, 16, v137
	v_and_b32_e32 v47, 0xffff0000, v137
	v_cvt_pk_bf16_f32 v42, v42, v43
	v_cvt_pk_bf16_f32 v43, v52, v53
	v_lshlrev_b32_e32 v52, 16, v138
	v_and_b32_e32 v53, 0xffff0000, v138
	v_pk_add_f32 v[38:39], v[38:39], v[46:47]
	v_pk_add_f32 v[36:37], v[36:37], v[44:45]
	v_lshlrev_b32_e32 v54, 16, v139
	v_and_b32_e32 v55, 0xffff0000, v139
	v_pk_add_f32 v[46:47], v[32:33], v[52:53]
	v_mul_f32_e32 v32, v37, v37
	v_mul_f32_e32 v33, v39, v39
	v_pk_add_f32 v[44:45], v[34:35], v[54:55]
	v_fmac_f32_e32 v32, v36, v36
	v_fmac_f32_e32 v33, v38, v38
	v_add_f32_e32 v32, v32, v33
	v_mul_f32_e32 v33, v47, v47
	v_mul_f32_e32 v34, v45, v45
	v_fmac_f32_e32 v33, v46, v46
	v_fmac_f32_e32 v34, v44, v44
	v_add_f32_e32 v33, v33, v34
	v_add_f32_e32 v32, v32, v33
	v_add_f32_e32 v35, v56, v32
	ds_bpermute_b32 v52, v112, v35
	v_add_u32_e32 v48, 0x90, v216
	s_waitcnt lgkmcnt(1)
	v_ashrrev_i32_e32 v49, 31, v48
	v_lshlrev_b64 v[50:51], 11, v[48:49]
	v_lshl_add_u64 v[32:33], s[10:11], 0, v[50:51]
	v_lshl_add_u64 v[50:51], v[214:215], 1, v[32:33]
	s_waitcnt lgkmcnt(0)
	v_add_f32_e32 v32, v35, v52
	ds_bpermute_b32 v33, v113, v32
	global_store_dwordx4 v[50:51], v[40:43], off sc1
	v_cvt_pk_bf16_f32 v34, v36, v37
	v_cvt_pk_bf16_f32 v35, v38, v39
	v_cvt_pk_bf16_f32 v36, v46, v47
	v_cvt_pk_bf16_f32 v37, v44, v45
	global_store_dwordx4 v[50:51], v[34:37], off offset:256 sc1
	s_and_saveexec_b64 s[0:1], vcc
	s_cbranch_execz .LBB0_529
	v_lshlrev_b64 v[34:35], 6, v[48:49]
	v_lshl_add_u64 v[34:35], s[12:13], 0, v[34:35]
	v_lshl_add_u64 v[34:35], s[26:27], 2, v[34:35]
	s_lshl_b32 s72, s17, 2
	v_lshl_add_u64 v[34:35], v[34:35], 0, s[72:73]
	s_waitcnt lgkmcnt(0)
	v_add_f32_e32 v32, v32, v33
	global_store_dword v[34:35], v32, off
; __device__ __forceinline__ u32x4 pack8(const f32x4 v0, const f32x4 v1) { u32x4 w; w.x = cvt_pk_bf16(v0[0], v0[1]); w.y = cvt_pk_bf16(v0[2], v0[3]); w.z = cvt_pk_bf16(v1[0], v1[1]); w.w = cvt_pk_bf16(v1[2], v1[3]); return w; }
; __device__ __forceinline__ float sumsq8(const f32x4 a, const f32x4 b) { return ((a[0] * a[0] + a[1] * a[1]) + (a[2] * a[2] + a[3] * a[3])) + ((b[0] * b[0] + b[1] * b[1]) + (b[2] * b[2] + b[3] * b[3])); }
; __device__ __forceinline__ void unpack8(const u32x4 w, f32x4& a, f32x4& b) { a = (f32x4){bf_lo(w.x), bf_hi(w.x), bf_lo(w.y), bf_hi(w.y)}; b = (f32x4){bf_lo(w.z), bf_hi(w.z), bf_lo(w.w), bf_hi(w.w)}; }
;     __device__ __forceinline__ void operator()(const f32x4 (&acc)[2][2][4][2], const Unit& u, int wr, int wc, int fr, int fq) const {
;     ...
; #pragma unroll
;         for (int ai = 0; ai < 2; ++ai)
; #pragma unroll
;             for (int m = 0; m < 4; ++m) { const int row = row0 + ai * HALF + m * 16; float part = 0.f;
; #pragma unroll
;                 for (int bj = 0; bj < 2; ++bj) { f32x4 r0, r1; unpack8(rv[ai * 4 + m][bj], r0, r1);
;                     const f32x4 h0 = r0 + acc[ai][bj][m][0], h1 = r1 + acc[ai][bj][m][1]; part += sumsq8(h0, h1);
;                     *(u32x4*)(XBo + (size_t)row * DMODEL + col0 + bj * HALF) = pack8(h0, h1); }
;                 part += __shfl_xor(part, 16); part += __shfl_xor(part, 32);
;                 if (fq == 0) ssq[(size_t)row * 16 + u.pn * 4 + wc] = part; }
.LBB0_529:
	s_or_b64 exec, exec, s[0:1]
	s_waitcnt vmcnt(20)
	v_lshlrev_b32_e32 v36, 16, v128
	v_and_b32_e32 v37, 0xffff0000, v128
	v_lshlrev_b32_e32 v38, 16, v129
	v_and_b32_e32 v39, 0xffff0000, v129
	v_lshlrev_b32_e32 v40, 16, v130
	v_and_b32_e32 v41, 0xffff0000, v130
	v_lshlrev_b32_e32 v42, 16, v131
	v_and_b32_e32 v43, 0xffff0000, v131
	v_pk_add_f32 v[30:31], v[30:31], v[38:39]
	v_pk_add_f32 v[28:29], v[28:29], v[36:37]
	v_pk_add_f32 v[36:37], v[26:27], v[42:43]
	v_pk_add_f32 v[26:27], v[24:25], v[40:41]
	v_mul_f32_e32 v24, v29, v29
	v_mul_f32_e32 v25, v31, v31
	v_fmac_f32_e32 v24, v28, v28
	v_fmac_f32_e32 v25, v30, v30
	v_add_f32_e32 v24, v24, v25
	v_mul_f32_e32 v25, v27, v27
	v_mul_f32_e32 v38, v37, v37
	v_fmac_f32_e32 v25, v26, v26
	v_fmac_f32_e32 v38, v36, v36
	v_add_f32_e32 v25, v25, v38
	v_add_f32_e32 v40, v24, v25
	v_cvt_pk_bf16_f32 v24, v28, v29
	v_cvt_pk_bf16_f32 v25, v30, v31
	v_lshlrev_b32_e32 v28, 16, v116
	v_and_b32_e32 v29, 0xffff0000, v116
	v_lshlrev_b32_e32 v30, 16, v117
	v_and_b32_e32 v31, 0xffff0000, v117
	v_cvt_pk_bf16_f32 v26, v26, v27
	v_cvt_pk_bf16_f32 v27, v36, v37
	v_lshlrev_b32_e32 v36, 16, v118
	v_and_b32_e32 v37, 0xffff0000, v118
	v_pk_add_f32 v[22:23], v[22:23], v[30:31]
	v_pk_add_f32 v[20:21], v[20:21], v[28:29]
	v_lshlrev_b32_e32 v38, 16, v119
	v_and_b32_e32 v39, 0xffff0000, v119
	v_pk_add_f32 v[30:31], v[16:17], v[36:37]
	v_mul_f32_e32 v16, v21, v21
	v_mul_f32_e32 v17, v23, v23
	v_pk_add_f32 v[28:29], v[18:19], v[38:39]
	v_fmac_f32_e32 v16, v20, v20
	v_fmac_f32_e32 v17, v22, v22
	v_add_f32_e32 v16, v16, v17
	v_mul_f32_e32 v17, v31, v31
	v_mul_f32_e32 v18, v29, v29
	v_fmac_f32_e32 v17, v30, v30
	v_fmac_f32_e32 v18, v28, v28
	v_add_f32_e32 v17, v17, v18
	v_add_f32_e32 v16, v16, v17
	v_add_f32_e32 v19, v40, v16
	ds_bpermute_b32 v36, v112, v19
	v_add_u32_e32 v32, 0xa0, v216
	s_waitcnt lgkmcnt(1)
	v_ashrrev_i32_e32 v33, 31, v32
	v_lshlrev_b64 v[34:35], 11, v[32:33]
	v_lshl_add_u64 v[16:17], s[10:11], 0, v[34:35]
	v_lshl_add_u64 v[34:35], v[214:215], 1, v[16:17]
	s_waitcnt lgkmcnt(0)
	v_add_f32_e32 v16, v19, v36
	ds_bpermute_b32 v17, v113, v16
	global_store_dwordx4 v[34:35], v[24:27], off sc1
	v_cvt_pk_bf16_f32 v18, v20, v21
	v_cvt_pk_bf16_f32 v19, v22, v23
	v_cvt_pk_bf16_f32 v20, v30, v31
	v_cvt_pk_bf16_f32 v21, v28, v29
	global_store_dwordx4 v[34:35], v[18:21], off offset:256 sc1
	s_and_saveexec_b64 s[0:1], vcc
	s_cbranch_execz .LBB0_531
	v_lshlrev_b64 v[18:19], 6, v[32:33]
	v_lshl_add_u64 v[18:19], s[12:13], 0, v[18:19]
	v_lshl_add_u64 v[18:19], s[26:27], 2, v[18:19]
	s_lshl_b32 s72, s17, 2
	v_lshl_add_u64 v[18:19], v[18:19], 0, s[72:73]
	s_waitcnt lgkmcnt(0)
	v_add_f32_e32 v16, v16, v17
	global_store_dword v[18:19], v16, off
.LBB0_531:
	s_or_b64 exec, exec, s[0:1]
	s_waitcnt vmcnt(21)
	v_lshlrev_b32_e32 v20, 16, v132
	v_and_b32_e32 v21, 0xffff0000, v132
	v_lshlrev_b32_e32 v22, 16, v133
	v_and_b32_e32 v23, 0xffff0000, v133
	v_lshlrev_b32_e32 v24, 16, v134
	v_and_b32_e32 v25, 0xffff0000, v134
	v_lshlrev_b32_e32 v26, 16, v135
	v_and_b32_e32 v27, 0xffff0000, v135
	v_pk_add_f32 v[14:15], v[14:15], v[22:23]
	v_pk_add_f32 v[12:13], v[12:13], v[20:21]
	v_pk_add_f32 v[20:21], v[10:11], v[26:27]
	v_pk_add_f32 v[10:11], v[8:9], v[24:25]
	v_mul_f32_e32 v8, v13, v13
	v_mul_f32_e32 v9, v15, v15
	v_fmac_f32_e32 v8, v12, v12
	v_fmac_f32_e32 v9, v14, v14
	v_add_f32_e32 v8, v8, v9
	v_mul_f32_e32 v9, v11, v11
	v_mul_f32_e32 v22, v21, v21
	v_fmac_f32_e32 v9, v10, v10
	v_fmac_f32_e32 v22, v20, v20
	v_add_f32_e32 v9, v9, v22
	v_add_f32_e32 v24, v8, v9
	v_cvt_pk_bf16_f32 v8, v12, v13
	v_cvt_pk_bf16_f32 v9, v14, v15
	v_lshlrev_b32_e32 v12, 16, v120
	v_and_b32_e32 v13, 0xffff0000, v120
	v_lshlrev_b32_e32 v14, 16, v121
	v_and_b32_e32 v15, 0xffff0000, v121
	v_cvt_pk_bf16_f32 v10, v10, v11
	v_cvt_pk_bf16_f32 v11, v20, v21
	v_lshlrev_b32_e32 v20, 16, v122
	v_and_b32_e32 v21, 0xffff0000, v122
	v_pk_add_f32 v[6:7], v[6:7], v[14:15]
	v_pk_add_f32 v[4:5], v[4:5], v[12:13]
	v_lshlrev_b32_e32 v22, 16, v123
	v_and_b32_e32 v23, 0xffff0000, v123
	v_pk_add_f32 v[14:15], v[0:1], v[20:21]
	v_mul_f32_e32 v0, v5, v5
	v_mul_f32_e32 v1, v7, v7
	v_pk_add_f32 v[12:13], v[2:3], v[22:23]
	v_fmac_f32_e32 v0, v4, v4
	v_fmac_f32_e32 v1, v6, v6
	v_add_f32_e32 v0, v0, v1
	v_mul_f32_e32 v1, v15, v15
	v_mul_f32_e32 v2, v13, v13
	v_fmac_f32_e32 v1, v14, v14
	v_fmac_f32_e32 v2, v12, v12
	v_add_f32_e32 v1, v1, v2
	v_add_f32_e32 v0, v0, v1
	v_add_f32_e32 v3, v24, v0
	ds_bpermute_b32 v20, v112, v3
	v_add_u32_e32 v16, 0xb0, v216
	s_waitcnt lgkmcnt(1)
	v_ashrrev_i32_e32 v17, 31, v16
	v_lshlrev_b64 v[18:19], 11, v[16:17]
	v_lshl_add_u64 v[0:1], s[10:11], 0, v[18:19]
	v_lshl_add_u64 v[18:19], v[214:215], 1, v[0:1]
	s_waitcnt lgkmcnt(0)
	v_add_f32_e32 v0, v3, v20
	ds_bpermute_b32 v1, v113, v0
	global_store_dwordx4 v[18:19], v[8:11], off sc1
	v_cvt_pk_bf16_f32 v2, v4, v5
	v_cvt_pk_bf16_f32 v3, v6, v7
	v_cvt_pk_bf16_f32 v4, v14, v15
	v_cvt_pk_bf16_f32 v5, v12, v13
	global_store_dwordx4 v[18:19], v[2:5], off offset:256 sc1
	s_and_saveexec_b64 s[0:1], vcc
	s_cbranch_execz .LBB0_533
	v_lshlrev_b64 v[2:3], 6, v[16:17]
	v_lshl_add_u64 v[2:3], s[12:13], 0, v[2:3]
	v_lshl_add_u64 v[2:3], s[26:27], 2, v[2:3]
	s_lshl_b32 s72, s17, 2
	v_lshl_add_u64 v[2:3], v[2:3], 0, s[72:73]
	s_waitcnt lgkmcnt(0)
	v_add_f32_e32 v0, v0, v1
	global_store_dword v[2:3], v0, off

; __device__ __forceinline__ u32x4 pack8(const f32x4 v0, const f32x4 v1) { u32x4 w; w.x = cvt_pk_bf16(v0[0], v0[1]); w.y = cvt_pk_bf16(v0[2], v0[3]); w.z = cvt_pk_bf16(v1[0], v1[1]); w.w = cvt_pk_bf16(v1[2], v1[3]); return w; }
; __device__ __forceinline__ float sumsq8(const f32x4 a, const f32x4 b) { return ((a[0] * a[0] + a[1] * a[1]) + (a[2] * a[2] + a[3] * a[3])) + ((b[0] * b[0] + b[1] * b[1]) + (b[2] * b[2] + b[3] * b[3])); }
; __device__ __forceinline__ void unpack8(const u32x4 w, f32x4& a, f32x4& b) { a = (f32x4){bf_lo(w.x), bf_hi(w.x), bf_lo(w.y), bf_hi(w.y)}; b = (f32x4){bf_lo(w.z), bf_hi(w.z), bf_lo(w.w), bf_hi(w.w)}; }
;     __device__ __forceinline__ void operator()(const f32x4 (&acc)[2][2][4][2], const Unit& u, int wr, int wc, int fr, int fq) const {
;         const int row0 = u.pm * BM + wr * 64 + fr, col0 = u.pn * BM + wc * 32 + 8 * fq;
;         u32x4 rv[8][2];
; #pragma unroll
;         for (int i = 0; i < 8; ++i)
; #pragma unroll
;             for (int bj = 0; bj < 2; ++bj) rv[i][bj] = *(const u32x4*)(Rin + (size_t)(row0 + (i >> 2) * HALF + (i & 3) * 16) * DMODEL + col0 + bj * HALF);
; #pragma unroll
;         for (int ai = 0; ai < 2; ++ai)
; #pragma unroll
;             for (int m = 0; m < 4; ++m) { const int row = row0 + ai * HALF + m * 16; float part = 0.f;
; #pragma unroll
;                 for (int bj = 0; bj < 2; ++bj) { f32x4 r0, r1; unpack8(rv[ai * 4 + m][bj], r0, r1);
;                     const f32x4 h0 = r0 + acc[ai][bj][m][0], h1 = r1 + acc[ai][bj][m][1]; part += sumsq8(h0, h1);
;                     *(u32x4*)(XBo + (size_t)row * DMODEL + col0 + bj * HALF) = pack8(h0, h1); }
;                 part += __shfl_xor(part, 16); part += __shfl_xor(part, 32);
;                 if (fq == 0) ssq[(size_t)row * 16 + u.pn * 4 + wc] = part; }
.LBB0_968:
	v_mov_b32_e32 v116, v192
	s_lshl_b32 s1, s24, 8
	v_readfirstlane_b32 s0, v116
	s_bfe_u32 s13, s0, 0x20006
	s_ashr_i32 s0, s0, 2
	s_andn2_b32 s0, s0, 63
	s_add_i32 s0, s0, s1
	v_and_or_b32 v216, v116, 15, s0
	s_lshl_b32 s0, s22, 8
	s_lshl_b32 s1, s13, 5
	v_bfe_u32 v249, v116, 4, 2
	s_or_b32 s0, s1, s0
	v_lshl_or_b32 v214, v249, 3, s0
	v_ashrrev_i32_e32 v215, 31, v214
	v_lshlrev_b64 v[234:235], 1, v[214:215]
	v_ashrrev_i32_e32 v217, 31, v216
	v_lshl_add_u64 v[120:121], s[6:7], 0, v[234:235]
	v_lshlrev_b64 v[236:237], 11, v[216:217]
	v_lshl_add_u64 v[116:117], v[120:121], 0, v[236:237]
	global_load_dwordx4 v[188:191], v[116:117], off
	global_load_dwordx4 v[184:187], v[116:117], off offset:256
	v_or_b32_e32 v230, 16, v216
	v_ashrrev_i32_e32 v231, 31, v230
	v_or_b32_e32 v226, 32, v216
	v_lshlrev_b64 v[232:233], 11, v[230:231]
	v_ashrrev_i32_e32 v227, 31, v226
	v_or_b32_e32 v222, 48, v216
	v_lshl_add_u64 v[116:117], v[120:121], 0, v[232:233]
	v_lshlrev_b64 v[228:229], 11, v[226:227]
	v_ashrrev_i32_e32 v223, 31, v222
	v_add_u32_e32 v218, 0x80, v216
	global_load_dwordx4 v[180:183], v[116:117], off
	global_load_dwordx4 v[176:179], v[116:117], off offset:256
	v_lshl_add_u64 v[116:117], v[120:121], 0, v[228:229]
	v_lshlrev_b64 v[224:225], 11, v[222:223]
	v_ashrrev_i32_e32 v219, 31, v218
	global_load_dwordx4 v[172:175], v[116:117], off
	global_load_dwordx4 v[168:171], v[116:117], off offset:256
	v_lshl_add_u64 v[116:117], v[120:121], 0, v[224:225]
	v_lshlrev_b64 v[220:221], 11, v[218:219]
	global_load_dwordx4 v[164:167], v[116:117], off
	global_load_dwordx4 v[160:163], v[116:117], off offset:256
	v_lshl_add_u64 v[116:117], v[120:121], 0, v[220:221]
	global_load_dwordx4 v[156:159], v[116:117], off
	global_load_dwordx4 v[144:147], v[116:117], off offset:256
	v_add_u32_e32 v116, 0x90, v216
	v_ashrrev_i32_e32 v117, 31, v116
	v_lshlrev_b64 v[116:117], 11, v[116:117]
	v_lshl_add_u64 v[116:117], v[120:121], 0, v[116:117]
	global_load_dwordx4 v[140:143], v[116:117], off
	global_load_dwordx4 v[136:139], v[116:117], off offset:256
	v_add_u32_e32 v116, 0xa0, v216
	v_add_u32_e32 v122, 0xb0, v216
	v_ashrrev_i32_e32 v117, 31, v116
	v_ashrrev_i32_e32 v123, 31, v122
	v_lshlrev_b64 v[116:117], 11, v[116:117]
	v_lshlrev_b64 v[122:123], 11, v[122:123]
	v_lshl_add_u64 v[116:117], v[120:121], 0, v[116:117]
	v_lshl_add_u64 v[120:121], v[120:121], 0, v[122:123]
	global_load_dwordx4 v[128:131], v[116:117], off
	s_nop 0
	global_load_dwordx4 v[116:119], v[116:117], off offset:256
	s_nop 0
	global_load_dwordx4 v[132:135], v[120:121], off
	s_nop 0
	global_load_dwordx4 v[120:123], v[120:121], off offset:256
	s_lshl_b32 s22, s22, 2
	v_cmp_eq_u32_e32 vcc, 0, v249
	s_ashr_i32 s23, s22, 31
	s_waitcnt vmcnt(14)
	v_lshlrev_b32_e32 v250, 16, v188
	v_and_b32_e32 v251, 0xffff0000, v188
	v_lshlrev_b32_e32 v188, 16, v189
	v_and_b32_e32 v189, 0xffff0000, v189
	v_lshlrev_b32_e32 v252, 16, v190
	v_and_b32_e32 v253, 0xffff0000, v190
	v_lshlrev_b32_e32 v190, 16, v191
	v_and_b32_e32 v191, 0xffff0000, v191
	v_pk_add_f32 v[154:155], v[154:155], v[188:189]
	v_pk_add_f32 v[152:153], v[152:153], v[250:251]
	v_pk_add_f32 v[188:189], v[150:151], v[190:191]
	v_pk_add_f32 v[150:151], v[148:149], v[252:253]
	v_mul_f32_e32 v148, v153, v153
	v_mul_f32_e32 v149, v155, v155
	v_fmac_f32_e32 v148, v152, v152
	v_fmac_f32_e32 v149, v154, v154
	v_add_f32_e32 v148, v148, v149
	v_mul_f32_e32 v149, v151, v151
	v_mul_f32_e32 v190, v189, v189
	v_fmac_f32_e32 v149, v150, v150
	v_fmac_f32_e32 v190, v188, v188
	v_add_f32_e32 v149, v149, v190
	v_add_f32_e32 v190, v148, v149
	v_cvt_pk_bf16_f32 v148, v152, v153
	v_lshl_add_u64 v[152:153], s[6:7], 0, v[236:237]
	v_cvt_pk_bf16_f32 v149, v154, v155
	v_cvt_pk_bf16_f32 v150, v150, v151
	v_cvt_pk_bf16_f32 v151, v188, v189
	v_lshl_add_u64 v[152:153], v[152:153], 0, v[234:235]
	global_store_dwordx4 v[152:153], v[148:151], off sc1
	v_lshlrev_b32_e32 v154, 16, v186
	v_and_b32_e32 v155, 0xffff0000, v186
	v_lshlrev_b32_e32 v148, 16, v184
	v_and_b32_e32 v149, 0xffff0000, v184
	v_lshlrev_b32_e32 v150, 16, v185
	v_and_b32_e32 v151, 0xffff0000, v185
	v_lshlrev_b32_e32 v184, 16, v187
	v_and_b32_e32 v185, 0xffff0000, v187
	v_pk_add_f32 v[126:127], v[126:127], v[150:151]
	v_pk_add_f32 v[124:125], v[124:125], v[148:149]
	v_pk_add_f32 v[148:149], v[114:115], v[184:185]
	v_pk_add_f32 v[114:115], v[112:113], v[154:155]
	v_mul_f32_e32 v112, v125, v125
	v_mul_f32_e32 v113, v127, v127
	v_fmac_f32_e32 v112, v124, v124
	v_fmac_f32_e32 v113, v126, v126
	v_add_f32_e32 v112, v112, v113
	v_mul_f32_e32 v113, v115, v115
	v_mul_f32_e32 v150, v149, v149
	v_fmac_f32_e32 v113, v114, v114
	v_fmac_f32_e32 v150, v148, v148
	v_add_f32_e32 v113, v113, v150
	v_add_f32_e32 v112, v112, v113
	v_add_f32_e32 v150, v190, v112
	v_cvt_pk_bf16_f32 v112, v124, v125
	v_cvt_pk_bf16_f32 v113, v126, v127
	v_cvt_pk_bf16_f32 v114, v114, v115
	v_cvt_pk_bf16_f32 v115, v148, v149
	global_store_dwordx4 v[152:153], v[112:115], off offset:256 sc1
	s_nop 1
	v_and_b32_e32 v113, 64, v241
	v_xor_b32_e32 v112, 16, v241
	v_add_u32_e32 v113, 64, v113
	v_cmp_lt_i32_e64 s[0:1], v112, v113
	v_xor_b32_e32 v115, 32, v241
	s_nop 0
	v_cndmask_b32_e64 v112, v241, v112, s[0:1]
	v_lshlrev_b32_e32 v112, 2, v112
	ds_bpermute_b32 v114, v112, v150
	v_cmp_lt_i32_e64 s[0:1], v115, v113
	s_waitcnt lgkmcnt(0)
	v_add_f32_e32 v114, v150, v114
	v_cndmask_b32_e64 v113, v241, v115, s[0:1]
	v_lshlrev_b32_e32 v113, 2, v113
	ds_bpermute_b32 v115, v113, v114
	s_and_saveexec_b64 s[0:1], vcc
	s_cbranch_execz .LBB0_970
	v_lshlrev_b64 v[124:125], 6, v[216:217]
	v_lshl_add_u64 v[124:125], s[8:9], 0, v[124:125]
	v_lshl_add_u64 v[124:125], s[22:23], 2, v[124:125]
	s_lshl_b32 s72, s13, 2
	v_lshl_add_u64 v[124:125], v[124:125], 0, s[72:73]
	s_waitcnt lgkmcnt(0)
	v_add_f32_e32 v114, v114, v115
	global_store_dword v[124:125], v114, off
; __device__ __forceinline__ u32x4 pack8(const f32x4 v0, const f32x4 v1) { u32x4 w; w.x = cvt_pk_bf16(v0[0], v0[1]); w.y = cvt_pk_bf16(v0[2], v0[3]); w.z = cvt_pk_bf16(v1[0], v1[1]); w.w = cvt_pk_bf16(v1[2], v1[3]); return w; }
; __device__ __forceinline__ float sumsq8(const f32x4 a, const f32x4 b) { return ((a[0] * a[0] + a[1] * a[1]) + (a[2] * a[2] + a[3] * a[3])) + ((b[0] * b[0] + b[1] * b[1]) + (b[2] * b[2] + b[3] * b[3])); }
; __device__ __forceinline__ void unpack8(const u32x4 w, f32x4& a, f32x4& b) { a = (f32x4){bf_lo(w.x), bf_hi(w.x), bf_lo(w.y), bf_hi(w.y)}; b = (f32x4){bf_lo(w.z), bf_hi(w.z), bf_lo(w.w), bf_hi(w.w)}; }
;     __device__ __forceinline__ void operator()(const f32x4 (&acc)[2][2][4][2], const Unit& u, int wr, int wc, int fr, int fq) const {
;     ...
; #pragma unroll
;         for (int ai = 0; ai < 2; ++ai)
; #pragma unroll
;             for (int m = 0; m < 4; ++m) { const int row = row0 + ai * HALF + m * 16; float part = 0.f;
; #pragma unroll
;                 for (int bj = 0; bj < 2; ++bj) { f32x4 r0, r1; unpack8(rv[ai * 4 + m][bj], r0, r1);
;                     const f32x4 h0 = r0 + acc[ai][bj][m][0], h1 = r1 + acc[ai][bj][m][1]; part += sumsq8(h0, h1);
;                     *(u32x4*)(XBo + (size_t)row * DMODEL + col0 + bj * HALF) = pack8(h0, h1); }
;                 part += __shfl_xor(part, 16); part += __shfl_xor(part, 32);
;                 if (fq == 0) ssq[(size_t)row * 16 + u.pn * 4 + wc] = part; }
.LBB0_970:
	s_or_b64 exec, exec, s[0:1]
	s_waitcnt vmcnt(15)
	v_lshlrev_b32_e32 v114, 16, v180
	s_waitcnt lgkmcnt(0)
	v_and_b32_e32 v115, 0xffff0000, v180
	v_lshlrev_b32_e32 v124, 16, v181
	v_and_b32_e32 v125, 0xffff0000, v181
	v_lshlrev_b32_e32 v126, 16, v182
	v_and_b32_e32 v127, 0xffff0000, v182
	v_lshlrev_b32_e32 v148, 16, v183
	v_and_b32_e32 v149, 0xffff0000, v183
	v_pk_add_f32 v[110:111], v[110:111], v[124:125]
	v_pk_add_f32 v[108:109], v[108:109], v[114:115]
	v_pk_add_f32 v[114:115], v[106:107], v[148:149]
	v_pk_add_f32 v[106:107], v[104:105], v[126:127]
	v_mul_f32_e32 v104, v109, v109
	v_mul_f32_e32 v105, v111, v111
	v_fmac_f32_e32 v104, v108, v108
	v_fmac_f32_e32 v105, v110, v110
	v_add_f32_e32 v104, v104, v105
	v_mul_f32_e32 v105, v107, v107
	v_mul_f32_e32 v124, v115, v115
	v_fmac_f32_e32 v105, v106, v106
	v_fmac_f32_e32 v124, v114, v114
	v_add_f32_e32 v105, v105, v124
	v_add_f32_e32 v126, v104, v105
	v_cvt_pk_bf16_f32 v104, v108, v109
	v_cvt_pk_bf16_f32 v105, v110, v111
	v_lshlrev_b32_e32 v108, 16, v176
	v_and_b32_e32 v109, 0xffff0000, v176
	v_lshlrev_b32_e32 v110, 16, v177
	v_and_b32_e32 v111, 0xffff0000, v177
	v_cvt_pk_bf16_f32 v106, v106, v107
	v_cvt_pk_bf16_f32 v107, v114, v115
	v_lshlrev_b32_e32 v114, 16, v178
	v_and_b32_e32 v115, 0xffff0000, v178
	v_pk_add_f32 v[102:103], v[102:103], v[110:111]
	v_pk_add_f32 v[100:101], v[100:101], v[108:109]
	v_lshlrev_b32_e32 v124, 16, v179
	v_and_b32_e32 v125, 0xffff0000, v179
	v_pk_add_f32 v[110:111], v[96:97], v[114:115]
	v_mul_f32_e32 v96, v101, v101
	v_mul_f32_e32 v97, v103, v103
	v_pk_add_f32 v[108:109], v[98:99], v[124:125]
	v_fmac_f32_e32 v96, v100, v100
	v_fmac_f32_e32 v97, v102, v102
	v_add_f32_e32 v96, v96, v97
	v_mul_f32_e32 v97, v111, v111
	v_mul_f32_e32 v98, v109, v109
	v_fmac_f32_e32 v97, v110, v110
	v_fmac_f32_e32 v98, v108, v108
	v_add_f32_e32 v97, v97, v98
	v_add_f32_e32 v96, v96, v97
	v_add_f32_e32 v99, v126, v96
	ds_bpermute_b32 v124, v112, v99
	v_lshl_add_u64 v[96:97], s[6:7], 0, v[232:233]
	v_lshl_add_u64 v[114:115], v[214:215], 1, v[96:97]
	global_store_dwordx4 v[114:115], v[104:107], off sc1
	v_cvt_pk_bf16_f32 v98, v100, v101
	s_waitcnt lgkmcnt(0)
	v_add_f32_e32 v96, v99, v124
	ds_bpermute_b32 v97, v113, v96
	v_cvt_pk_bf16_f32 v99, v102, v103
	v_cvt_pk_bf16_f32 v100, v110, v111
	v_cvt_pk_bf16_f32 v101, v108, v109
	global_store_dwordx4 v[114:115], v[98:101], off offset:256 sc1
	s_and_saveexec_b64 s[0:1], vcc
	s_cbranch_execz .LBB0_972
	v_lshlrev_b64 v[98:99], 6, v[230:231]
	v_lshl_add_u64 v[98:99], s[8:9], 0, v[98:99]
	v_lshl_add_u64 v[98:99], s[22:23], 2, v[98:99]
	s_lshl_b32 s72, s13, 2
	v_lshl_add_u64 v[98:99], v[98:99], 0, s[72:73]
	s_waitcnt lgkmcnt(0)
	v_add_f32_e32 v96, v96, v97
	global_store_dword v[98:99], v96, off
.LBB0_972:
	s_or_b64 exec, exec, s[0:1]
	s_waitcnt vmcnt(16)
	v_lshlrev_b32_e32 v96, 16, v172
	s_waitcnt lgkmcnt(0)
	v_and_b32_e32 v97, 0xffff0000, v172
	v_lshlrev_b32_e32 v98, 16, v173
	v_and_b32_e32 v99, 0xffff0000, v173
	v_lshlrev_b32_e32 v100, 16, v174
	v_and_b32_e32 v101, 0xffff0000, v174
	v_lshlrev_b32_e32 v102, 16, v175
	v_and_b32_e32 v103, 0xffff0000, v175
	v_pk_add_f32 v[94:95], v[94:95], v[98:99]
	v_pk_add_f32 v[92:93], v[92:93], v[96:97]
	v_pk_add_f32 v[96:97], v[90:91], v[102:103]
	v_pk_add_f32 v[90:91], v[88:89], v[100:101]
	v_mul_f32_e32 v88, v93, v93
	v_mul_f32_e32 v89, v95, v95
	v_fmac_f32_e32 v88, v92, v92
	v_fmac_f32_e32 v89, v94, v94
	v_add_f32_e32 v88, v88, v89
	v_mul_f32_e32 v89, v91, v91
	v_mul_f32_e32 v98, v97, v97
	v_fmac_f32_e32 v89, v90, v90
	v_fmac_f32_e32 v98, v96, v96
	v_add_f32_e32 v89, v89, v98
	v_add_f32_e32 v100, v88, v89
	v_cvt_pk_bf16_f32 v88, v92, v93
	v_cvt_pk_bf16_f32 v89, v94, v95
	v_lshlrev_b32_e32 v92, 16, v168
	v_and_b32_e32 v93, 0xffff0000, v168
	v_lshlrev_b32_e32 v94, 16, v169
	v_and_b32_e32 v95, 0xffff0000, v169
	v_cvt_pk_bf16_f32 v90, v90, v91
	v_cvt_pk_bf16_f32 v91, v96, v97
	v_lshlrev_b32_e32 v96, 16, v170
	v_and_b32_e32 v97, 0xffff0000, v170
	v_pk_add_f32 v[86:87], v[86:87], v[94:95]
	v_pk_add_f32 v[84:85], v[84:85], v[92:93]
	v_lshlrev_b32_e32 v98, 16, v171
	v_and_b32_e32 v99, 0xffff0000, v171
	v_pk_add_f32 v[94:95], v[80:81], v[96:97]
	v_mul_f32_e32 v80, v85, v85
	v_mul_f32_e32 v81, v87, v87
	v_pk_add_f32 v[92:93], v[82:83], v[98:99]
	v_fmac_f32_e32 v80, v84, v84
	v_fmac_f32_e32 v81, v86, v86
	v_add_f32_e32 v80, v80, v81
	v_mul_f32_e32 v81, v95, v95
	v_mul_f32_e32 v82, v93, v93
	v_fmac_f32_e32 v81, v94, v94
	v_fmac_f32_e32 v82, v92, v92
	v_add_f32_e32 v81, v81, v82
	v_add_f32_e32 v80, v80, v81
	v_add_f32_e32 v83, v100, v80
	ds_bpermute_b32 v98, v112, v83
	v_lshl_add_u64 v[80:81], s[6:7], 0, v[228:229]
	v_lshl_add_u64 v[96:97], v[214:215], 1, v[80:81]
	global_store_dwordx4 v[96:97], v[88:91], off sc1
	v_cvt_pk_bf16_f32 v82, v84, v85
	s_waitcnt lgkmcnt(0)
	v_add_f32_e32 v80, v83, v98
	ds_bpermute_b32 v81, v113, v80
	v_cvt_pk_bf16_f32 v83, v86, v87
	v_cvt_pk_bf16_f32 v84, v94, v95
	v_cvt_pk_bf16_f32 v85, v92, v93
	global_store_dwordx4 v[96:97], v[82:85], off offset:256 sc1
	s_and_saveexec_b64 s[0:1], vcc
	s_cbranch_execz .LBB0_974
	v_lshlrev_b64 v[82:83], 6, v[226:227]
	v_lshl_add_u64 v[82:83], s[8:9], 0, v[82:83]
	v_lshl_add_u64 v[82:83], s[22:23], 2, v[82:83]
	s_lshl_b32 s72, s13, 2
	v_lshl_add_u64 v[82:83], v[82:83], 0, s[72:73]
	s_waitcnt lgkmcnt(0)
	v_add_f32_e32 v80, v80, v81
	global_store_dword v[82:83], v80, off
; __device__ __forceinline__ u32x4 pack8(const f32x4 v0, const f32x4 v1) { u32x4 w; w.x = cvt_pk_bf16(v0[0], v0[1]); w.y = cvt_pk_bf16(v0[2], v0[3]); w.z = cvt_pk_bf16(v1[0], v1[1]); w.w = cvt_pk_bf16(v1[2], v1[3]); return w; }
; __device__ __forceinline__ float sumsq8(const f32x4 a, const f32x4 b) { return ((a[0] * a[0] + a[1] * a[1]) + (a[2] * a[2] + a[3] * a[3])) + ((b[0] * b[0] + b[1] * b[1]) + (b[2] * b[2] + b[3] * b[3])); }
; __device__ __forceinline__ void unpack8(const u32x4 w, f32x4& a, f32x4& b) { a = (f32x4){bf_lo(w.x), bf_hi(w.x), bf_lo(w.y), bf_hi(w.y)}; b = (f32x4){bf_lo(w.z), bf_hi(w.z), bf_lo(w.w), bf_hi(w.w)}; }
;     __device__ __forceinline__ void operator()(const f32x4 (&acc)[2][2][4][2], const Unit& u, int wr, int wc, int fr, int fq) const {
;     ...
; #pragma unroll
;         for (int ai = 0; ai < 2; ++ai)
; #pragma unroll
;             for (int m = 0; m < 4; ++m) { const int row = row0 + ai * HALF + m * 16; float part = 0.f;
; #pragma unroll
;                 for (int bj = 0; bj < 2; ++bj) { f32x4 r0, r1; unpack8(rv[ai * 4 + m][bj], r0, r1);
;                     const f32x4 h0 = r0 + acc[ai][bj][m][0], h1 = r1 + acc[ai][bj][m][1]; part += sumsq8(h0, h1);
;                     *(u32x4*)(XBo + (size_t)row * DMODEL + col0 + bj * HALF) = pack8(h0, h1); }
;                 part += __shfl_xor(part, 16); part += __shfl_xor(part, 32);
;                 if (fq == 0) ssq[(size_t)row * 16 + u.pn * 4 + wc] = part; }
.LBB0_974:
	s_or_b64 exec, exec, s[0:1]
	s_waitcnt vmcnt(17)
	v_lshlrev_b32_e32 v80, 16, v164
	s_waitcnt lgkmcnt(0)
	v_and_b32_e32 v81, 0xffff0000, v164
	v_lshlrev_b32_e32 v82, 16, v165
	v_and_b32_e32 v83, 0xffff0000, v165
	v_lshlrev_b32_e32 v84, 16, v166
	v_and_b32_e32 v85, 0xffff0000, v166
	v_lshlrev_b32_e32 v86, 16, v167
	v_and_b32_e32 v87, 0xffff0000, v167
	v_pk_add_f32 v[78:79], v[78:79], v[82:83]
	v_pk_add_f32 v[76:77], v[76:77], v[80:81]
	v_pk_add_f32 v[80:81], v[74:75], v[86:87]
	v_pk_add_f32 v[74:75], v[72:73], v[84:85]
	v_mul_f32_e32 v72, v77, v77
	v_mul_f32_e32 v73, v79, v79
	v_fmac_f32_e32 v72, v76, v76
	v_fmac_f32_e32 v73, v78, v78
	v_add_f32_e32 v72, v72, v73
	v_mul_f32_e32 v73, v75, v75
	v_mul_f32_e32 v82, v81, v81
	v_fmac_f32_e32 v73, v74, v74
	v_fmac_f32_e32 v82, v80, v80
	v_add_f32_e32 v73, v73, v82
	v_add_f32_e32 v84, v72, v73
	v_cvt_pk_bf16_f32 v72, v76, v77
	v_cvt_pk_bf16_f32 v73, v78, v79
	v_lshlrev_b32_e32 v76, 16, v160
	v_and_b32_e32 v77, 0xffff0000, v160
	v_lshlrev_b32_e32 v78, 16, v161
	v_and_b32_e32 v79, 0xffff0000, v161
	v_cvt_pk_bf16_f32 v74, v74, v75
	v_cvt_pk_bf16_f32 v75, v80, v81
	v_lshlrev_b32_e32 v80, 16, v162
	v_and_b32_e32 v81, 0xffff0000, v162
	v_pk_add_f32 v[70:71], v[70:71], v[78:79]
	v_pk_add_f32 v[68:69], v[68:69], v[76:77]
	v_lshlrev_b32_e32 v82, 16, v163
	v_and_b32_e32 v83, 0xffff0000, v163
	v_pk_add_f32 v[78:79], v[64:65], v[80:81]
	v_mul_f32_e32 v64, v69, v69
	v_mul_f32_e32 v65, v71, v71
	v_pk_add_f32 v[76:77], v[66:67], v[82:83]
	v_fmac_f32_e32 v64, v68, v68
	v_fmac_f32_e32 v65, v70, v70
	v_add_f32_e32 v64, v64, v65
	v_mul_f32_e32 v65, v79, v79
	v_mul_f32_e32 v66, v77, v77
	v_fmac_f32_e32 v65, v78, v78
	v_fmac_f32_e32 v66, v76, v76
	v_add_f32_e32 v65, v65, v66
	v_add_f32_e32 v64, v64, v65
	v_add_f32_e32 v67, v84, v64
	ds_bpermute_b32 v82, v112, v67
	v_lshl_add_u64 v[64:65], s[6:7], 0, v[224:225]
	v_lshl_add_u64 v[80:81], v[214:215], 1, v[64:65]
	global_store_dwordx4 v[80:81], v[72:75], off sc1
	v_cvt_pk_bf16_f32 v66, v68, v69
	s_waitcnt lgkmcnt(0)
	v_add_f32_e32 v64, v67, v82
	ds_bpermute_b32 v65, v113, v64
	v_cvt_pk_bf16_f32 v67, v70, v71
	v_cvt_pk_bf16_f32 v68, v78, v79
	v_cvt_pk_bf16_f32 v69, v76, v77
	global_store_dwordx4 v[80:81], v[66:69], off offset:256 sc1
	s_and_saveexec_b64 s[0:1], vcc
	s_cbranch_execz .LBB0_976
	v_lshlrev_b64 v[66:67], 6, v[222:223]
	v_lshl_add_u64 v[66:67], s[8:9], 0, v[66:67]
	v_lshl_add_u64 v[66:67], s[22:23], 2, v[66:67]
	s_lshl_b32 s72, s13, 2
	v_lshl_add_u64 v[66:67], v[66:67], 0, s[72:73]
	s_waitcnt lgkmcnt(0)
	v_add_f32_e32 v64, v64, v65
	global_store_dword v[66:67], v64, off
.LBB0_976:
	s_or_b64 exec, exec, s[0:1]
	s_waitcnt vmcnt(18)
	v_lshlrev_b32_e32 v64, 16, v156
	s_waitcnt lgkmcnt(0)
	v_and_b32_e32 v65, 0xffff0000, v156
	v_lshlrev_b32_e32 v66, 16, v157
	v_and_b32_e32 v67, 0xffff0000, v157
	v_lshlrev_b32_e32 v68, 16, v158
	v_and_b32_e32 v69, 0xffff0000, v158
	v_lshlrev_b32_e32 v70, 16, v159
	v_and_b32_e32 v71, 0xffff0000, v159
	v_pk_add_f32 v[62:63], v[62:63], v[66:67]
	v_pk_add_f32 v[60:61], v[60:61], v[64:65]
	v_pk_add_f32 v[64:65], v[58:59], v[70:71]
	v_pk_add_f32 v[58:59], v[56:57], v[68:69]
	v_mul_f32_e32 v56, v61, v61
	v_mul_f32_e32 v57, v63, v63
	v_fmac_f32_e32 v56, v60, v60
	v_fmac_f32_e32 v57, v62, v62
	v_add_f32_e32 v56, v56, v57
	v_mul_f32_e32 v57, v59, v59
	v_mul_f32_e32 v66, v65, v65
	v_fmac_f32_e32 v57, v58, v58
	v_fmac_f32_e32 v66, v64, v64
	v_add_f32_e32 v57, v57, v66
	v_add_f32_e32 v68, v56, v57
	v_cvt_pk_bf16_f32 v56, v60, v61
	v_cvt_pk_bf16_f32 v57, v62, v63
	v_lshlrev_b32_e32 v60, 16, v144
	v_and_b32_e32 v61, 0xffff0000, v144
	v_lshlrev_b32_e32 v62, 16, v145
	v_and_b32_e32 v63, 0xffff0000, v145
	v_cvt_pk_bf16_f32 v58, v58, v59
	v_cvt_pk_bf16_f32 v59, v64, v65
	v_lshlrev_b32_e32 v64, 16, v146
	v_and_b32_e32 v65, 0xffff0000, v146
	v_pk_add_f32 v[54:55], v[54:55], v[62:63]
	v_pk_add_f32 v[52:53], v[52:53], v[60:61]
	v_lshlrev_b32_e32 v66, 16, v147
	v_and_b32_e32 v67, 0xffff0000, v147
	v_pk_add_f32 v[62:63], v[48:49], v[64:65]
	v_mul_f32_e32 v48, v53, v53
	v_mul_f32_e32 v49, v55, v55
	v_pk_add_f32 v[60:61], v[50:51], v[66:67]
	v_fmac_f32_e32 v48, v52, v52
	v_fmac_f32_e32 v49, v54, v54
	v_add_f32_e32 v48, v48, v49
	v_mul_f32_e32 v49, v63, v63
	v_mul_f32_e32 v50, v61, v61
	v_fmac_f32_e32 v49, v62, v62
	v_fmac_f32_e32 v50, v60, v60
	v_add_f32_e32 v49, v49, v50
	v_add_f32_e32 v48, v48, v49
	v_add_f32_e32 v51, v68, v48
	ds_bpermute_b32 v66, v112, v51
	v_lshl_add_u64 v[48:49], s[6:7], 0, v[220:221]
	v_lshl_add_u64 v[64:65], v[214:215], 1, v[48:49]
	global_store_dwordx4 v[64:65], v[56:59], off sc1
	v_cvt_pk_bf16_f32 v50, v52, v53
	s_waitcnt lgkmcnt(0)
	v_add_f32_e32 v48, v51, v66
	ds_bpermute_b32 v49, v113, v48
	v_cvt_pk_bf16_f32 v51, v54, v55
	v_cvt_pk_bf16_f32 v52, v62, v63
	v_cvt_pk_bf16_f32 v53, v60, v61
	global_store_dwordx4 v[64:65], v[50:53], off offset:256 sc1
	s_and_saveexec_b64 s[0:1], vcc
	s_cbranch_execz .LBB0_978
	v_lshlrev_b64 v[50:51], 6, v[218:219]
	v_lshl_add_u64 v[50:51], s[8:9], 0, v[50:51]
	v_lshl_add_u64 v[50:51], s[22:23], 2, v[50:51]
	s_lshl_b32 s72, s13, 2
	v_lshl_add_u64 v[50:51], v[50:51], 0, s[72:73]
	s_waitcnt lgkmcnt(0)
	v_add_f32_e32 v48, v48, v49
	global_store_dword v[50:51], v48, off
; __device__ __forceinline__ u32x4 pack8(const f32x4 v0, const f32x4 v1) { u32x4 w; w.x = cvt_pk_bf16(v0[0], v0[1]); w.y = cvt_pk_bf16(v0[2], v0[3]); w.z = cvt_pk_bf16(v1[0], v1[1]); w.w = cvt_pk_bf16(v1[2], v1[3]); return w; }
; __device__ __forceinline__ float sumsq8(const f32x4 a, const f32x4 b) { return ((a[0] * a[0] + a[1] * a[1]) + (a[2] * a[2] + a[3] * a[3])) + ((b[0] * b[0] + b[1] * b[1]) + (b[2] * b[2] + b[3] * b[3])); }
; __device__ __forceinline__ void unpack8(const u32x4 w, f32x4& a, f32x4& b) { a = (f32x4){bf_lo(w.x), bf_hi(w.x), bf_lo(w.y), bf_hi(w.y)}; b = (f32x4){bf_lo(w.z), bf_hi(w.z), bf_lo(w.w), bf_hi(w.w)}; }
;     __device__ __forceinline__ void operator()(const f32x4 (&acc)[2][2][4][2], const Unit& u, int wr, int wc, int fr, int fq) const {
;     ...
; #pragma unroll
;         for (int ai = 0; ai < 2; ++ai)
; #pragma unroll
;             for (int m = 0; m < 4; ++m) { const int row = row0 + ai * HALF + m * 16; float part = 0.f;
; #pragma unroll
;                 for (int bj = 0; bj < 2; ++bj) { f32x4 r0, r1; unpack8(rv[ai * 4 + m][bj], r0, r1);
;                     const f32x4 h0 = r0 + acc[ai][bj][m][0], h1 = r1 + acc[ai][bj][m][1]; part += sumsq8(h0, h1);
;                     *(u32x4*)(XBo + (size_t)row * DMODEL + col0 + bj * HALF) = pack8(h0, h1); }
;                 part += __shfl_xor(part, 16); part += __shfl_xor(part, 32);
;                 if (fq == 0) ssq[(size_t)row * 16 + u.pn * 4 + wc] = part; }
.LBB0_978:
	s_or_b64 exec, exec, s[0:1]
	s_waitcnt vmcnt(19)
	v_lshlrev_b32_e32 v52, 16, v140
	v_and_b32_e32 v53, 0xffff0000, v140
	v_lshlrev_b32_e32 v54, 16, v141
	v_and_b32_e32 v55, 0xffff0000, v141
	v_lshlrev_b32_e32 v56, 16, v142
	v_and_b32_e32 v57, 0xffff0000, v142
	v_lshlrev_b32_e32 v58, 16, v143
	v_and_b32_e32 v59, 0xffff0000, v143
	v_pk_add_f32 v[46:47], v[46:47], v[54:55]
	v_pk_add_f32 v[44:45], v[44:45], v[52:53]
	v_pk_add_f32 v[52:53], v[42:43], v[58:59]
	v_pk_add_f32 v[42:43], v[40:41], v[56:57]
	v_mul_f32_e32 v40, v45, v45
	v_mul_f32_e32 v41, v47, v47
	v_fmac_f32_e32 v40, v44, v44
	v_fmac_f32_e32 v41, v46, v46
	v_add_f32_e32 v40, v40, v41
	v_mul_f32_e32 v41, v43, v43
	v_mul_f32_e32 v54, v53, v53
	v_fmac_f32_e32 v41, v42, v42
	v_fmac_f32_e32 v54, v52, v52
	v_add_f32_e32 v41, v41, v54
	v_add_f32_e32 v56, v40, v41
	v_cvt_pk_bf16_f32 v40, v44, v45
	v_cvt_pk_bf16_f32 v41, v46, v47
	v_lshlrev_b32_e32 v44, 16, v136
	v_and_b32_e32 v45, 0xffff0000, v136
	v_lshlrev_b32_e32 v46, 16, v137
	v_and_b32_e32 v47, 0xffff0000, v137
	v_cvt_pk_bf16_f32 v42, v42, v43
	v_cvt_pk_bf16_f32 v43, v52, v53
	v_lshlrev_b32_e32 v52, 16, v138
	v_and_b32_e32 v53, 0xffff0000, v138
	v_pk_add_f32 v[38:39], v[38:39], v[46:47]
	v_pk_add_f32 v[36:37], v[36:37], v[44:45]
	v_lshlrev_b32_e32 v54, 16, v139
	v_and_b32_e32 v55, 0xffff0000, v139
	v_pk_add_f32 v[46:47], v[32:33], v[52:53]
	v_mul_f32_e32 v32, v37, v37
	v_mul_f32_e32 v33, v39, v39
	v_pk_add_f32 v[44:45], v[34:35], v[54:55]
	v_fmac_f32_e32 v32, v36, v36
	v_fmac_f32_e32 v33, v38, v38
	v_add_f32_e32 v32, v32, v33
	v_mul_f32_e32 v33, v47, v47
	v_mul_f32_e32 v34, v45, v45
	v_fmac_f32_e32 v33, v46, v46
	v_fmac_f32_e32 v34, v44, v44
	v_add_f32_e32 v33, v33, v34
	v_add_f32_e32 v32, v32, v33
	v_add_f32_e32 v35, v56, v32
	ds_bpermute_b32 v52, v112, v35
	v_add_u32_e32 v48, 0x90, v216
	s_waitcnt lgkmcnt(1)
	v_ashrrev_i32_e32 v49, 31, v48
	v_lshlrev_b64 v[50:51], 11, v[48:49]
	v_lshl_add_u64 v[32:33], s[6:7], 0, v[50:51]
	v_lshl_add_u64 v[50:51], v[214:215], 1, v[32:33]
	s_waitcnt lgkmcnt(0)
	v_add_f32_e32 v32, v35, v52
	ds_bpermute_b32 v33, v113, v32
	global_store_dwordx4 v[50:51], v[40:43], off sc1
	v_cvt_pk_bf16_f32 v34, v36, v37
	v_cvt_pk_bf16_f32 v35, v38, v39
	v_cvt_pk_bf16_f32 v36, v46, v47
	v_cvt_pk_bf16_f32 v37, v44, v45
	global_store_dwordx4 v[50:51], v[34:37], off offset:256 sc1
	s_and_saveexec_b64 s[0:1], vcc
	s_cbranch_execz .LBB0_980
	v_lshlrev_b64 v[34:35], 6, v[48:49]
	v_lshl_add_u64 v[34:35], s[8:9], 0, v[34:35]
	v_lshl_add_u64 v[34:35], s[22:23], 2, v[34:35]
	s_lshl_b32 s72, s13, 2
	v_lshl_add_u64 v[34:35], v[34:35], 0, s[72:73]
	s_waitcnt lgkmcnt(0)
	v_add_f32_e32 v32, v32, v33
	global_store_dword v[34:35], v32, off
; __device__ __forceinline__ u32x4 pack8(const f32x4 v0, const f32x4 v1) { u32x4 w; w.x = cvt_pk_bf16(v0[0], v0[1]); w.y = cvt_pk_bf16(v0[2], v0[3]); w.z = cvt_pk_bf16(v1[0], v1[1]); w.w = cvt_pk_bf16(v1[2], v1[3]); return w; }
; __device__ __forceinline__ float sumsq8(const f32x4 a, const f32x4 b) { return ((a[0] * a[0] + a[1] * a[1]) + (a[2] * a[2] + a[3] * a[3])) + ((b[0] * b[0] + b[1] * b[1]) + (b[2] * b[2] + b[3] * b[3])); }
; __device__ __forceinline__ void unpack8(const u32x4 w, f32x4& a, f32x4& b) { a = (f32x4){bf_lo(w.x), bf_hi(w.x), bf_lo(w.y), bf_hi(w.y)}; b = (f32x4){bf_lo(w.z), bf_hi(w.z), bf_lo(w.w), bf_hi(w.w)}; }
;     __device__ __forceinline__ void operator()(const f32x4 (&acc)[2][2][4][2], const Unit& u, int wr, int wc, int fr, int fq) const {
;     ...
; #pragma unroll
;         for (int ai = 0; ai < 2; ++ai)
; #pragma unroll
;             for (int m = 0; m < 4; ++m) { const int row = row0 + ai * HALF + m * 16; float part = 0.f;
; #pragma unroll
;                 for (int bj = 0; bj < 2; ++bj) { f32x4 r0, r1; unpack8(rv[ai * 4 + m][bj], r0, r1);
;                     const f32x4 h0 = r0 + acc[ai][bj][m][0], h1 = r1 + acc[ai][bj][m][1]; part += sumsq8(h0, h1);
;                     *(u32x4*)(XBo + (size_t)row * DMODEL + col0 + bj * HALF) = pack8(h0, h1); }
;                 part += __shfl_xor(part, 16); part += __shfl_xor(part, 32);
;                 if (fq == 0) ssq[(size_t)row * 16 + u.pn * 4 + wc] = part; }
.LBB0_980:
	s_or_b64 exec, exec, s[0:1]
	s_waitcnt vmcnt(20)
	v_lshlrev_b32_e32 v36, 16, v128
	v_and_b32_e32 v37, 0xffff0000, v128
	v_lshlrev_b32_e32 v38, 16, v129
	v_and_b32_e32 v39, 0xffff0000, v129
	v_lshlrev_b32_e32 v40, 16, v130
	v_and_b32_e32 v41, 0xffff0000, v130
	v_lshlrev_b32_e32 v42, 16, v131
	v_and_b32_e32 v43, 0xffff0000, v131
	v_pk_add_f32 v[30:31], v[30:31], v[38:39]
	v_pk_add_f32 v[28:29], v[28:29], v[36:37]
	v_pk_add_f32 v[36:37], v[26:27], v[42:43]
	v_pk_add_f32 v[26:27], v[24:25], v[40:41]
	v_mul_f32_e32 v24, v29, v29
	v_mul_f32_e32 v25, v31, v31
	v_fmac_f32_e32 v24, v28, v28
	v_fmac_f32_e32 v25, v30, v30
	v_add_f32_e32 v24, v24, v25
	v_mul_f32_e32 v25, v27, v27
	v_mul_f32_e32 v38, v37, v37
	v_fmac_f32_e32 v25, v26, v26
	v_fmac_f32_e32 v38, v36, v36
	v_add_f32_e32 v25, v25, v38
	v_add_f32_e32 v40, v24, v25
	v_cvt_pk_bf16_f32 v24, v28, v29
	v_cvt_pk_bf16_f32 v25, v30, v31
	v_lshlrev_b32_e32 v28, 16, v116
	v_and_b32_e32 v29, 0xffff0000, v116
	v_lshlrev_b32_e32 v30, 16, v117
	v_and_b32_e32 v31, 0xffff0000, v117
	v_cvt_pk_bf16_f32 v26, v26, v27
	v_cvt_pk_bf16_f32 v27, v36, v37
	v_lshlrev_b32_e32 v36, 16, v118
	v_and_b32_e32 v37, 0xffff0000, v118
	v_pk_add_f32 v[22:23], v[22:23], v[30:31]
	v_pk_add_f32 v[20:21], v[20:21], v[28:29]
	v_lshlrev_b32_e32 v38, 16, v119
	v_and_b32_e32 v39, 0xffff0000, v119
	v_pk_add_f32 v[30:31], v[16:17], v[36:37]
	v_mul_f32_e32 v16, v21, v21
	v_mul_f32_e32 v17, v23, v23
	v_pk_add_f32 v[28:29], v[18:19], v[38:39]
	v_fmac_f32_e32 v16, v20, v20
	v_fmac_f32_e32 v17, v22, v22
	v_add_f32_e32 v16, v16, v17
	v_mul_f32_e32 v17, v31, v31
	v_mul_f32_e32 v18, v29, v29
	v_fmac_f32_e32 v17, v30, v30
	v_fmac_f32_e32 v18, v28, v28
	v_add_f32_e32 v17, v17, v18
	v_add_f32_e32 v16, v16, v17
	v_add_f32_e32 v19, v40, v16
	ds_bpermute_b32 v36, v112, v19
	v_add_u32_e32 v32, 0xa0, v216
	s_waitcnt lgkmcnt(1)
	v_ashrrev_i32_e32 v33, 31, v32
	v_lshlrev_b64 v[34:35], 11, v[32:33]
	v_lshl_add_u64 v[16:17], s[6:7], 0, v[34:35]
	v_lshl_add_u64 v[34:35], v[214:215], 1, v[16:17]
	s_waitcnt lgkmcnt(0)
	v_add_f32_e32 v16, v19, v36
	ds_bpermute_b32 v17, v113, v16
	global_store_dwordx4 v[34:35], v[24:27], off sc1
	v_cvt_pk_bf16_f32 v18, v20, v21
	v_cvt_pk_bf16_f32 v19, v22, v23
	v_cvt_pk_bf16_f32 v20, v30, v31
	v_cvt_pk_bf16_f32 v21, v28, v29
	global_store_dwordx4 v[34:35], v[18:21], off offset:256 sc1
	s_and_saveexec_b64 s[0:1], vcc
	s_cbranch_execz .LBB0_982
	v_lshlrev_b64 v[18:19], 6, v[32:33]
	v_lshl_add_u64 v[18:19], s[8:9], 0, v[18:19]
	v_lshl_add_u64 v[18:19], s[22:23], 2, v[18:19]
	s_lshl_b32 s72, s13, 2
	v_lshl_add_u64 v[18:19], v[18:19], 0, s[72:73]
	s_waitcnt lgkmcnt(0)
	v_add_f32_e32 v16, v16, v17
	global_store_dword v[18:19], v16, off
.LBB0_982:
	s_or_b64 exec, exec, s[0:1]
	s_waitcnt vmcnt(21)
	v_lshlrev_b32_e32 v20, 16, v132
	v_and_b32_e32 v21, 0xffff0000, v132
	v_lshlrev_b32_e32 v22, 16, v133
	v_and_b32_e32 v23, 0xffff0000, v133
	v_lshlrev_b32_e32 v24, 16, v134
	v_and_b32_e32 v25, 0xffff0000, v134
	v_lshlrev_b32_e32 v26, 16, v135
	v_and_b32_e32 v27, 0xffff0000, v135
	v_pk_add_f32 v[14:15], v[14:15], v[22:23]
	v_pk_add_f32 v[12:13], v[12:13], v[20:21]
	v_pk_add_f32 v[20:21], v[10:11], v[26:27]
	v_pk_add_f32 v[10:11], v[8:9], v[24:25]
	v_mul_f32_e32 v8, v13, v13
	v_mul_f32_e32 v9, v15, v15
	v_fmac_f32_e32 v8, v12, v12
	v_fmac_f32_e32 v9, v14, v14
	v_add_f32_e32 v8, v8, v9
	v_mul_f32_e32 v9, v11, v11
	v_mul_f32_e32 v22, v21, v21
	v_fmac_f32_e32 v9, v10, v10
	v_fmac_f32_e32 v22, v20, v20
	v_add_f32_e32 v9, v9, v22
	v_add_f32_e32 v24, v8, v9
	v_cvt_pk_bf16_f32 v8, v12, v13
	v_cvt_pk_bf16_f32 v9, v14, v15
	v_lshlrev_b32_e32 v12, 16, v120
	v_and_b32_e32 v13, 0xffff0000, v120
	v_lshlrev_b32_e32 v14, 16, v121
	v_and_b32_e32 v15, 0xffff0000, v121
	v_cvt_pk_bf16_f32 v10, v10, v11
	v_cvt_pk_bf16_f32 v11, v20, v21
	v_lshlrev_b32_e32 v20, 16, v122
	v_and_b32_e32 v21, 0xffff0000, v122
	v_pk_add_f32 v[6:7], v[6:7], v[14:15]
	v_pk_add_f32 v[4:5], v[4:5], v[12:13]
	v_lshlrev_b32_e32 v22, 16, v123
	v_and_b32_e32 v23, 0xffff0000, v123
	v_pk_add_f32 v[14:15], v[0:1], v[20:21]
	v_mul_f32_e32 v0, v5, v5
	v_mul_f32_e32 v1, v7, v7
	v_pk_add_f32 v[12:13], v[2:3], v[22:23]
	v_fmac_f32_e32 v0, v4, v4
	v_fmac_f32_e32 v1, v6, v6
	v_add_f32_e32 v0, v0, v1
	v_mul_f32_e32 v1, v15, v15
	v_mul_f32_e32 v2, v13, v13
	v_fmac_f32_e32 v1, v14, v14
	v_fmac_f32_e32 v2, v12, v12
	v_add_f32_e32 v1, v1, v2
	v_add_f32_e32 v0, v0, v1
	v_add_f32_e32 v3, v24, v0
	ds_bpermute_b32 v20, v112, v3
	v_add_u32_e32 v16, 0xb0, v216
	s_waitcnt lgkmcnt(1)
	v_ashrrev_i32_e32 v17, 31, v16
	v_lshlrev_b64 v[18:19], 11, v[16:17]
	v_lshl_add_u64 v[0:1], s[6:7], 0, v[18:19]
	v_lshl_add_u64 v[18:19], v[214:215], 1, v[0:1]
	s_waitcnt lgkmcnt(0)
	v_add_f32_e32 v0, v3, v20
	ds_bpermute_b32 v1, v113, v0
	global_store_dwordx4 v[18:19], v[8:11], off sc1
	v_cvt_pk_bf16_f32 v2, v4, v5
	v_cvt_pk_bf16_f32 v3, v6, v7
	v_cvt_pk_bf16_f32 v4, v14, v15
	v_cvt_pk_bf16_f32 v5, v12, v13
	global_store_dwordx4 v[18:19], v[2:5], off offset:256 sc1
	s_and_saveexec_b64 s[0:1], vcc
	s_cbranch_execz .LBB0_984
	v_lshlrev_b64 v[2:3], 6, v[16:17]
	v_lshl_add_u64 v[2:3], s[8:9], 0, v[2:3]
	v_lshl_add_u64 v[2:3], s[22:23], 2, v[2:3]
	s_lshl_b32 s72, s13, 2
	v_lshl_add_u64 v[2:3], v[2:3], 0, s[72:73]
	s_waitcnt lgkmcnt(0)
	v_add_f32_e32 v0, v0, v1
	global_store_dword v[2:3], v0, off

; __device__ __forceinline__ u32x4 pack8(const f32x4 v0, const f32x4 v1) { u32x4 w; w.x = cvt_pk_bf16(v0[0], v0[1]); w.y = cvt_pk_bf16(v0[2], v0[3]); w.z = cvt_pk_bf16(v1[0], v1[1]); w.w = cvt_pk_bf16(v1[2], v1[3]); return w; }
; __device__ __forceinline__ float sumsq8(const f32x4 a, const f32x4 b) { return ((a[0] * a[0] + a[1] * a[1]) + (a[2] * a[2] + a[3] * a[3])) + ((b[0] * b[0] + b[1] * b[1]) + (b[2] * b[2] + b[3] * b[3])); }
;     __device__ __forceinline__ void operator()(const f32x4 (&acc)[2][2][4][2], const Unit& u, int wr, int wc, int fr, int fq) const {
;     ...
; #pragma unroll
;         for (int ai = 0; ai < 2; ++ai)
; #pragma unroll
;           for (int mh = 0; mh < 2; ++mh) {
;             u32x4 rv[2][2], pw[2][2]; f32x4 p[2];
; #pragma unroll
;             for (int mm = 0; mm < 2; ++mm) { const int rowl = row0 + ai * HALF + (2 * mh + mm) * 16; p[mm] = *(const f32x4*)(ssq_in + (size_t)rowl * 16 + 4 * fq);
; #pragma unroll
;                 for (int bj = 0; bj < 2; ++bj) { const size_t off = (size_t)rowl * DMODEL + col0 + bj * HALF; rv[mm][bj] = *(const u32x4*)(Rin + off); pw[mm][bj] = *(const u32x4*)(PP + off); } }
; #pragma unroll
;             for (int mm = 0; mm < 2; ++mm) { const int m = 2 * mh + mm; const int row = row0 + ai * HALF + m * 16; float part = 0.f;
;                 float sr = (p[mm][0] + p[mm][1]) + (p[mm][2] + p[mm][3]); sr += __shfl_xor(sr, 16); sr += __shfl_xor(sr, 32); const float r = __builtin_amdgcn_rsqf(sr * (1.0f / DMODEL) + RMS_EPS);
; #pragma unroll
;                 for (int bj = 0; bj < 2; ++bj) { f32x4 r0, r1, p0, p1; unpack8(rv[mm][bj], r0, r1); unpack8(pw[mm][bj], p0, p1);
;                     f32x4 g0 = acc[ai][bj][m][0] * r, g1 = acc[ai][bj][m][1] * r;
; #pragma unroll
;                     for (int e = 0; e < 4; ++e) { g0[e] = __builtin_amdgcn_rcpf(1.f + __builtin_amdgcn_exp2f(-1.4426950408889634f * g0[e])); g1[e] = __builtin_amdgcn_rcpf(1.f + __builtin_amdgcn_exp2f(-1.4426950408889634f * g1[e])); }
;                     const f32x4 h0 = r0 + g0 * p0, h1 = r1 + g1 * p1; part += sumsq8(h0, h1);
;                     *(u32x4*)(XBo + (size_t)row * DMODEL + col0 + bj * HALF) = pack8(h0, h1); }
;                 part += __shfl_xor(part, 16); part += __shfl_xor(part, 32);
;                 if (fq == 0) ssq_out[(size_t)row * 16 + u.pn * 4 + wc] = part; }
.LBB0_1136:
	v_readfirstlane_b32 s19, v192
	v_and_b32_e32 v247, 15, v192
	s_bfe_u32 s17, s19, 0x20006
	s_lshr_b32 s19, s19, 8
	s_lshl_b32 s19, s19, 6
	s_lshl_b32 s27, s40, 8
	s_add_i32 s19, s19, s27
	v_add_u32_e32 v247, s19, v247
	v_bfe_u32 v252, v192, 4, 2
	s_lshl_b32 s27, s26, 8
	s_lshl_b32 s28, s17, 5
	s_or_b32 s27, s27, s28
	v_lshl_or_b32 v253, v252, 3, s27
	v_lshlrev_b32_e32 v172, 11, v247
	v_lshl_add_u32 v172, v253, 1, v172
	v_lshlrev_b32_e32 v194, 6, v247
	v_lshl_add_u32 v173, v252, 4, v194
	s_lshl_b32 s28, s26, 4
	s_lshl_b32 s29, s17, 2
	s_add_i32 s28, s28, s29
	v_add_u32_e32 v194, s28, v194
	v_cmp_eq_u32_e32 vcc, 0, v252
	v_xor_b32_e32 v236, 16, v241
	v_xor_b32_e32 v237, 32, v241
	v_lshlrev_b32_e32 v236, 2, v236
	v_lshlrev_b32_e32 v237, 2, v237
	v_mov_b32_e32 v250, v172
	v_mov_b32_e32 v251, v173
	global_load_dwordx4 v[128:131], v251, s[10:11]
	global_load_dwordx4 v[132:135], v250, s[6:7]
	global_load_dwordx4 v[140:143], v250, s[2:3]
	global_load_dwordx4 v[136:139], v250, s[6:7] offset:256
	global_load_dwordx4 v[144:147], v250, s[2:3] offset:256
	v_add_u32_e32 v250, 0x8000, v172
	v_add_u32_e32 v251, 0x400, v173
	global_load_dwordx4 v[160:163], v251, s[10:11]
	global_load_dwordx4 v[164:167], v250, s[6:7]
	global_load_dwordx4 v[176:179], v250, s[2:3]
	global_load_dwordx4 v[168:171], v250, s[6:7] offset:256
	global_load_dwordx4 v[180:183], v250, s[2:3] offset:256
	v_add_u32_e32 v250, 0x10000, v172
	v_add_u32_e32 v251, 0x800, v173
	global_load_dwordx4 v[184:187], v251, s[10:11]
	global_load_dwordx4 v[188:191], v250, s[6:7]
	global_load_dwordx4 v[208:211], v250, s[2:3]
	global_load_dwordx4 v[204:207], v250, s[6:7] offset:256
	global_load_dwordx4 v[212:215], v250, s[2:3] offset:256
	s_waitcnt vmcnt(10)
	v_add_f32_e32 v247, v128, v129
	v_add_f32_e32 v252, v130, v131
	v_add_f32_e32 v247, v247, v252
	ds_bpermute_b32 v252, v236, v247
	s_waitcnt lgkmcnt(0)
	v_add_f32_e32 v247, v247, v252
	ds_bpermute_b32 v252, v237, v247
	s_waitcnt lgkmcnt(0)
	v_add_f32_e32 v247, v247, v252
	v_fmamk_f32 v247, v247, 0x3a800000, v193
	v_rsq_f32_e32 v247, v247
	s_nop 0
	v_mul_f32_e32 v253, 0xbfb8aa3b, v247
	v_mul_f32_e32 v124, v124, v253
	v_mul_f32_e32 v125, v125, v253
	v_mul_f32_e32 v126, v126, v253
	v_mul_f32_e32 v127, v127, v253
	v_exp_f32_e32 v124, v124
	v_exp_f32_e32 v125, v125
	v_exp_f32_e32 v126, v126
	v_exp_f32_e32 v127, v127
	v_add_f32_e32 v124, 1.0, v124
	v_add_f32_e32 v125, 1.0, v125
	v_add_f32_e32 v126, 1.0, v126
	v_add_f32_e32 v127, 1.0, v127
	v_rcp_f32_e32 v124, v124
	v_rcp_f32_e32 v125, v125
	v_rcp_f32_e32 v126, v126
	v_rcp_f32_e32 v127, v127
	v_lshlrev_b32_e32 v224, 16, v132
	v_and_b32_e32 v225, 0xffff0000, v132
	v_lshlrev_b32_e32 v226, 16, v133
	v_and_b32_e32 v227, 0xffff0000, v133
	v_lshlrev_b32_e32 v228, 16, v140
	v_and_b32_e32 v229, 0xffff0000, v140
	v_lshlrev_b32_e32 v230, 16, v141
	v_and_b32_e32 v231, 0xffff0000, v141
	v_fma_f32 v124, v124, v228, v224
	v_fma_f32 v125, v125, v229, v225
	v_fma_f32 v126, v126, v230, v226
	v_fma_f32 v127, v127, v231, v227
	v_mul_f32_e32 v232, v125, v125
	v_mul_f32_e32 v233, v127, v127
	v_fmac_f32_e32 v232, v124, v124
	v_fmac_f32_e32 v233, v126, v126
	v_add_f32_e32 v234, v232, v233
	v_mul_f32_e32 v120, v120, v253
	v_mul_f32_e32 v121, v121, v253
	v_mul_f32_e32 v122, v122, v253
	v_mul_f32_e32 v123, v123, v253
	v_exp_f32_e32 v120, v120
	v_exp_f32_e32 v121, v121
	v_exp_f32_e32 v122, v122
	v_exp_f32_e32 v123, v123
	v_add_f32_e32 v120, 1.0, v120
	v_add_f32_e32 v121, 1.0, v121
	v_add_f32_e32 v122, 1.0, v122
	v_add_f32_e32 v123, 1.0, v123
	v_rcp_f32_e32 v120, v120
	v_rcp_f32_e32 v121, v121
	v_rcp_f32_e32 v122, v122
	v_rcp_f32_e32 v123, v123
	v_lshlrev_b32_e32 v224, 16, v134
	v_and_b32_e32 v225, 0xffff0000, v134
	v_lshlrev_b32_e32 v226, 16, v135
	v_and_b32_e32 v227, 0xffff0000, v135
	v_lshlrev_b32_e32 v228, 16, v142
	v_and_b32_e32 v229, 0xffff0000, v142
	v_lshlrev_b32_e32 v230, 16, v143
	v_and_b32_e32 v231, 0xffff0000, v143
	v_fma_f32 v120, v120, v228, v224
	v_fma_f32 v121, v121, v229, v225
	v_fma_f32 v122, v122, v230, v226
	v_fma_f32 v123, v123, v231, v227
	v_mul_f32_e32 v232, v121, v121
	v_mul_f32_e32 v233, v123, v123
	v_fmac_f32_e32 v232, v120, v120
	v_fmac_f32_e32 v233, v122, v122
	v_add_f32_e32 v235, v232, v233
	v_cvt_pk_bf16_f32 v124, v124, v125
	v_cvt_pk_bf16_f32 v125, v126, v127
	v_cvt_pk_bf16_f32 v126, v120, v121
	v_cvt_pk_bf16_f32 v127, v122, v123
	v_mov_b32_e32 v250, v172
	global_store_dwordx4 v250, v[124:127], s[0:1] sc1
	v_mul_f32_e32 v116, v116, v253
	v_mul_f32_e32 v117, v117, v253
	v_mul_f32_e32 v118, v118, v253
	v_mul_f32_e32 v119, v119, v253
	v_exp_f32_e32 v116, v116
	v_exp_f32_e32 v117, v117
	v_exp_f32_e32 v118, v118
	v_exp_f32_e32 v119, v119
	v_add_f32_e32 v116, 1.0, v116
	v_add_f32_e32 v117, 1.0, v117
	v_add_f32_e32 v118, 1.0, v118
	v_add_f32_e32 v119, 1.0, v119
	v_rcp_f32_e32 v116, v116
	v_rcp_f32_e32 v117, v117
	v_rcp_f32_e32 v118, v118
	v_rcp_f32_e32 v119, v119
	v_lshlrev_b32_e32 v224, 16, v136
	v_and_b32_e32 v225, 0xffff0000, v136
	v_lshlrev_b32_e32 v226, 16, v137
	v_and_b32_e32 v227, 0xffff0000, v137
	v_lshlrev_b32_e32 v228, 16, v144
	v_and_b32_e32 v229, 0xffff0000, v144
	v_lshlrev_b32_e32 v230, 16, v145
	v_and_b32_e32 v231, 0xffff0000, v145
	v_fma_f32 v116, v116, v228, v224
	v_fma_f32 v117, v117, v229, v225
	v_fma_f32 v118, v118, v230, v226
	v_fma_f32 v119, v119, v231, v227
	v_mul_f32_e32 v232, v117, v117
	v_mul_f32_e32 v233, v119, v119
	v_fmac_f32_e32 v232, v116, v116
	v_fmac_f32_e32 v233, v118, v118
	v_add_f32_e32 v248, v232, v233
	v_mul_f32_e32 v112, v112, v253
	v_mul_f32_e32 v113, v113, v253
	v_mul_f32_e32 v114, v114, v253
	v_mul_f32_e32 v115, v115, v253
	v_exp_f32_e32 v112, v112
	v_exp_f32_e32 v113, v113
	v_exp_f32_e32 v114, v114
	v_exp_f32_e32 v115, v115
	v_add_f32_e32 v112, 1.0, v112
	v_add_f32_e32 v113, 1.0, v113
	v_add_f32_e32 v114, 1.0, v114
	v_add_f32_e32 v115, 1.0, v115
	v_rcp_f32_e32 v112, v112
	v_rcp_f32_e32 v113, v113
	v_rcp_f32_e32 v114, v114
	v_rcp_f32_e32 v115, v115
	v_lshlrev_b32_e32 v224, 16, v138
	v_and_b32_e32 v225, 0xffff0000, v138
	v_lshlrev_b32_e32 v226, 16, v139
	v_and_b32_e32 v227, 0xffff0000, v139
	v_lshlrev_b32_e32 v228, 16, v146
	v_and_b32_e32 v229, 0xffff0000, v146
	v_lshlrev_b32_e32 v230, 16, v147
	v_and_b32_e32 v231, 0xffff0000, v147
	v_fma_f32 v112, v112, v228, v224
	v_fma_f32 v113, v113, v229, v225
	v_fma_f32 v114, v114, v230, v226
	v_fma_f32 v115, v115, v231, v227
	v_mul_f32_e32 v232, v113, v113
	v_mul_f32_e32 v233, v115, v115
	v_fmac_f32_e32 v232, v112, v112
	v_fmac_f32_e32 v233, v114, v114
	v_add_f32_e32 v249, v232, v233
	v_cvt_pk_bf16_f32 v116, v116, v117
	v_cvt_pk_bf16_f32 v117, v118, v119
	v_cvt_pk_bf16_f32 v118, v112, v113
	v_cvt_pk_bf16_f32 v119, v114, v115
	global_store_dwordx4 v250, v[116:119], s[0:1] offset:256 sc1
	v_add_f32_e32 v234, v234, v235
	v_add_f32_e32 v248, v248, v249
	v_add_f32_e32 v247, v234, v248
	ds_bpermute_b32 v252, v236, v247
	v_mov_b32_e32 v251, v194
	s_waitcnt lgkmcnt(0)
; __device__ __forceinline__ u32x4 pack8(const f32x4 v0, const f32x4 v1) { u32x4 w; w.x = cvt_pk_bf16(v0[0], v0[1]); w.y = cvt_pk_bf16(v0[2], v0[3]); w.z = cvt_pk_bf16(v1[0], v1[1]); w.w = cvt_pk_bf16(v1[2], v1[3]); return w; }
; __device__ __forceinline__ float sumsq8(const f32x4 a, const f32x4 b) { return ((a[0] * a[0] + a[1] * a[1]) + (a[2] * a[2] + a[3] * a[3])) + ((b[0] * b[0] + b[1] * b[1]) + (b[2] * b[2] + b[3] * b[3])); }
; __device__ __forceinline__ void unpack8(const u32x4 w, f32x4& a, f32x4& b) { a = (f32x4){bf_lo(w.x), bf_hi(w.x), bf_lo(w.y), bf_hi(w.y)}; b = (f32x4){bf_lo(w.z), bf_hi(w.z), bf_lo(w.w), bf_hi(w.w)}; }
;     __device__ __forceinline__ void operator()(const f32x4 (&acc)[2][2][4][2], const Unit& u, int wr, int wc, int fr, int fq) const {
;     ...
;             for (int mm = 0; mm < 2; ++mm) { const int rowl = row0 + ai * HALF + (2 * mh + mm) * 16; p[mm] = *(const f32x4*)(ssq_in + (size_t)rowl * 16 + 4 * fq);
; #pragma unroll
;                 for (int bj = 0; bj < 2; ++bj) { const size_t off = (size_t)rowl * DMODEL + col0 + bj * HALF; rv[mm][bj] = *(const u32x4*)(Rin + off); pw[mm][bj] = *(const u32x4*)(PP + off); } }
; #pragma unroll
;             for (int mm = 0; mm < 2; ++mm) { const int m = 2 * mh + mm; const int row = row0 + ai * HALF + m * 16; float part = 0.f;
;                 float sr = (p[mm][0] + p[mm][1]) + (p[mm][2] + p[mm][3]); sr += __shfl_xor(sr, 16); sr += __shfl_xor(sr, 32); const float r = __builtin_amdgcn_rsqf(sr * (1.0f / DMODEL) + RMS_EPS);
; #pragma unroll
;                 for (int bj = 0; bj < 2; ++bj) { f32x4 r0, r1, p0, p1; unpack8(rv[mm][bj], r0, r1); unpack8(pw[mm][bj], p0, p1);
;                     f32x4 g0 = acc[ai][bj][m][0] * r, g1 = acc[ai][bj][m][1] * r;
; #pragma unroll
;                     for (int e = 0; e < 4; ++e) { g0[e] = __builtin_amdgcn_rcpf(1.f + __builtin_amdgcn_exp2f(-1.4426950408889634f * g0[e])); g1[e] = __builtin_amdgcn_rcpf(1.f + __builtin_amdgcn_exp2f(-1.4426950408889634f * g1[e])); }
;                     const f32x4 h0 = r0 + g0 * p0, h1 = r1 + g1 * p1; part += sumsq8(h0, h1);
;                     *(u32x4*)(XBo + (size_t)row * DMODEL + col0 + bj * HALF) = pack8(h0, h1); }
;                 part += __shfl_xor(part, 16); part += __shfl_xor(part, 32);
;                 if (fq == 0) ssq_out[(size_t)row * 16 + u.pn * 4 + wc] = part; }
	v_add_f32_e32 v247, v247, v252
	ds_bpermute_b32 v252, v237, v247
	s_waitcnt lgkmcnt(0)
	v_add_f32_e32 v247, v247, v252
	s_and_saveexec_b64 s[28:29], vcc
	global_store_dword v251, v247, s[12:13]
	s_or_b64 exec, exec, s[28:29]
	v_add_u32_e32 v250, 0x18000, v172
	v_add_u32_e32 v251, 0xc00, v173
	global_load_dwordx4 v[128:131], v251, s[10:11]
	global_load_dwordx4 v[132:135], v250, s[6:7]
	global_load_dwordx4 v[140:143], v250, s[2:3]
	global_load_dwordx4 v[136:139], v250, s[6:7] offset:256
	global_load_dwordx4 v[144:147], v250, s[2:3] offset:256
	v_add_u32_e32 v250, 0x40000, v172
	v_add_u32_e32 v251, 0x2000, v173
	global_load_dwordx4 v[124:127], v251, s[10:11]
	global_load_dwordx4 v[120:123], v250, s[6:7]
	global_load_dwordx4 v[112:115], v250, s[2:3]
	global_load_dwordx4 v[116:119], v250, s[6:7] offset:256
	global_load_dwordx4 v[216:219], v250, s[2:3] offset:256
	s_waitcnt vmcnt(18)
	v_add_f32_e32 v247, v160, v161
	v_add_f32_e32 v252, v162, v163
	v_add_f32_e32 v247, v247, v252
	ds_bpermute_b32 v252, v236, v247
	s_waitcnt lgkmcnt(0)
	v_add_f32_e32 v247, v247, v252
	ds_bpermute_b32 v252, v237, v247
	s_waitcnt lgkmcnt(0)
	v_add_f32_e32 v247, v247, v252
	v_fmamk_f32 v247, v247, 0x3a800000, v193
	v_rsq_f32_e32 v247, v247
	s_nop 0
	v_mul_f32_e32 v253, 0xbfb8aa3b, v247
	v_mul_f32_e32 v108, v108, v253
	v_mul_f32_e32 v109, v109, v253
	v_mul_f32_e32 v110, v110, v253
	v_mul_f32_e32 v111, v111, v253
	v_exp_f32_e32 v108, v108
	v_exp_f32_e32 v109, v109
	v_exp_f32_e32 v110, v110
	v_exp_f32_e32 v111, v111
	v_add_f32_e32 v108, 1.0, v108
	v_add_f32_e32 v109, 1.0, v109
	v_add_f32_e32 v110, 1.0, v110
	v_add_f32_e32 v111, 1.0, v111
	v_rcp_f32_e32 v108, v108
	v_rcp_f32_e32 v109, v109
	v_rcp_f32_e32 v110, v110
	v_rcp_f32_e32 v111, v111
	v_lshlrev_b32_e32 v224, 16, v164
	v_and_b32_e32 v225, 0xffff0000, v164
	v_lshlrev_b32_e32 v226, 16, v165
	v_and_b32_e32 v227, 0xffff0000, v165
	v_lshlrev_b32_e32 v228, 16, v176
	v_and_b32_e32 v229, 0xffff0000, v176
	v_lshlrev_b32_e32 v230, 16, v177
	v_and_b32_e32 v231, 0xffff0000, v177
	v_fma_f32 v108, v108, v228, v224
	v_fma_f32 v109, v109, v229, v225
	v_fma_f32 v110, v110, v230, v226
	v_fma_f32 v111, v111, v231, v227
	v_mul_f32_e32 v232, v109, v109
	v_mul_f32_e32 v233, v111, v111
	v_fmac_f32_e32 v232, v108, v108
	v_fmac_f32_e32 v233, v110, v110
	v_add_f32_e32 v234, v232, v233
	v_mul_f32_e32 v104, v104, v253
	v_mul_f32_e32 v105, v105, v253
	v_mul_f32_e32 v106, v106, v253
	v_mul_f32_e32 v107, v107, v253
	v_exp_f32_e32 v104, v104
	v_exp_f32_e32 v105, v105
	v_exp_f32_e32 v106, v106
	v_exp_f32_e32 v107, v107
	v_add_f32_e32 v104, 1.0, v104
	v_add_f32_e32 v105, 1.0, v105
	v_add_f32_e32 v106, 1.0, v106
	v_add_f32_e32 v107, 1.0, v107
	v_rcp_f32_e32 v104, v104
	v_rcp_f32_e32 v105, v105
	v_rcp_f32_e32 v106, v106
	v_rcp_f32_e32 v107, v107
	v_lshlrev_b32_e32 v224, 16, v166
	v_and_b32_e32 v225, 0xffff0000, v166
	v_lshlrev_b32_e32 v226, 16, v167
	v_and_b32_e32 v227, 0xffff0000, v167
	v_lshlrev_b32_e32 v228, 16, v178
	v_and_b32_e32 v229, 0xffff0000, v178
	v_lshlrev_b32_e32 v230, 16, v179
	v_and_b32_e32 v231, 0xffff0000, v179
	v_fma_f32 v104, v104, v228, v224
	v_fma_f32 v105, v105, v229, v225
	v_fma_f32 v106, v106, v230, v226
	v_fma_f32 v107, v107, v231, v227
	v_mul_f32_e32 v232, v105, v105
	v_mul_f32_e32 v233, v107, v107
	v_fmac_f32_e32 v232, v104, v104
	v_fmac_f32_e32 v233, v106, v106
	v_add_f32_e32 v235, v232, v233
	v_cvt_pk_bf16_f32 v108, v108, v109
	v_cvt_pk_bf16_f32 v109, v110, v111
	v_cvt_pk_bf16_f32 v110, v104, v105
	v_cvt_pk_bf16_f32 v111, v106, v107
	v_add_u32_e32 v250, 0x8000, v172
	global_store_dwordx4 v250, v[108:111], s[0:1] sc1
	v_mul_f32_e32 v100, v100, v253
	v_mul_f32_e32 v101, v101, v253
	v_mul_f32_e32 v102, v102, v253
	v_mul_f32_e32 v103, v103, v253
	v_exp_f32_e32 v100, v100
	v_exp_f32_e32 v101, v101
	v_exp_f32_e32 v102, v102
	v_exp_f32_e32 v103, v103
	v_add_f32_e32 v100, 1.0, v100
	v_add_f32_e32 v101, 1.0, v101
	v_add_f32_e32 v102, 1.0, v102
	v_add_f32_e32 v103, 1.0, v103
	v_rcp_f32_e32 v100, v100
	v_rcp_f32_e32 v101, v101
	v_rcp_f32_e32 v102, v102
	v_rcp_f32_e32 v103, v103
	v_lshlrev_b32_e32 v224, 16, v168
	v_and_b32_e32 v225, 0xffff0000, v168
	v_lshlrev_b32_e32 v226, 16, v169
	v_and_b32_e32 v227, 0xffff0000, v169
	v_lshlrev_b32_e32 v228, 16, v180
	v_and_b32_e32 v229, 0xffff0000, v180
	v_lshlrev_b32_e32 v230, 16, v181
	v_and_b32_e32 v231, 0xffff0000, v181
	v_fma_f32 v100, v100, v228, v224
	v_fma_f32 v101, v101, v229, v225
	v_fma_f32 v102, v102, v230, v226
	v_fma_f32 v103, v103, v231, v227
	v_mul_f32_e32 v232, v101, v101
	v_mul_f32_e32 v233, v103, v103
	v_fmac_f32_e32 v232, v100, v100
	v_fmac_f32_e32 v233, v102, v102
	v_add_f32_e32 v248, v232, v233
	v_mul_f32_e32 v96, v96, v253
	v_mul_f32_e32 v97, v97, v253
	v_mul_f32_e32 v98, v98, v253
	v_mul_f32_e32 v99, v99, v253
	v_exp_f32_e32 v96, v96
	v_exp_f32_e32 v97, v97
	v_exp_f32_e32 v98, v98
	v_exp_f32_e32 v99, v99
	v_add_f32_e32 v96, 1.0, v96
	v_add_f32_e32 v97, 1.0, v97
	v_add_f32_e32 v98, 1.0, v98
	v_add_f32_e32 v99, 1.0, v99
	v_rcp_f32_e32 v96, v96
	v_rcp_f32_e32 v97, v97
	v_rcp_f32_e32 v98, v98
	v_rcp_f32_e32 v99, v99
	v_lshlrev_b32_e32 v224, 16, v170
	v_and_b32_e32 v225, 0xffff0000, v170
	v_lshlrev_b32_e32 v226, 16, v171
	v_and_b32_e32 v227, 0xffff0000, v171
	v_lshlrev_b32_e32 v228, 16, v182
	v_and_b32_e32 v229, 0xffff0000, v182
	v_lshlrev_b32_e32 v230, 16, v183
	v_and_b32_e32 v231, 0xffff0000, v183
	v_fma_f32 v96, v96, v228, v224
	v_fma_f32 v97, v97, v229, v225
	v_fma_f32 v98, v98, v230, v226
	v_fma_f32 v99, v99, v231, v227
	v_mul_f32_e32 v232, v97, v97
	v_mul_f32_e32 v233, v99, v99
	v_fmac_f32_e32 v232, v96, v96
	v_fmac_f32_e32 v233, v98, v98
	v_add_f32_e32 v249, v232, v233
	v_cvt_pk_bf16_f32 v100, v100, v101
	v_cvt_pk_bf16_f32 v101, v102, v103
	v_cvt_pk_bf16_f32 v102, v96, v97
	v_cvt_pk_bf16_f32 v103, v98, v99
	global_store_dwordx4 v250, v[100:103], s[0:1] offset:256 sc1
	v_add_f32_e32 v234, v234, v235
	v_add_f32_e32 v248, v248, v249
	v_add_f32_e32 v247, v234, v248
	ds_bpermute_b32 v252, v236, v247
	v_add_u32_e32 v251, 0x400, v194
	s_waitcnt lgkmcnt(0)
; __device__ __forceinline__ u32x4 pack8(const f32x4 v0, const f32x4 v1) { u32x4 w; w.x = cvt_pk_bf16(v0[0], v0[1]); w.y = cvt_pk_bf16(v0[2], v0[3]); w.z = cvt_pk_bf16(v1[0], v1[1]); w.w = cvt_pk_bf16(v1[2], v1[3]); return w; }
; __device__ __forceinline__ float sumsq8(const f32x4 a, const f32x4 b) { return ((a[0] * a[0] + a[1] * a[1]) + (a[2] * a[2] + a[3] * a[3])) + ((b[0] * b[0] + b[1] * b[1]) + (b[2] * b[2] + b[3] * b[3])); }
; __device__ __forceinline__ void unpack8(const u32x4 w, f32x4& a, f32x4& b) { a = (f32x4){bf_lo(w.x), bf_hi(w.x), bf_lo(w.y), bf_hi(w.y)}; b = (f32x4){bf_lo(w.z), bf_hi(w.z), bf_lo(w.w), bf_hi(w.w)}; }
;     __device__ __forceinline__ void operator()(const f32x4 (&acc)[2][2][4][2], const Unit& u, int wr, int wc, int fr, int fq) const {
;     ...
;             for (int mm = 0; mm < 2; ++mm) { const int rowl = row0 + ai * HALF + (2 * mh + mm) * 16; p[mm] = *(const f32x4*)(ssq_in + (size_t)rowl * 16 + 4 * fq);
; #pragma unroll
;                 for (int bj = 0; bj < 2; ++bj) { const size_t off = (size_t)rowl * DMODEL + col0 + bj * HALF; rv[mm][bj] = *(const u32x4*)(Rin + off); pw[mm][bj] = *(const u32x4*)(PP + off); } }
; #pragma unroll
;             for (int mm = 0; mm < 2; ++mm) { const int m = 2 * mh + mm; const int row = row0 + ai * HALF + m * 16; float part = 0.f;
;                 float sr = (p[mm][0] + p[mm][1]) + (p[mm][2] + p[mm][3]); sr += __shfl_xor(sr, 16); sr += __shfl_xor(sr, 32); const float r = __builtin_amdgcn_rsqf(sr * (1.0f / DMODEL) + RMS_EPS);
; #pragma unroll
;                 for (int bj = 0; bj < 2; ++bj) { f32x4 r0, r1, p0, p1; unpack8(rv[mm][bj], r0, r1); unpack8(pw[mm][bj], p0, p1);
;                     f32x4 g0 = acc[ai][bj][m][0] * r, g1 = acc[ai][bj][m][1] * r;
; #pragma unroll
;                     for (int e = 0; e < 4; ++e) { g0[e] = __builtin_amdgcn_rcpf(1.f + __builtin_amdgcn_exp2f(-1.4426950408889634f * g0[e])); g1[e] = __builtin_amdgcn_rcpf(1.f + __builtin_amdgcn_exp2f(-1.4426950408889634f * g1[e])); }
;                     const f32x4 h0 = r0 + g0 * p0, h1 = r1 + g1 * p1; part += sumsq8(h0, h1);
;                     *(u32x4*)(XBo + (size_t)row * DMODEL + col0 + bj * HALF) = pack8(h0, h1); }
;                 part += __shfl_xor(part, 16); part += __shfl_xor(part, 32);
;                 if (fq == 0) ssq_out[(size_t)row * 16 + u.pn * 4 + wc] = part; }
	v_add_f32_e32 v247, v247, v252
	ds_bpermute_b32 v252, v237, v247
	s_waitcnt lgkmcnt(0)
	v_add_f32_e32 v247, v247, v252
	s_and_saveexec_b64 s[28:29], vcc
	global_store_dword v251, v247, s[12:13]
	s_or_b64 exec, exec, s[28:29]
	v_add_u32_e32 v250, 0x48000, v172
	v_add_u32_e32 v251, 0x2400, v173
	global_load_dwordx4 v[160:163], v251, s[10:11]
	global_load_dwordx4 v[164:167], v250, s[6:7]
	global_load_dwordx4 v[176:179], v250, s[2:3]
	global_load_dwordx4 v[168:171], v250, s[6:7] offset:256
	global_load_dwordx4 v[180:183], v250, s[2:3] offset:256
	v_add_u32_e32 v250, 0x50000, v172
	v_add_u32_e32 v251, 0x2800, v173
	global_load_dwordx4 v[108:111], v251, s[10:11]
	global_load_dwordx4 v[104:107], v250, s[6:7]
	global_load_dwordx4 v[96:99], v250, s[2:3]
	global_load_dwordx4 v[100:103], v250, s[6:7] offset:256
	global_load_dwordx4 v[220:223], v250, s[2:3] offset:256
	s_waitcnt vmcnt(26)
	v_add_f32_e32 v247, v184, v185
	v_add_f32_e32 v252, v186, v187
	v_add_f32_e32 v247, v247, v252
	ds_bpermute_b32 v252, v236, v247
	s_waitcnt lgkmcnt(0)
	v_add_f32_e32 v247, v247, v252
	ds_bpermute_b32 v252, v237, v247
	s_waitcnt lgkmcnt(0)
	v_add_f32_e32 v247, v247, v252
	v_fmamk_f32 v247, v247, 0x3a800000, v193
	v_rsq_f32_e32 v247, v247
	s_nop 0
	v_mul_f32_e32 v253, 0xbfb8aa3b, v247
	v_mul_f32_e32 v92, v92, v253
	v_mul_f32_e32 v93, v93, v253
	v_mul_f32_e32 v94, v94, v253
	v_mul_f32_e32 v95, v95, v253
	v_exp_f32_e32 v92, v92
	v_exp_f32_e32 v93, v93
	v_exp_f32_e32 v94, v94
	v_exp_f32_e32 v95, v95
	v_add_f32_e32 v92, 1.0, v92
	v_add_f32_e32 v93, 1.0, v93
	v_add_f32_e32 v94, 1.0, v94
	v_add_f32_e32 v95, 1.0, v95
	v_rcp_f32_e32 v92, v92
	v_rcp_f32_e32 v93, v93
	v_rcp_f32_e32 v94, v94
	v_rcp_f32_e32 v95, v95
	v_lshlrev_b32_e32 v224, 16, v188
	v_and_b32_e32 v225, 0xffff0000, v188
	v_lshlrev_b32_e32 v226, 16, v189
	v_and_b32_e32 v227, 0xffff0000, v189
	v_lshlrev_b32_e32 v228, 16, v208
	v_and_b32_e32 v229, 0xffff0000, v208
	v_lshlrev_b32_e32 v230, 16, v209
	v_and_b32_e32 v231, 0xffff0000, v209
	v_fma_f32 v92, v92, v228, v224
	v_fma_f32 v93, v93, v229, v225
	v_fma_f32 v94, v94, v230, v226
	v_fma_f32 v95, v95, v231, v227
	v_mul_f32_e32 v232, v93, v93
	v_mul_f32_e32 v233, v95, v95
	v_fmac_f32_e32 v232, v92, v92
	v_fmac_f32_e32 v233, v94, v94
	v_add_f32_e32 v234, v232, v233
	v_mul_f32_e32 v88, v88, v253
	v_mul_f32_e32 v89, v89, v253
	v_mul_f32_e32 v90, v90, v253
	v_mul_f32_e32 v91, v91, v253
	v_exp_f32_e32 v88, v88
	v_exp_f32_e32 v89, v89
	v_exp_f32_e32 v90, v90
	v_exp_f32_e32 v91, v91
	v_add_f32_e32 v88, 1.0, v88
	v_add_f32_e32 v89, 1.0, v89
	v_add_f32_e32 v90, 1.0, v90
	v_add_f32_e32 v91, 1.0, v91
	v_rcp_f32_e32 v88, v88
	v_rcp_f32_e32 v89, v89
	v_rcp_f32_e32 v90, v90
	v_rcp_f32_e32 v91, v91
	v_lshlrev_b32_e32 v224, 16, v190
	v_and_b32_e32 v225, 0xffff0000, v190
	v_lshlrev_b32_e32 v226, 16, v191
	v_and_b32_e32 v227, 0xffff0000, v191
	v_lshlrev_b32_e32 v228, 16, v210
	v_and_b32_e32 v229, 0xffff0000, v210
	v_lshlrev_b32_e32 v230, 16, v211
	v_and_b32_e32 v231, 0xffff0000, v211
	v_fma_f32 v88, v88, v228, v224
	v_fma_f32 v89, v89, v229, v225
	v_fma_f32 v90, v90, v230, v226
	v_fma_f32 v91, v91, v231, v227
	v_mul_f32_e32 v232, v89, v89
	v_mul_f32_e32 v233, v91, v91
	v_fmac_f32_e32 v232, v88, v88
	v_fmac_f32_e32 v233, v90, v90
	v_add_f32_e32 v235, v232, v233
	v_cvt_pk_bf16_f32 v92, v92, v93
	v_cvt_pk_bf16_f32 v93, v94, v95
	v_cvt_pk_bf16_f32 v94, v88, v89
	v_cvt_pk_bf16_f32 v95, v90, v91
	v_add_u32_e32 v250, 0x10000, v172
	global_store_dwordx4 v250, v[92:95], s[0:1] sc1
	v_mul_f32_e32 v84, v84, v253
	v_mul_f32_e32 v85, v85, v253
	v_mul_f32_e32 v86, v86, v253
	v_mul_f32_e32 v87, v87, v253
	v_exp_f32_e32 v84, v84
	v_exp_f32_e32 v85, v85
	v_exp_f32_e32 v86, v86
	v_exp_f32_e32 v87, v87
	v_add_f32_e32 v84, 1.0, v84
	v_add_f32_e32 v85, 1.0, v85
	v_add_f32_e32 v86, 1.0, v86
	v_add_f32_e32 v87, 1.0, v87
	v_rcp_f32_e32 v84, v84
	v_rcp_f32_e32 v85, v85
	v_rcp_f32_e32 v86, v86
	v_rcp_f32_e32 v87, v87
	v_lshlrev_b32_e32 v224, 16, v204
	v_and_b32_e32 v225, 0xffff0000, v204
	v_lshlrev_b32_e32 v226, 16, v205
	v_and_b32_e32 v227, 0xffff0000, v205
	v_lshlrev_b32_e32 v228, 16, v212
	v_and_b32_e32 v229, 0xffff0000, v212
	v_lshlrev_b32_e32 v230, 16, v213
	v_and_b32_e32 v231, 0xffff0000, v213
	v_fma_f32 v84, v84, v228, v224
	v_fma_f32 v85, v85, v229, v225
	v_fma_f32 v86, v86, v230, v226
	v_fma_f32 v87, v87, v231, v227
	v_mul_f32_e32 v232, v85, v85
	v_mul_f32_e32 v233, v87, v87
	v_fmac_f32_e32 v232, v84, v84
	v_fmac_f32_e32 v233, v86, v86
	v_add_f32_e32 v248, v232, v233
	v_mul_f32_e32 v80, v80, v253
	v_mul_f32_e32 v81, v81, v253
	v_mul_f32_e32 v82, v82, v253
	v_mul_f32_e32 v83, v83, v253
	v_exp_f32_e32 v80, v80
	v_exp_f32_e32 v81, v81
	v_exp_f32_e32 v82, v82
	v_exp_f32_e32 v83, v83
	v_add_f32_e32 v80, 1.0, v80
	v_add_f32_e32 v81, 1.0, v81
	v_add_f32_e32 v82, 1.0, v82
	v_add_f32_e32 v83, 1.0, v83
	v_rcp_f32_e32 v80, v80
	v_rcp_f32_e32 v81, v81
	v_rcp_f32_e32 v82, v82
	v_rcp_f32_e32 v83, v83
	v_lshlrev_b32_e32 v224, 16, v206
	v_and_b32_e32 v225, 0xffff0000, v206
	v_lshlrev_b32_e32 v226, 16, v207
	v_and_b32_e32 v227, 0xffff0000, v207
	v_lshlrev_b32_e32 v228, 16, v214
	v_and_b32_e32 v229, 0xffff0000, v214
	v_lshlrev_b32_e32 v230, 16, v215
	v_and_b32_e32 v231, 0xffff0000, v215
	v_fma_f32 v80, v80, v228, v224
	v_fma_f32 v81, v81, v229, v225
	v_fma_f32 v82, v82, v230, v226
	v_fma_f32 v83, v83, v231, v227
	v_mul_f32_e32 v232, v81, v81
	v_mul_f32_e32 v233, v83, v83
	v_fmac_f32_e32 v232, v80, v80
	v_fmac_f32_e32 v233, v82, v82
	v_add_f32_e32 v249, v232, v233
	v_cvt_pk_bf16_f32 v84, v84, v85
	v_cvt_pk_bf16_f32 v85, v86, v87
	v_cvt_pk_bf16_f32 v86, v80, v81
	v_cvt_pk_bf16_f32 v87, v82, v83
	global_store_dwordx4 v250, v[84:87], s[0:1] offset:256 sc1
	v_add_f32_e32 v234, v234, v235
	v_add_f32_e32 v248, v248, v249
	v_add_f32_e32 v247, v234, v248
	ds_bpermute_b32 v252, v236, v247
	v_add_u32_e32 v251, 0x800, v194
	s_waitcnt lgkmcnt(0)
; __device__ __forceinline__ u32x4 pack8(const f32x4 v0, const f32x4 v1) { u32x4 w; w.x = cvt_pk_bf16(v0[0], v0[1]); w.y = cvt_pk_bf16(v0[2], v0[3]); w.z = cvt_pk_bf16(v1[0], v1[1]); w.w = cvt_pk_bf16(v1[2], v1[3]); return w; }
; __device__ __forceinline__ float sumsq8(const f32x4 a, const f32x4 b) { return ((a[0] * a[0] + a[1] * a[1]) + (a[2] * a[2] + a[3] * a[3])) + ((b[0] * b[0] + b[1] * b[1]) + (b[2] * b[2] + b[3] * b[3])); }
; __device__ __forceinline__ void unpack8(const u32x4 w, f32x4& a, f32x4& b) { a = (f32x4){bf_lo(w.x), bf_hi(w.x), bf_lo(w.y), bf_hi(w.y)}; b = (f32x4){bf_lo(w.z), bf_hi(w.z), bf_lo(w.w), bf_hi(w.w)}; }
;     __device__ __forceinline__ void operator()(const f32x4 (&acc)[2][2][4][2], const Unit& u, int wr, int wc, int fr, int fq) const {
;     ...
;             for (int mm = 0; mm < 2; ++mm) { const int rowl = row0 + ai * HALF + (2 * mh + mm) * 16; p[mm] = *(const f32x4*)(ssq_in + (size_t)rowl * 16 + 4 * fq);
; #pragma unroll
;                 for (int bj = 0; bj < 2; ++bj) { const size_t off = (size_t)rowl * DMODEL + col0 + bj * HALF; rv[mm][bj] = *(const u32x4*)(Rin + off); pw[mm][bj] = *(const u32x4*)(PP + off); } }
; #pragma unroll
;             for (int mm = 0; mm < 2; ++mm) { const int m = 2 * mh + mm; const int row = row0 + ai * HALF + m * 16; float part = 0.f;
;                 float sr = (p[mm][0] + p[mm][1]) + (p[mm][2] + p[mm][3]); sr += __shfl_xor(sr, 16); sr += __shfl_xor(sr, 32); const float r = __builtin_amdgcn_rsqf(sr * (1.0f / DMODEL) + RMS_EPS);
; #pragma unroll
;                 for (int bj = 0; bj < 2; ++bj) { f32x4 r0, r1, p0, p1; unpack8(rv[mm][bj], r0, r1); unpack8(pw[mm][bj], p0, p1);
;                     f32x4 g0 = acc[ai][bj][m][0] * r, g1 = acc[ai][bj][m][1] * r;
; #pragma unroll
;                     for (int e = 0; e < 4; ++e) { g0[e] = __builtin_amdgcn_rcpf(1.f + __builtin_amdgcn_exp2f(-1.4426950408889634f * g0[e])); g1[e] = __builtin_amdgcn_rcpf(1.f + __builtin_amdgcn_exp2f(-1.4426950408889634f * g1[e])); }
;                     const f32x4 h0 = r0 + g0 * p0, h1 = r1 + g1 * p1; part += sumsq8(h0, h1);
;                     *(u32x4*)(XBo + (size_t)row * DMODEL + col0 + bj * HALF) = pack8(h0, h1); }
;                 part += __shfl_xor(part, 16); part += __shfl_xor(part, 32);
;                 if (fq == 0) ssq_out[(size_t)row * 16 + u.pn * 4 + wc] = part; }
	v_add_f32_e32 v247, v247, v252
	ds_bpermute_b32 v252, v237, v247
	s_waitcnt lgkmcnt(0)
	v_add_f32_e32 v247, v247, v252
	s_and_saveexec_b64 s[28:29], vcc
	global_store_dword v251, v247, s[12:13]
	s_or_b64 exec, exec, s[28:29]
	v_add_u32_e32 v250, 0x58000, v172
	v_add_u32_e32 v251, 0x2c00, v173
	global_load_dwordx4 v[184:187], v251, s[10:11]
	global_load_dwordx4 v[188:191], v250, s[6:7]
	global_load_dwordx4 v[208:211], v250, s[2:3]
	global_load_dwordx4 v[204:207], v250, s[6:7] offset:256
	global_load_dwordx4 v[212:215], v250, s[2:3] offset:256
	s_waitcnt vmcnt(26)
	v_add_f32_e32 v247, v128, v129
	v_add_f32_e32 v252, v130, v131
	v_add_f32_e32 v247, v247, v252
	ds_bpermute_b32 v252, v236, v247
	s_waitcnt lgkmcnt(0)
	v_add_f32_e32 v247, v247, v252
	ds_bpermute_b32 v252, v237, v247
	s_waitcnt lgkmcnt(0)
	v_add_f32_e32 v247, v247, v252
	v_fmamk_f32 v247, v247, 0x3a800000, v193
	v_rsq_f32_e32 v247, v247
	s_nop 0
	v_mul_f32_e32 v253, 0xbfb8aa3b, v247
	v_mul_f32_e32 v76, v76, v253
	v_mul_f32_e32 v77, v77, v253
	v_mul_f32_e32 v78, v78, v253
	v_mul_f32_e32 v79, v79, v253
	v_exp_f32_e32 v76, v76
	v_exp_f32_e32 v77, v77
	v_exp_f32_e32 v78, v78
	v_exp_f32_e32 v79, v79
	v_add_f32_e32 v76, 1.0, v76
	v_add_f32_e32 v77, 1.0, v77
	v_add_f32_e32 v78, 1.0, v78
	v_add_f32_e32 v79, 1.0, v79
	v_rcp_f32_e32 v76, v76
	v_rcp_f32_e32 v77, v77
	v_rcp_f32_e32 v78, v78
	v_rcp_f32_e32 v79, v79
	v_lshlrev_b32_e32 v224, 16, v132
	v_and_b32_e32 v225, 0xffff0000, v132
	v_lshlrev_b32_e32 v226, 16, v133
	v_and_b32_e32 v227, 0xffff0000, v133
	v_lshlrev_b32_e32 v228, 16, v140
	v_and_b32_e32 v229, 0xffff0000, v140
	v_lshlrev_b32_e32 v230, 16, v141
	v_and_b32_e32 v231, 0xffff0000, v141
	v_fma_f32 v76, v76, v228, v224
	v_fma_f32 v77, v77, v229, v225
	v_fma_f32 v78, v78, v230, v226
	v_fma_f32 v79, v79, v231, v227
	v_mul_f32_e32 v232, v77, v77
	v_mul_f32_e32 v233, v79, v79
	v_fmac_f32_e32 v232, v76, v76
	v_fmac_f32_e32 v233, v78, v78
	v_add_f32_e32 v234, v232, v233
	v_mul_f32_e32 v72, v72, v253
	v_mul_f32_e32 v73, v73, v253
	v_mul_f32_e32 v74, v74, v253
	v_mul_f32_e32 v75, v75, v253
	v_exp_f32_e32 v72, v72
	v_exp_f32_e32 v73, v73
	v_exp_f32_e32 v74, v74
	v_exp_f32_e32 v75, v75
	v_add_f32_e32 v72, 1.0, v72
	v_add_f32_e32 v73, 1.0, v73
	v_add_f32_e32 v74, 1.0, v74
	v_add_f32_e32 v75, 1.0, v75
	v_rcp_f32_e32 v72, v72
	v_rcp_f32_e32 v73, v73
	v_rcp_f32_e32 v74, v74
	v_rcp_f32_e32 v75, v75
	v_lshlrev_b32_e32 v224, 16, v134
	v_and_b32_e32 v225, 0xffff0000, v134
	v_lshlrev_b32_e32 v226, 16, v135
	v_and_b32_e32 v227, 0xffff0000, v135
	v_lshlrev_b32_e32 v228, 16, v142
	v_and_b32_e32 v229, 0xffff0000, v142
	v_lshlrev_b32_e32 v230, 16, v143
	v_and_b32_e32 v231, 0xffff0000, v143
	v_fma_f32 v72, v72, v228, v224
	v_fma_f32 v73, v73, v229, v225
	v_fma_f32 v74, v74, v230, v226
	v_fma_f32 v75, v75, v231, v227
	v_mul_f32_e32 v232, v73, v73
	v_mul_f32_e32 v233, v75, v75
	v_fmac_f32_e32 v232, v72, v72
	v_fmac_f32_e32 v233, v74, v74
	v_add_f32_e32 v235, v232, v233
	v_cvt_pk_bf16_f32 v76, v76, v77
	v_cvt_pk_bf16_f32 v77, v78, v79
	v_cvt_pk_bf16_f32 v78, v72, v73
	v_cvt_pk_bf16_f32 v79, v74, v75
	v_add_u32_e32 v250, 0x18000, v172
	global_store_dwordx4 v250, v[76:79], s[0:1] sc1
	v_mul_f32_e32 v68, v68, v253
	v_mul_f32_e32 v69, v69, v253
	v_mul_f32_e32 v70, v70, v253
	v_mul_f32_e32 v71, v71, v253
	v_exp_f32_e32 v68, v68
	v_exp_f32_e32 v69, v69
	v_exp_f32_e32 v70, v70
	v_exp_f32_e32 v71, v71
	v_add_f32_e32 v68, 1.0, v68
	v_add_f32_e32 v69, 1.0, v69
	v_add_f32_e32 v70, 1.0, v70
	v_add_f32_e32 v71, 1.0, v71
	v_rcp_f32_e32 v68, v68
	v_rcp_f32_e32 v69, v69
	v_rcp_f32_e32 v70, v70
	v_rcp_f32_e32 v71, v71
	v_lshlrev_b32_e32 v224, 16, v136
	v_and_b32_e32 v225, 0xffff0000, v136
	v_lshlrev_b32_e32 v226, 16, v137
	v_and_b32_e32 v227, 0xffff0000, v137
	v_lshlrev_b32_e32 v228, 16, v144
	v_and_b32_e32 v229, 0xffff0000, v144
	v_lshlrev_b32_e32 v230, 16, v145
	v_and_b32_e32 v231, 0xffff0000, v145
	v_fma_f32 v68, v68, v228, v224
	v_fma_f32 v69, v69, v229, v225
	v_fma_f32 v70, v70, v230, v226
	v_fma_f32 v71, v71, v231, v227
	v_mul_f32_e32 v232, v69, v69
	v_mul_f32_e32 v233, v71, v71
	v_fmac_f32_e32 v232, v68, v68
	v_fmac_f32_e32 v233, v70, v70
	v_add_f32_e32 v248, v232, v233
	v_mul_f32_e32 v64, v64, v253
	v_mul_f32_e32 v65, v65, v253
	v_mul_f32_e32 v66, v66, v253
	v_mul_f32_e32 v67, v67, v253
	v_exp_f32_e32 v64, v64
	v_exp_f32_e32 v65, v65
	v_exp_f32_e32 v66, v66
	v_exp_f32_e32 v67, v67
	v_add_f32_e32 v64, 1.0, v64
	v_add_f32_e32 v65, 1.0, v65
	v_add_f32_e32 v66, 1.0, v66
	v_add_f32_e32 v67, 1.0, v67
	v_rcp_f32_e32 v64, v64
	v_rcp_f32_e32 v65, v65
	v_rcp_f32_e32 v66, v66
	v_rcp_f32_e32 v67, v67
	v_lshlrev_b32_e32 v224, 16, v138
	v_and_b32_e32 v225, 0xffff0000, v138
	v_lshlrev_b32_e32 v226, 16, v139
	v_and_b32_e32 v227, 0xffff0000, v139
	v_lshlrev_b32_e32 v228, 16, v146
	v_and_b32_e32 v229, 0xffff0000, v146
	v_lshlrev_b32_e32 v230, 16, v147
	v_and_b32_e32 v231, 0xffff0000, v147
	v_fma_f32 v64, v64, v228, v224
	v_fma_f32 v65, v65, v229, v225
	v_fma_f32 v66, v66, v230, v226
	v_fma_f32 v67, v67, v231, v227
	v_mul_f32_e32 v232, v65, v65
	v_mul_f32_e32 v233, v67, v67
	v_fmac_f32_e32 v232, v64, v64
	v_fmac_f32_e32 v233, v66, v66
	v_add_f32_e32 v249, v232, v233
	v_cvt_pk_bf16_f32 v68, v68, v69
	v_cvt_pk_bf16_f32 v69, v70, v71
	v_cvt_pk_bf16_f32 v70, v64, v65
	v_cvt_pk_bf16_f32 v71, v66, v67
	global_store_dwordx4 v250, v[68:71], s[0:1] offset:256 sc1
	v_add_f32_e32 v234, v234, v235
	v_add_f32_e32 v248, v248, v249
	v_add_f32_e32 v247, v234, v248
	ds_bpermute_b32 v252, v236, v247
	v_add_u32_e32 v251, 0xc00, v194
	s_waitcnt lgkmcnt(0)
	v_add_f32_e32 v247, v247, v252
	ds_bpermute_b32 v252, v237, v247
	s_waitcnt lgkmcnt(0)
; __device__ __forceinline__ u32x4 pack8(const f32x4 v0, const f32x4 v1) { u32x4 w; w.x = cvt_pk_bf16(v0[0], v0[1]); w.y = cvt_pk_bf16(v0[2], v0[3]); w.z = cvt_pk_bf16(v1[0], v1[1]); w.w = cvt_pk_bf16(v1[2], v1[3]); return w; }
; __device__ __forceinline__ float sumsq8(const f32x4 a, const f32x4 b) { return ((a[0] * a[0] + a[1] * a[1]) + (a[2] * a[2] + a[3] * a[3])) + ((b[0] * b[0] + b[1] * b[1]) + (b[2] * b[2] + b[3] * b[3])); }
; __device__ __forceinline__ void unpack8(const u32x4 w, f32x4& a, f32x4& b) { a = (f32x4){bf_lo(w.x), bf_hi(w.x), bf_lo(w.y), bf_hi(w.y)}; b = (f32x4){bf_lo(w.z), bf_hi(w.z), bf_lo(w.w), bf_hi(w.w)}; }
;     __device__ __forceinline__ void operator()(const f32x4 (&acc)[2][2][4][2], const Unit& u, int wr, int wc, int fr, int fq) const {
;     ...
;             for (int mm = 0; mm < 2; ++mm) { const int rowl = row0 + ai * HALF + (2 * mh + mm) * 16; p[mm] = *(const f32x4*)(ssq_in + (size_t)rowl * 16 + 4 * fq);
; #pragma unroll
;                 for (int bj = 0; bj < 2; ++bj) { const size_t off = (size_t)rowl * DMODEL + col0 + bj * HALF; rv[mm][bj] = *(const u32x4*)(Rin + off); pw[mm][bj] = *(const u32x4*)(PP + off); } }
; #pragma unroll
;             for (int mm = 0; mm < 2; ++mm) { const int m = 2 * mh + mm; const int row = row0 + ai * HALF + m * 16; float part = 0.f;
;                 float sr = (p[mm][0] + p[mm][1]) + (p[mm][2] + p[mm][3]); sr += __shfl_xor(sr, 16); sr += __shfl_xor(sr, 32); const float r = __builtin_amdgcn_rsqf(sr * (1.0f / DMODEL) + RMS_EPS);
; #pragma unroll
;                 for (int bj = 0; bj < 2; ++bj) { f32x4 r0, r1, p0, p1; unpack8(rv[mm][bj], r0, r1); unpack8(pw[mm][bj], p0, p1);
;                     f32x4 g0 = acc[ai][bj][m][0] * r, g1 = acc[ai][bj][m][1] * r;
; #pragma unroll
;                     for (int e = 0; e < 4; ++e) { g0[e] = __builtin_amdgcn_rcpf(1.f + __builtin_amdgcn_exp2f(-1.4426950408889634f * g0[e])); g1[e] = __builtin_amdgcn_rcpf(1.f + __builtin_amdgcn_exp2f(-1.4426950408889634f * g1[e])); }
;                     const f32x4 h0 = r0 + g0 * p0, h1 = r1 + g1 * p1; part += sumsq8(h0, h1);
;                     *(u32x4*)(XBo + (size_t)row * DMODEL + col0 + bj * HALF) = pack8(h0, h1); }
;                 part += __shfl_xor(part, 16); part += __shfl_xor(part, 32);
;                 if (fq == 0) ssq_out[(size_t)row * 16 + u.pn * 4 + wc] = part; }
	v_add_f32_e32 v247, v247, v252
	s_and_saveexec_b64 s[28:29], vcc
	global_store_dword v251, v247, s[12:13]
	s_or_b64 exec, exec, s[28:29]
	s_waitcnt vmcnt(24)
	v_add_f32_e32 v247, v124, v125
	v_add_f32_e32 v252, v126, v127
	v_add_f32_e32 v247, v247, v252
	ds_bpermute_b32 v252, v236, v247
	s_waitcnt lgkmcnt(0)
	v_add_f32_e32 v247, v247, v252
	ds_bpermute_b32 v252, v237, v247
	s_waitcnt lgkmcnt(0)
	v_add_f32_e32 v247, v247, v252
	v_fmamk_f32 v247, v247, 0x3a800000, v193
	v_rsq_f32_e32 v247, v247
	s_nop 0
	v_mul_f32_e32 v253, 0xbfb8aa3b, v247
	v_mul_f32_e32 v60, v60, v253
	v_mul_f32_e32 v61, v61, v253
	v_mul_f32_e32 v62, v62, v253
	v_mul_f32_e32 v63, v63, v253
	v_exp_f32_e32 v60, v60
	v_exp_f32_e32 v61, v61
	v_exp_f32_e32 v62, v62
	v_exp_f32_e32 v63, v63
	v_add_f32_e32 v60, 1.0, v60
	v_add_f32_e32 v61, 1.0, v61
	v_add_f32_e32 v62, 1.0, v62
	v_add_f32_e32 v63, 1.0, v63
	v_rcp_f32_e32 v60, v60
	v_rcp_f32_e32 v61, v61
	v_rcp_f32_e32 v62, v62
	v_rcp_f32_e32 v63, v63
	v_lshlrev_b32_e32 v224, 16, v120
	v_and_b32_e32 v225, 0xffff0000, v120
	v_lshlrev_b32_e32 v226, 16, v121
	v_and_b32_e32 v227, 0xffff0000, v121
	v_lshlrev_b32_e32 v228, 16, v112
	v_and_b32_e32 v229, 0xffff0000, v112
	v_lshlrev_b32_e32 v230, 16, v113
	v_and_b32_e32 v231, 0xffff0000, v113
	v_fma_f32 v60, v60, v228, v224
	v_fma_f32 v61, v61, v229, v225
	v_fma_f32 v62, v62, v230, v226
	v_fma_f32 v63, v63, v231, v227
	v_mul_f32_e32 v232, v61, v61
	v_mul_f32_e32 v233, v63, v63
	v_fmac_f32_e32 v232, v60, v60
	v_fmac_f32_e32 v233, v62, v62
	v_add_f32_e32 v234, v232, v233
	v_mul_f32_e32 v56, v56, v253
	v_mul_f32_e32 v57, v57, v253
	v_mul_f32_e32 v58, v58, v253
	v_mul_f32_e32 v59, v59, v253
	v_exp_f32_e32 v56, v56
	v_exp_f32_e32 v57, v57
	v_exp_f32_e32 v58, v58
	v_exp_f32_e32 v59, v59
	v_add_f32_e32 v56, 1.0, v56
	v_add_f32_e32 v57, 1.0, v57
	v_add_f32_e32 v58, 1.0, v58
	v_add_f32_e32 v59, 1.0, v59
	v_rcp_f32_e32 v56, v56
	v_rcp_f32_e32 v57, v57
	v_rcp_f32_e32 v58, v58
	v_rcp_f32_e32 v59, v59
	v_lshlrev_b32_e32 v224, 16, v122
	v_and_b32_e32 v225, 0xffff0000, v122
	v_lshlrev_b32_e32 v226, 16, v123
	v_and_b32_e32 v227, 0xffff0000, v123
	v_lshlrev_b32_e32 v228, 16, v114
	v_and_b32_e32 v229, 0xffff0000, v114
	v_lshlrev_b32_e32 v230, 16, v115
	v_and_b32_e32 v231, 0xffff0000, v115
	v_fma_f32 v56, v56, v228, v224
	v_fma_f32 v57, v57, v229, v225
	v_fma_f32 v58, v58, v230, v226
	v_fma_f32 v59, v59, v231, v227
	v_mul_f32_e32 v232, v57, v57
	v_mul_f32_e32 v233, v59, v59
	v_fmac_f32_e32 v232, v56, v56
	v_fmac_f32_e32 v233, v58, v58
	v_add_f32_e32 v235, v232, v233
	v_cvt_pk_bf16_f32 v60, v60, v61
	v_cvt_pk_bf16_f32 v61, v62, v63
	v_cvt_pk_bf16_f32 v62, v56, v57
	v_cvt_pk_bf16_f32 v63, v58, v59
	v_add_u32_e32 v250, 0x40000, v172
	global_store_dwordx4 v250, v[60:63], s[0:1] sc1
	v_mul_f32_e32 v52, v52, v253
	v_mul_f32_e32 v53, v53, v253
	v_mul_f32_e32 v54, v54, v253
	v_mul_f32_e32 v55, v55, v253
	v_exp_f32_e32 v52, v52
	v_exp_f32_e32 v53, v53
	v_exp_f32_e32 v54, v54
	v_exp_f32_e32 v55, v55
	v_add_f32_e32 v52, 1.0, v52
	v_add_f32_e32 v53, 1.0, v53
	v_add_f32_e32 v54, 1.0, v54
	v_add_f32_e32 v55, 1.0, v55
	v_rcp_f32_e32 v52, v52
	v_rcp_f32_e32 v53, v53
	v_rcp_f32_e32 v54, v54
	v_rcp_f32_e32 v55, v55
	v_lshlrev_b32_e32 v224, 16, v116
	v_and_b32_e32 v225, 0xffff0000, v116
	v_lshlrev_b32_e32 v226, 16, v117
	v_and_b32_e32 v227, 0xffff0000, v117
	v_lshlrev_b32_e32 v228, 16, v216
	v_and_b32_e32 v229, 0xffff0000, v216
	v_lshlrev_b32_e32 v230, 16, v217
	v_and_b32_e32 v231, 0xffff0000, v217
	v_fma_f32 v52, v52, v228, v224
	v_fma_f32 v53, v53, v229, v225
	v_fma_f32 v54, v54, v230, v226
	v_fma_f32 v55, v55, v231, v227
	v_mul_f32_e32 v232, v53, v53
	v_mul_f32_e32 v233, v55, v55
	v_fmac_f32_e32 v232, v52, v52
	v_fmac_f32_e32 v233, v54, v54
	v_add_f32_e32 v248, v232, v233
	v_mul_f32_e32 v48, v48, v253
	v_mul_f32_e32 v49, v49, v253
	v_mul_f32_e32 v50, v50, v253
	v_mul_f32_e32 v51, v51, v253
	v_exp_f32_e32 v48, v48
	v_exp_f32_e32 v49, v49
	v_exp_f32_e32 v50, v50
	v_exp_f32_e32 v51, v51
	v_add_f32_e32 v48, 1.0, v48
	v_add_f32_e32 v49, 1.0, v49
	v_add_f32_e32 v50, 1.0, v50
	v_add_f32_e32 v51, 1.0, v51
	v_rcp_f32_e32 v48, v48
	v_rcp_f32_e32 v49, v49
	v_rcp_f32_e32 v50, v50
	v_rcp_f32_e32 v51, v51
	v_lshlrev_b32_e32 v224, 16, v118
	v_and_b32_e32 v225, 0xffff0000, v118
	v_lshlrev_b32_e32 v226, 16, v119
	v_and_b32_e32 v227, 0xffff0000, v119
	v_lshlrev_b32_e32 v228, 16, v218
	v_and_b32_e32 v229, 0xffff0000, v218
	v_lshlrev_b32_e32 v230, 16, v219
	v_and_b32_e32 v231, 0xffff0000, v219
	v_fma_f32 v48, v48, v228, v224
	v_fma_f32 v49, v49, v229, v225
	v_fma_f32 v50, v50, v230, v226
	v_fma_f32 v51, v51, v231, v227
	v_mul_f32_e32 v232, v49, v49
	v_mul_f32_e32 v233, v51, v51
	v_fmac_f32_e32 v232, v48, v48
	v_fmac_f32_e32 v233, v50, v50
	v_add_f32_e32 v249, v232, v233
	v_cvt_pk_bf16_f32 v52, v52, v53
	v_cvt_pk_bf16_f32 v53, v54, v55
	v_cvt_pk_bf16_f32 v54, v48, v49
	v_cvt_pk_bf16_f32 v55, v50, v51
	global_store_dwordx4 v250, v[52:55], s[0:1] offset:256 sc1
	v_add_f32_e32 v234, v234, v235
	v_add_f32_e32 v248, v248, v249
	v_add_f32_e32 v247, v234, v248
	ds_bpermute_b32 v252, v236, v247
	v_add_u32_e32 v251, 0x2000, v194
	s_waitcnt lgkmcnt(0)
	v_add_f32_e32 v247, v247, v252
	ds_bpermute_b32 v252, v237, v247
	s_waitcnt lgkmcnt(0)
	v_add_f32_e32 v247, v247, v252
	s_and_saveexec_b64 s[28:29], vcc
	global_store_dword v251, v247, s[12:13]
	s_or_b64 exec, exec, s[28:29]
	s_waitcnt vmcnt(19)
	v_add_f32_e32 v247, v160, v161
	v_add_f32_e32 v252, v162, v163
	v_add_f32_e32 v247, v247, v252
	ds_bpermute_b32 v252, v236, v247
	s_waitcnt lgkmcnt(0)
	v_add_f32_e32 v247, v247, v252
	ds_bpermute_b32 v252, v237, v247
	s_waitcnt lgkmcnt(0)
; __device__ __forceinline__ u32x4 pack8(const f32x4 v0, const f32x4 v1) { u32x4 w; w.x = cvt_pk_bf16(v0[0], v0[1]); w.y = cvt_pk_bf16(v0[2], v0[3]); w.z = cvt_pk_bf16(v1[0], v1[1]); w.w = cvt_pk_bf16(v1[2], v1[3]); return w; }
; __device__ __forceinline__ float sumsq8(const f32x4 a, const f32x4 b) { return ((a[0] * a[0] + a[1] * a[1]) + (a[2] * a[2] + a[3] * a[3])) + ((b[0] * b[0] + b[1] * b[1]) + (b[2] * b[2] + b[3] * b[3])); }
; __device__ __forceinline__ void unpack8(const u32x4 w, f32x4& a, f32x4& b) { a = (f32x4){bf_lo(w.x), bf_hi(w.x), bf_lo(w.y), bf_hi(w.y)}; b = (f32x4){bf_lo(w.z), bf_hi(w.z), bf_lo(w.w), bf_hi(w.w)}; }
;     __device__ __forceinline__ void operator()(const f32x4 (&acc)[2][2][4][2], const Unit& u, int wr, int wc, int fr, int fq) const {
;     ...
;             for (int mm = 0; mm < 2; ++mm) { const int m = 2 * mh + mm; const int row = row0 + ai * HALF + m * 16; float part = 0.f;
;                 float sr = (p[mm][0] + p[mm][1]) + (p[mm][2] + p[mm][3]); sr += __shfl_xor(sr, 16); sr += __shfl_xor(sr, 32); const float r = __builtin_amdgcn_rsqf(sr * (1.0f / DMODEL) + RMS_EPS);
; #pragma unroll
;                 for (int bj = 0; bj < 2; ++bj) { f32x4 r0, r1, p0, p1; unpack8(rv[mm][bj], r0, r1); unpack8(pw[mm][bj], p0, p1);
;                     f32x4 g0 = acc[ai][bj][m][0] * r, g1 = acc[ai][bj][m][1] * r;
; #pragma unroll
;                     for (int e = 0; e < 4; ++e) { g0[e] = __builtin_amdgcn_rcpf(1.f + __builtin_amdgcn_exp2f(-1.4426950408889634f * g0[e])); g1[e] = __builtin_amdgcn_rcpf(1.f + __builtin_amdgcn_exp2f(-1.4426950408889634f * g1[e])); }
;                     const f32x4 h0 = r0 + g0 * p0, h1 = r1 + g1 * p1; part += sumsq8(h0, h1);
;                     *(u32x4*)(XBo + (size_t)row * DMODEL + col0 + bj * HALF) = pack8(h0, h1); }
;                 part += __shfl_xor(part, 16); part += __shfl_xor(part, 32);
;                 if (fq == 0) ssq_out[(size_t)row * 16 + u.pn * 4 + wc] = part; }
	v_add_f32_e32 v247, v247, v252
	v_fmamk_f32 v247, v247, 0x3a800000, v193
	v_rsq_f32_e32 v247, v247
	s_nop 0
	v_mul_f32_e32 v253, 0xbfb8aa3b, v247
	v_mul_f32_e32 v44, v44, v253
	v_mul_f32_e32 v45, v45, v253
	v_mul_f32_e32 v46, v46, v253
	v_mul_f32_e32 v47, v47, v253
	v_exp_f32_e32 v44, v44
	v_exp_f32_e32 v45, v45
	v_exp_f32_e32 v46, v46
	v_exp_f32_e32 v47, v47
	v_add_f32_e32 v44, 1.0, v44
	v_add_f32_e32 v45, 1.0, v45
	v_add_f32_e32 v46, 1.0, v46
	v_add_f32_e32 v47, 1.0, v47
	v_rcp_f32_e32 v44, v44
	v_rcp_f32_e32 v45, v45
	v_rcp_f32_e32 v46, v46
	v_rcp_f32_e32 v47, v47
	v_lshlrev_b32_e32 v224, 16, v164
	v_and_b32_e32 v225, 0xffff0000, v164
	v_lshlrev_b32_e32 v226, 16, v165
	v_and_b32_e32 v227, 0xffff0000, v165
	v_lshlrev_b32_e32 v228, 16, v176
	v_and_b32_e32 v229, 0xffff0000, v176
	v_lshlrev_b32_e32 v230, 16, v177
	v_and_b32_e32 v231, 0xffff0000, v177
	v_fma_f32 v44, v44, v228, v224
	v_fma_f32 v45, v45, v229, v225
	v_fma_f32 v46, v46, v230, v226
	v_fma_f32 v47, v47, v231, v227
	v_mul_f32_e32 v232, v45, v45
	v_mul_f32_e32 v233, v47, v47
	v_fmac_f32_e32 v232, v44, v44
	v_fmac_f32_e32 v233, v46, v46
	v_add_f32_e32 v234, v232, v233
	v_mul_f32_e32 v40, v40, v253
	v_mul_f32_e32 v41, v41, v253
	v_mul_f32_e32 v42, v42, v253
	v_mul_f32_e32 v43, v43, v253
	v_exp_f32_e32 v40, v40
	v_exp_f32_e32 v41, v41
	v_exp_f32_e32 v42, v42
	v_exp_f32_e32 v43, v43
	v_add_f32_e32 v40, 1.0, v40
	v_add_f32_e32 v41, 1.0, v41
	v_add_f32_e32 v42, 1.0, v42
	v_add_f32_e32 v43, 1.0, v43
	v_rcp_f32_e32 v40, v40
	v_rcp_f32_e32 v41, v41
	v_rcp_f32_e32 v42, v42
	v_rcp_f32_e32 v43, v43
	v_lshlrev_b32_e32 v224, 16, v166
	v_and_b32_e32 v225, 0xffff0000, v166
	v_lshlrev_b32_e32 v226, 16, v167
	v_and_b32_e32 v227, 0xffff0000, v167
	v_lshlrev_b32_e32 v228, 16, v178
	v_and_b32_e32 v229, 0xffff0000, v178
	v_lshlrev_b32_e32 v230, 16, v179
	v_and_b32_e32 v231, 0xffff0000, v179
	v_fma_f32 v40, v40, v228, v224
	v_fma_f32 v41, v41, v229, v225
	v_fma_f32 v42, v42, v230, v226
	v_fma_f32 v43, v43, v231, v227
	v_mul_f32_e32 v232, v41, v41
	v_mul_f32_e32 v233, v43, v43
	v_fmac_f32_e32 v232, v40, v40
	v_fmac_f32_e32 v233, v42, v42
	v_add_f32_e32 v235, v232, v233
	v_cvt_pk_bf16_f32 v44, v44, v45
	v_cvt_pk_bf16_f32 v45, v46, v47
	v_cvt_pk_bf16_f32 v46, v40, v41
	v_cvt_pk_bf16_f32 v47, v42, v43
	v_add_u32_e32 v250, 0x48000, v172
	global_store_dwordx4 v250, v[44:47], s[0:1] sc1
	v_mul_f32_e32 v36, v36, v253
	v_mul_f32_e32 v37, v37, v253
	v_mul_f32_e32 v38, v38, v253
	v_mul_f32_e32 v39, v39, v253
	v_exp_f32_e32 v36, v36
	v_exp_f32_e32 v37, v37
	v_exp_f32_e32 v38, v38
	v_exp_f32_e32 v39, v39
	v_add_f32_e32 v36, 1.0, v36
	v_add_f32_e32 v37, 1.0, v37
	v_add_f32_e32 v38, 1.0, v38
	v_add_f32_e32 v39, 1.0, v39
	v_rcp_f32_e32 v36, v36
	v_rcp_f32_e32 v37, v37
	v_rcp_f32_e32 v38, v38
	v_rcp_f32_e32 v39, v39
	v_lshlrev_b32_e32 v224, 16, v168
	v_and_b32_e32 v225, 0xffff0000, v168
	v_lshlrev_b32_e32 v226, 16, v169
	v_and_b32_e32 v227, 0xffff0000, v169
	v_lshlrev_b32_e32 v228, 16, v180
	v_and_b32_e32 v229, 0xffff0000, v180
	v_lshlrev_b32_e32 v230, 16, v181
	v_and_b32_e32 v231, 0xffff0000, v181
	v_fma_f32 v36, v36, v228, v224
	v_fma_f32 v37, v37, v229, v225
	v_fma_f32 v38, v38, v230, v226
	v_fma_f32 v39, v39, v231, v227
	v_mul_f32_e32 v232, v37, v37
	v_mul_f32_e32 v233, v39, v39
	v_fmac_f32_e32 v232, v36, v36
	v_fmac_f32_e32 v233, v38, v38
	v_add_f32_e32 v248, v232, v233
	v_mul_f32_e32 v32, v32, v253
	v_mul_f32_e32 v33, v33, v253
	v_mul_f32_e32 v34, v34, v253
	v_mul_f32_e32 v35, v35, v253
	v_exp_f32_e32 v32, v32
	v_exp_f32_e32 v33, v33
	v_exp_f32_e32 v34, v34
	v_exp_f32_e32 v35, v35
	v_add_f32_e32 v32, 1.0, v32
	v_add_f32_e32 v33, 1.0, v33
	v_add_f32_e32 v34, 1.0, v34
	v_add_f32_e32 v35, 1.0, v35
	v_rcp_f32_e32 v32, v32
	v_rcp_f32_e32 v33, v33
	v_rcp_f32_e32 v34, v34
	v_rcp_f32_e32 v35, v35
	v_lshlrev_b32_e32 v224, 16, v170
	v_and_b32_e32 v225, 0xffff0000, v170
	v_lshlrev_b32_e32 v226, 16, v171
	v_and_b32_e32 v227, 0xffff0000, v171
	v_lshlrev_b32_e32 v228, 16, v182
	v_and_b32_e32 v229, 0xffff0000, v182
	v_lshlrev_b32_e32 v230, 16, v183
	v_and_b32_e32 v231, 0xffff0000, v183
	v_fma_f32 v32, v32, v228, v224
	v_fma_f32 v33, v33, v229, v225
	v_fma_f32 v34, v34, v230, v226
	v_fma_f32 v35, v35, v231, v227
	v_mul_f32_e32 v232, v33, v33
	v_mul_f32_e32 v233, v35, v35
	v_fmac_f32_e32 v232, v32, v32
	v_fmac_f32_e32 v233, v34, v34
	v_add_f32_e32 v249, v232, v233
	v_cvt_pk_bf16_f32 v36, v36, v37
	v_cvt_pk_bf16_f32 v37, v38, v39
	v_cvt_pk_bf16_f32 v38, v32, v33
	v_cvt_pk_bf16_f32 v39, v34, v35
	global_store_dwordx4 v250, v[36:39], s[0:1] offset:256 sc1
	v_add_f32_e32 v234, v234, v235
	v_add_f32_e32 v248, v248, v249
	v_add_f32_e32 v247, v234, v248
	ds_bpermute_b32 v252, v236, v247
	v_add_u32_e32 v251, 0x2400, v194
	s_waitcnt lgkmcnt(0)
	v_add_f32_e32 v247, v247, v252
	ds_bpermute_b32 v252, v237, v247
	s_waitcnt lgkmcnt(0)
	v_add_f32_e32 v247, v247, v252
	s_and_saveexec_b64 s[28:29], vcc
	global_store_dword v251, v247, s[12:13]
	s_or_b64 exec, exec, s[28:29]
	s_waitcnt vmcnt(17)
	v_add_f32_e32 v247, v108, v109
	v_add_f32_e32 v252, v110, v111
	v_add_f32_e32 v247, v247, v252
	ds_bpermute_b32 v252, v236, v247
	s_waitcnt lgkmcnt(0)
	v_add_f32_e32 v247, v247, v252
	ds_bpermute_b32 v252, v237, v247
	s_waitcnt lgkmcnt(0)
; __device__ __forceinline__ u32x4 pack8(const f32x4 v0, const f32x4 v1) { u32x4 w; w.x = cvt_pk_bf16(v0[0], v0[1]); w.y = cvt_pk_bf16(v0[2], v0[3]); w.z = cvt_pk_bf16(v1[0], v1[1]); w.w = cvt_pk_bf16(v1[2], v1[3]); return w; }
; __device__ __forceinline__ float sumsq8(const f32x4 a, const f32x4 b) { return ((a[0] * a[0] + a[1] * a[1]) + (a[2] * a[2] + a[3] * a[3])) + ((b[0] * b[0] + b[1] * b[1]) + (b[2] * b[2] + b[3] * b[3])); }
; __device__ __forceinline__ void unpack8(const u32x4 w, f32x4& a, f32x4& b) { a = (f32x4){bf_lo(w.x), bf_hi(w.x), bf_lo(w.y), bf_hi(w.y)}; b = (f32x4){bf_lo(w.z), bf_hi(w.z), bf_lo(w.w), bf_hi(w.w)}; }
;     __device__ __forceinline__ void operator()(const f32x4 (&acc)[2][2][4][2], const Unit& u, int wr, int wc, int fr, int fq) const {
;     ...
;             for (int mm = 0; mm < 2; ++mm) { const int m = 2 * mh + mm; const int row = row0 + ai * HALF + m * 16; float part = 0.f;
;                 float sr = (p[mm][0] + p[mm][1]) + (p[mm][2] + p[mm][3]); sr += __shfl_xor(sr, 16); sr += __shfl_xor(sr, 32); const float r = __builtin_amdgcn_rsqf(sr * (1.0f / DMODEL) + RMS_EPS);
; #pragma unroll
;                 for (int bj = 0; bj < 2; ++bj) { f32x4 r0, r1, p0, p1; unpack8(rv[mm][bj], r0, r1); unpack8(pw[mm][bj], p0, p1);
;                     f32x4 g0 = acc[ai][bj][m][0] * r, g1 = acc[ai][bj][m][1] * r;
; #pragma unroll
;                     for (int e = 0; e < 4; ++e) { g0[e] = __builtin_amdgcn_rcpf(1.f + __builtin_amdgcn_exp2f(-1.4426950408889634f * g0[e])); g1[e] = __builtin_amdgcn_rcpf(1.f + __builtin_amdgcn_exp2f(-1.4426950408889634f * g1[e])); }
;                     const f32x4 h0 = r0 + g0 * p0, h1 = r1 + g1 * p1; part += sumsq8(h0, h1);
;                     *(u32x4*)(XBo + (size_t)row * DMODEL + col0 + bj * HALF) = pack8(h0, h1); }
;                 part += __shfl_xor(part, 16); part += __shfl_xor(part, 32);
;                 if (fq == 0) ssq_out[(size_t)row * 16 + u.pn * 4 + wc] = part; }
	v_add_f32_e32 v247, v247, v252
	v_fmamk_f32 v247, v247, 0x3a800000, v193
	v_rsq_f32_e32 v247, v247
	s_nop 0
	v_mul_f32_e32 v253, 0xbfb8aa3b, v247
	v_mul_f32_e32 v28, v28, v253
	v_mul_f32_e32 v29, v29, v253
	v_mul_f32_e32 v30, v30, v253
	v_mul_f32_e32 v31, v31, v253
	v_exp_f32_e32 v28, v28
	v_exp_f32_e32 v29, v29
	v_exp_f32_e32 v30, v30
	v_exp_f32_e32 v31, v31
	v_add_f32_e32 v28, 1.0, v28
	v_add_f32_e32 v29, 1.0, v29
	v_add_f32_e32 v30, 1.0, v30
	v_add_f32_e32 v31, 1.0, v31
	v_rcp_f32_e32 v28, v28
	v_rcp_f32_e32 v29, v29
	v_rcp_f32_e32 v30, v30
	v_rcp_f32_e32 v31, v31
	v_lshlrev_b32_e32 v224, 16, v104
	v_and_b32_e32 v225, 0xffff0000, v104
	v_lshlrev_b32_e32 v226, 16, v105
	v_and_b32_e32 v227, 0xffff0000, v105
	v_lshlrev_b32_e32 v228, 16, v96
	v_and_b32_e32 v229, 0xffff0000, v96
	v_lshlrev_b32_e32 v230, 16, v97
	v_and_b32_e32 v231, 0xffff0000, v97
	v_fma_f32 v28, v28, v228, v224
	v_fma_f32 v29, v29, v229, v225
	v_fma_f32 v30, v30, v230, v226
	v_fma_f32 v31, v31, v231, v227
	v_mul_f32_e32 v232, v29, v29
	v_mul_f32_e32 v233, v31, v31
	v_fmac_f32_e32 v232, v28, v28
	v_fmac_f32_e32 v233, v30, v30
	v_add_f32_e32 v234, v232, v233
	v_mul_f32_e32 v24, v24, v253
	v_mul_f32_e32 v25, v25, v253
	v_mul_f32_e32 v26, v26, v253
	v_mul_f32_e32 v27, v27, v253
	v_exp_f32_e32 v24, v24
	v_exp_f32_e32 v25, v25
	v_exp_f32_e32 v26, v26
	v_exp_f32_e32 v27, v27
	v_add_f32_e32 v24, 1.0, v24
	v_add_f32_e32 v25, 1.0, v25
	v_add_f32_e32 v26, 1.0, v26
	v_add_f32_e32 v27, 1.0, v27
	v_rcp_f32_e32 v24, v24
	v_rcp_f32_e32 v25, v25
	v_rcp_f32_e32 v26, v26
	v_rcp_f32_e32 v27, v27
	v_lshlrev_b32_e32 v224, 16, v106
	v_and_b32_e32 v225, 0xffff0000, v106
	v_lshlrev_b32_e32 v226, 16, v107
	v_and_b32_e32 v227, 0xffff0000, v107
	v_lshlrev_b32_e32 v228, 16, v98
	v_and_b32_e32 v229, 0xffff0000, v98
	v_lshlrev_b32_e32 v230, 16, v99
	v_and_b32_e32 v231, 0xffff0000, v99
	v_fma_f32 v24, v24, v228, v224
	v_fma_f32 v25, v25, v229, v225
	v_fma_f32 v26, v26, v230, v226
	v_fma_f32 v27, v27, v231, v227
	v_mul_f32_e32 v232, v25, v25
	v_mul_f32_e32 v233, v27, v27
	v_fmac_f32_e32 v232, v24, v24
	v_fmac_f32_e32 v233, v26, v26
	v_add_f32_e32 v235, v232, v233
	v_cvt_pk_bf16_f32 v28, v28, v29
	v_cvt_pk_bf16_f32 v29, v30, v31
	v_cvt_pk_bf16_f32 v30, v24, v25
	v_cvt_pk_bf16_f32 v31, v26, v27
	v_add_u32_e32 v250, 0x50000, v172
	global_store_dwordx4 v250, v[28:31], s[0:1] sc1
	v_mul_f32_e32 v20, v20, v253
	v_mul_f32_e32 v21, v21, v253
	v_mul_f32_e32 v22, v22, v253
	v_mul_f32_e32 v23, v23, v253
	v_exp_f32_e32 v20, v20
	v_exp_f32_e32 v21, v21
	v_exp_f32_e32 v22, v22
	v_exp_f32_e32 v23, v23
	v_add_f32_e32 v20, 1.0, v20
	v_add_f32_e32 v21, 1.0, v21
	v_add_f32_e32 v22, 1.0, v22
	v_add_f32_e32 v23, 1.0, v23
	v_rcp_f32_e32 v20, v20
	v_rcp_f32_e32 v21, v21
	v_rcp_f32_e32 v22, v22
	v_rcp_f32_e32 v23, v23
	v_lshlrev_b32_e32 v224, 16, v100
	v_and_b32_e32 v225, 0xffff0000, v100
	v_lshlrev_b32_e32 v226, 16, v101
	v_and_b32_e32 v227, 0xffff0000, v101
	v_lshlrev_b32_e32 v228, 16, v220
	v_and_b32_e32 v229, 0xffff0000, v220
	v_lshlrev_b32_e32 v230, 16, v221
	v_and_b32_e32 v231, 0xffff0000, v221
	v_fma_f32 v20, v20, v228, v224
	v_fma_f32 v21, v21, v229, v225
	v_fma_f32 v22, v22, v230, v226
	v_fma_f32 v23, v23, v231, v227
	v_mul_f32_e32 v232, v21, v21
	v_mul_f32_e32 v233, v23, v23
	v_fmac_f32_e32 v232, v20, v20
	v_fmac_f32_e32 v233, v22, v22
	v_add_f32_e32 v248, v232, v233
	v_mul_f32_e32 v16, v16, v253
	v_mul_f32_e32 v17, v17, v253
	v_mul_f32_e32 v18, v18, v253
	v_mul_f32_e32 v19, v19, v253
	v_exp_f32_e32 v16, v16
	v_exp_f32_e32 v17, v17
	v_exp_f32_e32 v18, v18
	v_exp_f32_e32 v19, v19
	v_add_f32_e32 v16, 1.0, v16
	v_add_f32_e32 v17, 1.0, v17
	v_add_f32_e32 v18, 1.0, v18
	v_add_f32_e32 v19, 1.0, v19
	v_rcp_f32_e32 v16, v16
	v_rcp_f32_e32 v17, v17
	v_rcp_f32_e32 v18, v18
	v_rcp_f32_e32 v19, v19
	v_lshlrev_b32_e32 v224, 16, v102
	v_and_b32_e32 v225, 0xffff0000, v102
	v_lshlrev_b32_e32 v226, 16, v103
	v_and_b32_e32 v227, 0xffff0000, v103
	v_lshlrev_b32_e32 v228, 16, v222
	v_and_b32_e32 v229, 0xffff0000, v222
	v_lshlrev_b32_e32 v230, 16, v223
	v_and_b32_e32 v231, 0xffff0000, v223
	v_fma_f32 v16, v16, v228, v224
	v_fma_f32 v17, v17, v229, v225
	v_fma_f32 v18, v18, v230, v226
	v_fma_f32 v19, v19, v231, v227
	v_mul_f32_e32 v232, v17, v17
	v_mul_f32_e32 v233, v19, v19
	v_fmac_f32_e32 v232, v16, v16
	v_fmac_f32_e32 v233, v18, v18
	v_add_f32_e32 v249, v232, v233
	v_cvt_pk_bf16_f32 v20, v20, v21
	v_cvt_pk_bf16_f32 v21, v22, v23
	v_cvt_pk_bf16_f32 v22, v16, v17
	v_cvt_pk_bf16_f32 v23, v18, v19
	global_store_dwordx4 v250, v[20:23], s[0:1] offset:256 sc1
	v_add_f32_e32 v234, v234, v235
	v_add_f32_e32 v248, v248, v249
	v_add_f32_e32 v247, v234, v248
	ds_bpermute_b32 v252, v236, v247
	v_add_u32_e32 v251, 0x2800, v194
	s_waitcnt lgkmcnt(0)
	v_add_f32_e32 v247, v247, v252
	ds_bpermute_b32 v252, v237, v247
	s_waitcnt lgkmcnt(0)
	v_add_f32_e32 v247, v247, v252
	s_and_saveexec_b64 s[28:29], vcc
	global_store_dword v251, v247, s[12:13]
	s_or_b64 exec, exec, s[28:29]
	s_waitcnt vmcnt(12)
	v_add_f32_e32 v247, v184, v185
	v_add_f32_e32 v252, v186, v187
	v_add_f32_e32 v247, v247, v252
	ds_bpermute_b32 v252, v236, v247
	s_waitcnt lgkmcnt(0)
; __device__ __forceinline__ u32x4 pack8(const f32x4 v0, const f32x4 v1) { u32x4 w; w.x = cvt_pk_bf16(v0[0], v0[1]); w.y = cvt_pk_bf16(v0[2], v0[3]); w.z = cvt_pk_bf16(v1[0], v1[1]); w.w = cvt_pk_bf16(v1[2], v1[3]); return w; }
; __device__ __forceinline__ float sumsq8(const f32x4 a, const f32x4 b) { return ((a[0] * a[0] + a[1] * a[1]) + (a[2] * a[2] + a[3] * a[3])) + ((b[0] * b[0] + b[1] * b[1]) + (b[2] * b[2] + b[3] * b[3])); }
; __device__ __forceinline__ void unpack8(const u32x4 w, f32x4& a, f32x4& b) { a = (f32x4){bf_lo(w.x), bf_hi(w.x), bf_lo(w.y), bf_hi(w.y)}; b = (f32x4){bf_lo(w.z), bf_hi(w.z), bf_lo(w.w), bf_hi(w.w)}; }
;     __device__ __forceinline__ void operator()(const f32x4 (&acc)[2][2][4][2], const Unit& u, int wr, int wc, int fr, int fq) const {
;     ...
;             for (int mm = 0; mm < 2; ++mm) { const int m = 2 * mh + mm; const int row = row0 + ai * HALF + m * 16; float part = 0.f;
;                 float sr = (p[mm][0] + p[mm][1]) + (p[mm][2] + p[mm][3]); sr += __shfl_xor(sr, 16); sr += __shfl_xor(sr, 32); const float r = __builtin_amdgcn_rsqf(sr * (1.0f / DMODEL) + RMS_EPS);
; #pragma unroll
;                 for (int bj = 0; bj < 2; ++bj) { f32x4 r0, r1, p0, p1; unpack8(rv[mm][bj], r0, r1); unpack8(pw[mm][bj], p0, p1);
;                     f32x4 g0 = acc[ai][bj][m][0] * r, g1 = acc[ai][bj][m][1] * r;
; #pragma unroll
;                     for (int e = 0; e < 4; ++e) { g0[e] = __builtin_amdgcn_rcpf(1.f + __builtin_amdgcn_exp2f(-1.4426950408889634f * g0[e])); g1[e] = __builtin_amdgcn_rcpf(1.f + __builtin_amdgcn_exp2f(-1.4426950408889634f * g1[e])); }
;                     const f32x4 h0 = r0 + g0 * p0, h1 = r1 + g1 * p1; part += sumsq8(h0, h1);
;                     *(u32x4*)(XBo + (size_t)row * DMODEL + col0 + bj * HALF) = pack8(h0, h1); }
;                 part += __shfl_xor(part, 16); part += __shfl_xor(part, 32);
;                 if (fq == 0) ssq_out[(size_t)row * 16 + u.pn * 4 + wc] = part; }
	v_add_f32_e32 v247, v247, v252
	ds_bpermute_b32 v252, v237, v247
	s_waitcnt lgkmcnt(0)
	v_add_f32_e32 v247, v247, v252
	v_fmamk_f32 v247, v247, 0x3a800000, v193
	v_rsq_f32_e32 v247, v247
	s_nop 0
	v_mul_f32_e32 v253, 0xbfb8aa3b, v247
	v_mul_f32_e32 v12, v12, v253
	v_mul_f32_e32 v13, v13, v253
	v_mul_f32_e32 v14, v14, v253
	v_mul_f32_e32 v15, v15, v253
	v_exp_f32_e32 v12, v12
	v_exp_f32_e32 v13, v13
	v_exp_f32_e32 v14, v14
	v_exp_f32_e32 v15, v15
	v_add_f32_e32 v12, 1.0, v12
	v_add_f32_e32 v13, 1.0, v13
	v_add_f32_e32 v14, 1.0, v14
	v_add_f32_e32 v15, 1.0, v15
	v_rcp_f32_e32 v12, v12
	v_rcp_f32_e32 v13, v13
	v_rcp_f32_e32 v14, v14
	v_rcp_f32_e32 v15, v15
	v_lshlrev_b32_e32 v224, 16, v188
	v_and_b32_e32 v225, 0xffff0000, v188
	v_lshlrev_b32_e32 v226, 16, v189
	v_and_b32_e32 v227, 0xffff0000, v189
	v_lshlrev_b32_e32 v228, 16, v208
	v_and_b32_e32 v229, 0xffff0000, v208
	v_lshlrev_b32_e32 v230, 16, v209
	v_and_b32_e32 v231, 0xffff0000, v209
	v_fma_f32 v12, v12, v228, v224
	v_fma_f32 v13, v13, v229, v225
	v_fma_f32 v14, v14, v230, v226
	v_fma_f32 v15, v15, v231, v227
	v_mul_f32_e32 v232, v13, v13
	v_mul_f32_e32 v233, v15, v15
	v_fmac_f32_e32 v232, v12, v12
	v_fmac_f32_e32 v233, v14, v14
	v_add_f32_e32 v234, v232, v233
	v_mul_f32_e32 v8, v8, v253
	v_mul_f32_e32 v9, v9, v253
	v_mul_f32_e32 v10, v10, v253
	v_mul_f32_e32 v11, v11, v253
	v_exp_f32_e32 v8, v8
	v_exp_f32_e32 v9, v9
	v_exp_f32_e32 v10, v10
	v_exp_f32_e32 v11, v11
	v_add_f32_e32 v8, 1.0, v8
	v_add_f32_e32 v9, 1.0, v9
	v_add_f32_e32 v10, 1.0, v10
	v_add_f32_e32 v11, 1.0, v11
	v_rcp_f32_e32 v8, v8
	v_rcp_f32_e32 v9, v9
	v_rcp_f32_e32 v10, v10
	v_rcp_f32_e32 v11, v11
	v_lshlrev_b32_e32 v224, 16, v190
	v_and_b32_e32 v225, 0xffff0000, v190
	v_lshlrev_b32_e32 v226, 16, v191
	v_and_b32_e32 v227, 0xffff0000, v191
	v_lshlrev_b32_e32 v228, 16, v210
	v_and_b32_e32 v229, 0xffff0000, v210
	v_lshlrev_b32_e32 v230, 16, v211
	v_and_b32_e32 v231, 0xffff0000, v211
	v_fma_f32 v8, v8, v228, v224
	v_fma_f32 v9, v9, v229, v225
	v_fma_f32 v10, v10, v230, v226
	v_fma_f32 v11, v11, v231, v227
	v_mul_f32_e32 v232, v9, v9
	v_mul_f32_e32 v233, v11, v11
	v_fmac_f32_e32 v232, v8, v8
	v_fmac_f32_e32 v233, v10, v10
	v_add_f32_e32 v235, v232, v233
	v_cvt_pk_bf16_f32 v12, v12, v13
	v_cvt_pk_bf16_f32 v13, v14, v15
	v_cvt_pk_bf16_f32 v14, v8, v9
	v_cvt_pk_bf16_f32 v15, v10, v11
	v_add_u32_e32 v250, 0x58000, v172
	global_store_dwordx4 v250, v[12:15], s[0:1] sc1
	v_mul_f32_e32 v4, v4, v253
	v_mul_f32_e32 v5, v5, v253
	v_mul_f32_e32 v6, v6, v253
	v_mul_f32_e32 v7, v7, v253
	v_exp_f32_e32 v4, v4
	v_exp_f32_e32 v5, v5
	v_exp_f32_e32 v6, v6
	v_exp_f32_e32 v7, v7
	v_add_f32_e32 v4, 1.0, v4
	v_add_f32_e32 v5, 1.0, v5
	v_add_f32_e32 v6, 1.0, v6
	v_add_f32_e32 v7, 1.0, v7
	v_rcp_f32_e32 v4, v4
	v_rcp_f32_e32 v5, v5
	v_rcp_f32_e32 v6, v6
	v_rcp_f32_e32 v7, v7
	v_lshlrev_b32_e32 v224, 16, v204
	v_and_b32_e32 v225, 0xffff0000, v204
	v_lshlrev_b32_e32 v226, 16, v205
	v_and_b32_e32 v227, 0xffff0000, v205
	v_lshlrev_b32_e32 v228, 16, v212
	v_and_b32_e32 v229, 0xffff0000, v212
	v_lshlrev_b32_e32 v230, 16, v213
	v_and_b32_e32 v231, 0xffff0000, v213
	v_fma_f32 v4, v4, v228, v224
	v_fma_f32 v5, v5, v229, v225
	v_fma_f32 v6, v6, v230, v226
	v_fma_f32 v7, v7, v231, v227
	v_mul_f32_e32 v232, v5, v5
	v_mul_f32_e32 v233, v7, v7
	v_fmac_f32_e32 v232, v4, v4
	v_fmac_f32_e32 v233, v6, v6
	v_add_f32_e32 v248, v232, v233
	v_mul_f32_e32 v0, v0, v253
	v_mul_f32_e32 v1, v1, v253
	v_mul_f32_e32 v2, v2, v253
	v_mul_f32_e32 v3, v3, v253
	v_exp_f32_e32 v0, v0
	v_exp_f32_e32 v1, v1
	v_exp_f32_e32 v2, v2
	v_exp_f32_e32 v3, v3
	v_add_f32_e32 v0, 1.0, v0
	v_add_f32_e32 v1, 1.0, v1
	v_add_f32_e32 v2, 1.0, v2
	v_add_f32_e32 v3, 1.0, v3
	v_rcp_f32_e32 v0, v0
	v_rcp_f32_e32 v1, v1
	v_rcp_f32_e32 v2, v2
	v_rcp_f32_e32 v3, v3
	v_lshlrev_b32_e32 v224, 16, v206
	v_and_b32_e32 v225, 0xffff0000, v206
	v_lshlrev_b32_e32 v226, 16, v207
	v_and_b32_e32 v227, 0xffff0000, v207
	v_lshlrev_b32_e32 v228, 16, v214
	v_and_b32_e32 v229, 0xffff0000, v214
	v_lshlrev_b32_e32 v230, 16, v215
	v_and_b32_e32 v231, 0xffff0000, v215
	v_fma_f32 v0, v0, v228, v224
	v_fma_f32 v1, v1, v229, v225
	v_fma_f32 v2, v2, v230, v226
	v_fma_f32 v3, v3, v231, v227
	v_mul_f32_e32 v232, v1, v1
	v_mul_f32_e32 v233, v3, v3
	v_fmac_f32_e32 v232, v0, v0
	v_fmac_f32_e32 v233, v2, v2
	v_add_f32_e32 v249, v232, v233
	v_cvt_pk_bf16_f32 v4, v4, v5
	v_cvt_pk_bf16_f32 v5, v6, v7
	v_cvt_pk_bf16_f32 v6, v0, v1
	v_cvt_pk_bf16_f32 v7, v2, v3
	global_store_dwordx4 v250, v[4:7], s[0:1] offset:256 sc1
	v_add_f32_e32 v234, v234, v235
	v_add_f32_e32 v248, v248, v249
	v_add_f32_e32 v247, v234, v248
	ds_bpermute_b32 v252, v236, v247
	v_add_u32_e32 v251, 0x2c00, v194
	s_waitcnt lgkmcnt(0)
	v_add_f32_e32 v247, v247, v252
	ds_bpermute_b32 v252, v237, v247
	s_waitcnt lgkmcnt(0)
	v_add_f32_e32 v247, v247, v252
	s_and_saveexec_b64 s[28:29], vcc
	global_store_dword v251, v247, s[12:13]
	s_or_b64 exec, exec, s[28:29]
	s_mov_b64 s[62:63], -1
	s_andn2_b64 vcc, exec, s[20:21]
	s_mov_b64 s[20:21], -1
	s_cbranch_vccnz .LBB0_1123
	s_andn2_b64 vcc, exec, s[8:9]
	s_cbranch_vccnz .LBB0_1122
	s_barrier
	s_branch .LBB0_1122
